# K-loops: drop the back-to-back setprio 0/1 pair and the duplicate lgkmcnt wait inside each MFMA segment
# baseline (speedup 1.0000x reference)
; #define PG8_STAGE(bufoff, gbase, voff) do { _Pragma("unroll") for (int _i = 0; _i < 2; ++_i) \
;         __builtin_amdgcn_global_load_lds((const unsigned*)((const char*)(gbase) + (voff)[_i]), (LAS unsigned*)(lds + (bufoff) + ldsw + _i * 8192), 16, 0, 0); } while (0)
; #define PG8_LDA(dst, b, h) do { _Pragma("unroll") for (int m = 0; m < 4; ++m) _Pragma("unroll") for (int k = 0; k < 2; ++k) dst[m][k] = *(const LAS bf16x8*)(lds + PG8_SA(b, h) + aoff + m * 2048 + k * 1024); } while (0)
; #define PG8_LDB(dst, b, h) do { _Pragma("unroll") for (int n = 0; n < 2; ++n) _Pragma("unroll") for (int k = 0; k < 2; ++k) dst[n][k] = *(const LAS bf16x8*)(lds + PG8_SB(b, h) + boff + n * 2048 + k * 1024); } while (0)
; #define PG8_WAIT_V(n) asm volatile("s_waitcnt vmcnt(" #n ")" ::: "memory")
; #define PG8_WAIT_L(n) asm volatile("s_waitcnt lgkmcnt(" #n ")" ::: "memory")
; #define PG8_BAR __builtin_amdgcn_s_barrier()
; #define PG8_SCHED __builtin_amdgcn_sched_barrier(0)
; template <bool F16, class Sched, class Epi>
; __device__ __forceinline__ void gemm_phase(LAS unsigned char* lds, const Gemm g, const Sched& S, const Epi& E, int wave_s) {
;     ...
;         const char* nA = has_next ? (const char*)g.A + PG8_AOFF(nxt) : cA + (size_t)(nt - 2) * kstep; const char* nB = has_next ? (const char*)g.Bt + (size_t)nxt.pn * tstepB : cB + (size_t)(nt - 2) * kstep;
;         for (int t = 0; t < nt; t += 2) {
;             const bool last = (t == nt - 2);
;             const char* a1 = cA + (size_t)(t + 1) * kstep;
;             const char* a2 = last ? nA : cA + (size_t)(t + 2) * kstep; const char* b2 = last ? nB : cB + (size_t)(t + 2) * kstep;
;             const char* a3 = a2 + kstep; const char* b3 = b2 + kstep;
;             PG8_LDB(B0, 0, 0); PG8_LDB(B1, 0, 1); PG8_SCHED; PG8_LDA(At, 0, 0); PG8_STAGE(PG8_SA(1, 1), a1 + hstepA, voffA);
;             PG8_WAIT_V(8); PG8_WAIT_L(0); PG8_BAR; PG8_MMA(0, 0, At, B0); PG8_MMA(0, 1, At, B1); PG8_BAR; PG8_SCHED;
;             PG8_LDA(At, 0, 1); PG8_STAGE(PG8_SB(0, 0), b2, voffB); PG8_STAGE(PG8_SB(0, 1), b2 + hstepB, voffB); PG8_STAGE(PG8_SA(0, 0), a2, voffA);
.LBB0_234:
	s_add_i32 s60, 0, 0x10000
	s_add_i32 s62, 0, 0x14000
	v_add_u32_e32 v150, s60, v163
	v_add_u32_e32 v170, s62, v163
	ds_read_b128 v[138:141], v150
	ds_read_b128 v[142:145], v150 offset:1024
	ds_read_b128 v[146:149], v150 offset:2048
	ds_read_b128 v[150:153], v150 offset:3072
	ds_read_b128 v[154:157], v170
	ds_read_b128 v[158:161], v170 offset:1024
	ds_read_b128 v[166:169], v170 offset:2048
	ds_read_b128 v[170:173], v170 offset:3072
	s_add_i32 m0, s41, 0xc000
	ds_read_b128 v[178:181], v165
	ds_read_b128 v[182:185], v165 offset:1024
	ds_read_b128 v[186:189], v165 offset:2048
	ds_read_b128 v[190:193], v165 offset:3072
	ds_read_b128 v[208:211], v165 offset:4096
	ds_read_b128 v[212:215], v165 offset:5120
	ds_read_b128 v[216:219], v165 offset:6144
	ds_read_b128 v[220:223], v165 offset:7168
	global_load_lds_dwordx4 v134, s[26:27]
	s_add_i32 m0, s41, 0xe000
	s_nop 0
	global_load_lds_dwordx4 v136, s[26:27]
	s_waitcnt vmcnt(8)
	s_waitcnt lgkmcnt(0)
	s_barrier
	s_setprio 1
	v_mfma_f32_16x16x32_bf16 v[124:127], v[138:141], v[178:181], v[124:127]
	v_mfma_f32_16x16x32_bf16 v[120:123], v[146:149], v[178:181], v[120:123]
	v_mfma_f32_16x16x32_bf16 v[108:111], v[138:141], v[186:189], v[108:111]
	v_mfma_f32_16x16x32_bf16 v[104:107], v[146:149], v[186:189], v[104:107]
	v_mfma_f32_16x16x32_bf16 v[96:99], v[138:141], v[208:211], v[96:99]
	v_mfma_f32_16x16x32_bf16 v[92:95], v[146:149], v[208:211], v[92:95]
	v_mfma_f32_16x16x32_bf16 v[84:87], v[138:141], v[216:219], v[84:87]
	v_mfma_f32_16x16x32_bf16 v[76:79], v[146:149], v[216:219], v[76:79]
	v_mfma_f32_16x16x32_bf16 v[124:127], v[142:145], v[182:185], v[124:127]
	v_mfma_f32_16x16x32_bf16 v[120:123], v[150:153], v[182:185], v[120:123]
	v_mfma_f32_16x16x32_bf16 v[108:111], v[142:145], v[190:193], v[108:111]
	v_mfma_f32_16x16x32_bf16 v[104:107], v[150:153], v[190:193], v[104:107]
	v_mfma_f32_16x16x32_bf16 v[96:99], v[142:145], v[212:215], v[96:99]
	v_mfma_f32_16x16x32_bf16 v[92:95], v[150:153], v[212:215], v[92:95]
	v_mfma_f32_16x16x32_bf16 v[84:87], v[142:145], v[220:223], v[84:87]
	v_mfma_f32_16x16x32_bf16 v[76:79], v[150:153], v[220:223], v[76:79]
	v_mfma_f32_16x16x32_bf16 v[116:119], v[154:157], v[178:181], v[116:119]
	v_mfma_f32_16x16x32_bf16 v[112:115], v[166:169], v[178:181], v[112:115]
	v_mfma_f32_16x16x32_bf16 v[100:103], v[154:157], v[186:189], v[100:103]
	v_mfma_f32_16x16x32_bf16 v[88:91], v[166:169], v[186:189], v[88:91]
	v_mfma_f32_16x16x32_bf16 v[80:83], v[154:157], v[208:211], v[80:83]
	v_mfma_f32_16x16x32_bf16 v[72:75], v[166:169], v[208:211], v[72:75]
	v_mfma_f32_16x16x32_bf16 v[68:71], v[154:157], v[216:219], v[68:71]
	v_mfma_f32_16x16x32_bf16 v[64:67], v[166:169], v[216:219], v[64:67]
	v_mfma_f32_16x16x32_bf16 v[116:119], v[158:161], v[182:185], v[116:119]
	v_mfma_f32_16x16x32_bf16 v[112:115], v[170:173], v[182:185], v[112:115]
	v_mfma_f32_16x16x32_bf16 v[100:103], v[158:161], v[190:193], v[100:103]
	v_mfma_f32_16x16x32_bf16 v[88:91], v[170:173], v[190:193], v[88:91]
	v_mfma_f32_16x16x32_bf16 v[80:83], v[158:161], v[212:215], v[80:83]
	v_mfma_f32_16x16x32_bf16 v[72:75], v[170:173], v[212:215], v[72:75]
	v_mfma_f32_16x16x32_bf16 v[68:71], v[158:161], v[220:223], v[68:71]
	v_mfma_f32_16x16x32_bf16 v[64:67], v[170:173], v[220:223], v[64:67]
	s_setprio 0
	s_barrier
	s_add_u32 s28, s26, 0xfff80080
	s_addc_u32 s29, s27, -1
	s_cmp_eq_u32 s59, 4
	s_cselect_b32 s31, s13, s29
	s_cselect_b32 s30, s12, s28
	s_cselect_b32 s29, s0, s58
	s_cselect_b32 s28, s1, s53
	s_add_i32 s60, s60, s39
	v_lshl_add_u64 v[174:175], s[28:29], 0, v[176:177]
	s_mov_b32 m0, s60
	ds_read_b128 v[178:181], v165 offset:16384
	ds_read_b128 v[182:185], v165 offset:17408
	ds_read_b128 v[186:189], v165 offset:18432
	ds_read_b128 v[190:193], v165 offset:19456
	ds_read_b128 v[208:211], v165 offset:20480
	ds_read_b128 v[212:215], v165 offset:21504
	ds_read_b128 v[216:219], v165 offset:22528
	ds_read_b128 v[220:223], v165 offset:23552
	global_load_lds_dwordx4 v[174:175], off
	s_add_i32 m0, s60, 0x2000
	s_add_u32 s60, s28, 0x20000
	v_lshl_add_u64 v[194:195], s[28:29], 0, v[128:129]
	s_addc_u32 s61, s29, 0
	s_add_i32 s62, s62, s39
	global_load_lds_dwordx4 v[194:195], off
	v_lshl_add_u64 v[198:199], s[60:61], 0, v[176:177]
	s_mov_b32 m0, s62
	v_lshl_add_u64 v[200:201], s[30:31], 0, v[130:131]
	global_load_lds_dwordx4 v[198:199], off
	v_lshl_add_u64 v[198:199], s[60:61], 0, v[128:129]
	s_add_i32 m0, s62, 0x2000
	s_nop 0
	global_load_lds_dwordx4 v[198:199], off
	v_lshl_add_u64 v[198:199], s[30:31], 0, v[132:133]
	s_mov_b32 m0, s41
	s_nop 0
	global_load_lds_dwordx4 v[198:199], off
	s_mov_b32 m0, s42
	s_nop 0
	global_load_lds_dwordx4 v[200:201], off
	s_add_u32 s30, s30, 0x80000
	s_addc_u32 s31, s31, 0
	s_waitcnt vmcnt(8)
	s_waitcnt lgkmcnt(0)
	s_barrier
; #define PG8_STAGE(bufoff, gbase, voff) do { _Pragma("unroll") for (int _i = 0; _i < 2; ++_i) \
;         __builtin_amdgcn_global_load_lds((const unsigned*)((const char*)(gbase) + (voff)[_i]), (LAS unsigned*)(lds + (bufoff) + ldsw + _i * 8192), 16, 0, 0); } while (0)
; #define PG8_LDA(dst, b, h) do { _Pragma("unroll") for (int m = 0; m < 4; ++m) _Pragma("unroll") for (int k = 0; k < 2; ++k) dst[m][k] = *(const LAS bf16x8*)(lds + PG8_SA(b, h) + aoff + m * 2048 + k * 1024); } while (0)
; #define PG8_LDB(dst, b, h) do { _Pragma("unroll") for (int n = 0; n < 2; ++n) _Pragma("unroll") for (int k = 0; k < 2; ++k) dst[n][k] = *(const LAS bf16x8*)(lds + PG8_SB(b, h) + boff + n * 2048 + k * 1024); } while (0)
; #define PG8_WAIT_V(n) asm volatile("s_waitcnt vmcnt(" #n ")" ::: "memory")
; #define PG8_WAIT_L(n) asm volatile("s_waitcnt lgkmcnt(" #n ")" ::: "memory")
; #define PG8_BAR __builtin_amdgcn_s_barrier()
; #define PG8_SCHED __builtin_amdgcn_sched_barrier(0)
; template <bool F16, class Sched, class Epi>
; __device__ __forceinline__ void gemm_phase(LAS unsigned char* lds, const Gemm g, const Sched& S, const Epi& E, int wave_s) {
;     ...
;             PG8_WAIT_V(8); PG8_WAIT_L(0); PG8_BAR; PG8_MMA(1, 0, At, B0); PG8_MMA(1, 1, At, B1); PG8_BAR; PG8_SCHED;
;             PG8_LDB(B0, 1, 0); PG8_LDB(B1, 1, 1); PG8_SCHED; PG8_LDA(At, 1, 0); PG8_STAGE(PG8_SA(0, 1), a2 + hstepA, voffA);
;             PG8_WAIT_V(8); PG8_WAIT_L(0); PG8_BAR; PG8_MMA(0, 0, At, B0); PG8_MMA(0, 1, At, B1); PG8_BAR; PG8_SCHED;
	s_setprio 1
	v_mfma_f32_16x16x32_bf16 v[60:63], v[138:141], v[178:181], v[60:63]
	v_mfma_f32_16x16x32_bf16 v[56:59], v[146:149], v[178:181], v[56:59]
	v_mfma_f32_16x16x32_bf16 v[52:55], v[138:141], v[186:189], v[52:55]
	v_mfma_f32_16x16x32_bf16 v[44:47], v[146:149], v[186:189], v[44:47]
	v_mfma_f32_16x16x32_bf16 v[36:39], v[138:141], v[208:211], v[36:39]
	v_mfma_f32_16x16x32_bf16 v[28:31], v[146:149], v[208:211], v[28:31]
	v_mfma_f32_16x16x32_bf16 v[20:23], v[138:141], v[216:219], v[20:23]
	v_mfma_f32_16x16x32_bf16 v[12:15], v[146:149], v[216:219], v[12:15]
	v_mfma_f32_16x16x32_bf16 v[60:63], v[142:145], v[182:185], v[60:63]
	v_mfma_f32_16x16x32_bf16 v[56:59], v[150:153], v[182:185], v[56:59]
	v_mfma_f32_16x16x32_bf16 v[52:55], v[142:145], v[190:193], v[52:55]
	v_mfma_f32_16x16x32_bf16 v[44:47], v[150:153], v[190:193], v[44:47]
	v_mfma_f32_16x16x32_bf16 v[36:39], v[142:145], v[212:215], v[36:39]
	v_mfma_f32_16x16x32_bf16 v[28:31], v[150:153], v[212:215], v[28:31]
	v_mfma_f32_16x16x32_bf16 v[20:23], v[142:145], v[220:223], v[20:23]
	v_mfma_f32_16x16x32_bf16 v[12:15], v[150:153], v[220:223], v[12:15]
	v_mfma_f32_16x16x32_bf16 v[48:51], v[154:157], v[178:181], v[48:51]
	v_mfma_f32_16x16x32_bf16 v[40:43], v[166:169], v[178:181], v[40:43]
	v_mfma_f32_16x16x32_bf16 v[32:35], v[154:157], v[186:189], v[32:35]
	v_mfma_f32_16x16x32_bf16 v[24:27], v[166:169], v[186:189], v[24:27]
	v_mfma_f32_16x16x32_bf16 v[16:19], v[154:157], v[208:211], v[16:19]
	v_mfma_f32_16x16x32_bf16 v[8:11], v[166:169], v[208:211], v[8:11]
	v_mfma_f32_16x16x32_bf16 v[4:7], v[154:157], v[216:219], v[4:7]
	v_mfma_f32_16x16x32_bf16 v[0:3], v[166:169], v[216:219], v[0:3]
	v_mfma_f32_16x16x32_bf16 v[48:51], v[158:161], v[182:185], v[48:51]
	v_mfma_f32_16x16x32_bf16 v[40:43], v[170:173], v[182:185], v[40:43]
	v_mfma_f32_16x16x32_bf16 v[32:35], v[158:161], v[190:193], v[32:35]
	v_mfma_f32_16x16x32_bf16 v[24:27], v[170:173], v[190:193], v[24:27]
	v_mfma_f32_16x16x32_bf16 v[16:19], v[158:161], v[212:215], v[16:19]
	v_mfma_f32_16x16x32_bf16 v[8:11], v[170:173], v[212:215], v[8:11]
	v_mfma_f32_16x16x32_bf16 v[4:7], v[158:161], v[220:223], v[4:7]
	v_mfma_f32_16x16x32_bf16 v[0:3], v[170:173], v[220:223], v[0:3]
	s_setprio 0
	s_barrier
	s_add_i32 s60, 0, 0x18000
	s_add_i32 s61, 0, 0x1c000
	v_add_u32_e32 v150, s60, v163
	v_add_u32_e32 v170, s61, v163
	ds_read_b128 v[138:141], v150
	ds_read_b128 v[142:145], v150 offset:1024
	ds_read_b128 v[146:149], v150 offset:2048
	ds_read_b128 v[150:153], v150 offset:3072
	ds_read_b128 v[154:157], v170
	ds_read_b128 v[158:161], v170 offset:1024
	ds_read_b128 v[166:169], v170 offset:2048
	ds_read_b128 v[170:173], v170 offset:3072
	s_mov_b32 m0, s43
	ds_read_b128 v[178:181], v165 offset:32768
	ds_read_b128 v[182:185], v165 offset:33792
	ds_read_b128 v[186:189], v165 offset:34816
	ds_read_b128 v[190:193], v165 offset:35840
	ds_read_b128 v[208:211], v165 offset:36864
	ds_read_b128 v[212:215], v165 offset:37888
	ds_read_b128 v[216:219], v165 offset:38912
	ds_read_b128 v[220:223], v165 offset:39936
	global_load_lds_dwordx4 v132, s[30:31]
	s_mov_b32 m0, s44
	s_nop 0
	global_load_lds_dwordx4 v130, s[30:31]
	s_waitcnt vmcnt(8)
	s_waitcnt lgkmcnt(0)
	s_barrier
	s_setprio 1
	v_mfma_f32_16x16x32_bf16 v[124:127], v[138:141], v[178:181], v[124:127]
	v_mfma_f32_16x16x32_bf16 v[120:123], v[146:149], v[178:181], v[120:123]
	v_mfma_f32_16x16x32_bf16 v[108:111], v[138:141], v[186:189], v[108:111]
	v_mfma_f32_16x16x32_bf16 v[104:107], v[146:149], v[186:189], v[104:107]
	v_mfma_f32_16x16x32_bf16 v[96:99], v[138:141], v[208:211], v[96:99]
	v_mfma_f32_16x16x32_bf16 v[92:95], v[146:149], v[208:211], v[92:95]
	v_mfma_f32_16x16x32_bf16 v[84:87], v[138:141], v[216:219], v[84:87]
	v_mfma_f32_16x16x32_bf16 v[76:79], v[146:149], v[216:219], v[76:79]
	v_mfma_f32_16x16x32_bf16 v[124:127], v[142:145], v[182:185], v[124:127]
	v_mfma_f32_16x16x32_bf16 v[120:123], v[150:153], v[182:185], v[120:123]
	v_mfma_f32_16x16x32_bf16 v[108:111], v[142:145], v[190:193], v[108:111]
	v_mfma_f32_16x16x32_bf16 v[104:107], v[150:153], v[190:193], v[104:107]
	v_mfma_f32_16x16x32_bf16 v[96:99], v[142:145], v[212:215], v[96:99]
	v_mfma_f32_16x16x32_bf16 v[92:95], v[150:153], v[212:215], v[92:95]
	v_mfma_f32_16x16x32_bf16 v[84:87], v[142:145], v[220:223], v[84:87]
	v_mfma_f32_16x16x32_bf16 v[76:79], v[150:153], v[220:223], v[76:79]
	v_mfma_f32_16x16x32_bf16 v[116:119], v[154:157], v[178:181], v[116:119]
	v_mfma_f32_16x16x32_bf16 v[112:115], v[166:169], v[178:181], v[112:115]
	v_mfma_f32_16x16x32_bf16 v[100:103], v[154:157], v[186:189], v[100:103]
	v_mfma_f32_16x16x32_bf16 v[88:91], v[166:169], v[186:189], v[88:91]
	v_mfma_f32_16x16x32_bf16 v[80:83], v[154:157], v[208:211], v[80:83]
	v_mfma_f32_16x16x32_bf16 v[72:75], v[166:169], v[208:211], v[72:75]
	v_mfma_f32_16x16x32_bf16 v[68:71], v[154:157], v[216:219], v[68:71]
	v_mfma_f32_16x16x32_bf16 v[64:67], v[166:169], v[216:219], v[64:67]
	v_mfma_f32_16x16x32_bf16 v[116:119], v[158:161], v[182:185], v[116:119]
	v_mfma_f32_16x16x32_bf16 v[112:115], v[170:173], v[182:185], v[112:115]
	v_mfma_f32_16x16x32_bf16 v[100:103], v[158:161], v[190:193], v[100:103]
	v_mfma_f32_16x16x32_bf16 v[88:91], v[170:173], v[190:193], v[88:91]
	v_mfma_f32_16x16x32_bf16 v[80:83], v[158:161], v[212:215], v[80:83]
	v_mfma_f32_16x16x32_bf16 v[72:75], v[170:173], v[212:215], v[72:75]
	v_mfma_f32_16x16x32_bf16 v[68:71], v[158:161], v[220:223], v[68:71]
	v_mfma_f32_16x16x32_bf16 v[64:67], v[170:173], v[220:223], v[64:67]
	s_setprio 0
	s_barrier
; #define PG8_STAGE(bufoff, gbase, voff) do { _Pragma("unroll") for (int _i = 0; _i < 2; ++_i) \
;         __builtin_amdgcn_global_load_lds((const unsigned*)((const char*)(gbase) + (voff)[_i]), (LAS unsigned*)(lds + (bufoff) + ldsw + _i * 8192), 16, 0, 0); } while (0)
; #define PG8_LDA(dst, b, h) do { _Pragma("unroll") for (int m = 0; m < 4; ++m) _Pragma("unroll") for (int k = 0; k < 2; ++k) dst[m][k] = *(const LAS bf16x8*)(lds + PG8_SA(b, h) + aoff + m * 2048 + k * 1024); } while (0)
; #define PG8_WAIT_V(n) asm volatile("s_waitcnt vmcnt(" #n ")" ::: "memory")
; #define PG8_WAIT_L(n) asm volatile("s_waitcnt lgkmcnt(" #n ")" ::: "memory")
; #define PG8_BAR __builtin_amdgcn_s_barrier()
; #define PG8_SCHED __builtin_amdgcn_sched_barrier(0)
; template <bool F16, class Sched, class Epi>
; __device__ __forceinline__ void gemm_phase(LAS unsigned char* lds, const Gemm g, const Sched& S, const Epi& E, int wave_s) {
;     ...
;             PG8_LDA(At, 1, 1); PG8_STAGE(PG8_SB(1, 0), b3, voffB); PG8_STAGE(PG8_SB(1, 1), b3 + hstepB, voffB); PG8_STAGE(PG8_SA(1, 0), a3, voffA);
;             PG8_WAIT_V(8); PG8_WAIT_L(0); PG8_BAR; PG8_MMA(1, 0, At, B0); PG8_MMA(1, 1, At, B1); PG8_BAR; PG8_SCHED;
;         }
;         if (wr == 0) PG8_BAR;
	s_add_i32 s30, s60, s39
	v_lshl_add_u64 v[174:175], v[174:175], 0, s[54:55]
	s_mov_b32 m0, s30
	ds_read_b128 v[178:181], v165 offset:49152
	ds_read_b128 v[182:185], v165 offset:50176
	ds_read_b128 v[186:189], v165 offset:51200
	ds_read_b128 v[190:193], v165 offset:52224
	ds_read_b128 v[208:211], v165 offset:53248
	ds_read_b128 v[212:215], v165 offset:54272
	ds_read_b128 v[216:219], v165 offset:55296
	ds_read_b128 v[220:223], v165 offset:56320
	global_load_lds_dwordx4 v[174:175], off
	s_add_i32 m0, s30, 0x2000
	s_add_u32 s28, s28, 0x20080
	v_lshl_add_u64 v[174:175], v[194:195], 0, s[54:55]
	s_addc_u32 s29, s29, 0
	s_add_i32 s30, s61, s39
	global_load_lds_dwordx4 v[174:175], off
	v_lshl_add_u64 v[174:175], s[28:29], 0, v[176:177]
	s_mov_b32 m0, s30
	s_nop 0
	global_load_lds_dwordx4 v[174:175], off
	v_lshl_add_u64 v[174:175], s[28:29], 0, v[128:129]
	s_add_i32 m0, s30, 0x2000
	s_nop 0
	global_load_lds_dwordx4 v[174:175], off
	v_lshl_add_u64 v[174:175], v[198:199], 0, s[54:55]
	s_mov_b32 m0, s19
	s_nop 0
	global_load_lds_dwordx4 v[174:175], off
	v_lshl_add_u64 v[174:175], v[200:201], 0, s[54:55]
	s_mov_b32 m0, s45
	s_nop 0
	global_load_lds_dwordx4 v[174:175], off
	s_waitcnt vmcnt(8)
	s_waitcnt lgkmcnt(0)
	s_barrier
	s_setprio 1
	v_mfma_f32_16x16x32_bf16 v[60:63], v[138:141], v[178:181], v[60:63]
	v_mfma_f32_16x16x32_bf16 v[56:59], v[146:149], v[178:181], v[56:59]
	v_mfma_f32_16x16x32_bf16 v[52:55], v[138:141], v[186:189], v[52:55]
	v_mfma_f32_16x16x32_bf16 v[44:47], v[146:149], v[186:189], v[44:47]
	v_mfma_f32_16x16x32_bf16 v[36:39], v[138:141], v[208:211], v[36:39]
	v_mfma_f32_16x16x32_bf16 v[28:31], v[146:149], v[208:211], v[28:31]
	v_mfma_f32_16x16x32_bf16 v[20:23], v[138:141], v[216:219], v[20:23]
	v_mfma_f32_16x16x32_bf16 v[12:15], v[146:149], v[216:219], v[12:15]
	v_mfma_f32_16x16x32_bf16 v[60:63], v[142:145], v[182:185], v[60:63]
	v_mfma_f32_16x16x32_bf16 v[56:59], v[150:153], v[182:185], v[56:59]
	v_mfma_f32_16x16x32_bf16 v[52:55], v[142:145], v[190:193], v[52:55]
	v_mfma_f32_16x16x32_bf16 v[44:47], v[150:153], v[190:193], v[44:47]
	v_mfma_f32_16x16x32_bf16 v[36:39], v[142:145], v[212:215], v[36:39]
	v_mfma_f32_16x16x32_bf16 v[28:31], v[150:153], v[212:215], v[28:31]
	v_mfma_f32_16x16x32_bf16 v[20:23], v[142:145], v[220:223], v[20:23]
	v_mfma_f32_16x16x32_bf16 v[12:15], v[150:153], v[220:223], v[12:15]
	v_mfma_f32_16x16x32_bf16 v[48:51], v[154:157], v[178:181], v[48:51]
	v_mfma_f32_16x16x32_bf16 v[40:43], v[166:169], v[178:181], v[40:43]
	v_mfma_f32_16x16x32_bf16 v[32:35], v[154:157], v[186:189], v[32:35]
	v_mfma_f32_16x16x32_bf16 v[24:27], v[166:169], v[186:189], v[24:27]
	v_mfma_f32_16x16x32_bf16 v[16:19], v[154:157], v[208:211], v[16:19]
	v_mfma_f32_16x16x32_bf16 v[8:11], v[166:169], v[208:211], v[8:11]
	v_mfma_f32_16x16x32_bf16 v[4:7], v[154:157], v[216:219], v[4:7]
	v_mfma_f32_16x16x32_bf16 v[0:3], v[166:169], v[216:219], v[0:3]
	v_mfma_f32_16x16x32_bf16 v[48:51], v[158:161], v[182:185], v[48:51]
	v_mfma_f32_16x16x32_bf16 v[40:43], v[170:173], v[182:185], v[40:43]
	v_mfma_f32_16x16x32_bf16 v[32:35], v[158:161], v[190:193], v[32:35]
	v_mfma_f32_16x16x32_bf16 v[24:27], v[170:173], v[190:193], v[24:27]
	v_mfma_f32_16x16x32_bf16 v[16:19], v[158:161], v[212:215], v[16:19]
	v_mfma_f32_16x16x32_bf16 v[8:11], v[170:173], v[212:215], v[8:11]
	v_mfma_f32_16x16x32_bf16 v[4:7], v[158:161], v[220:223], v[4:7]
	v_mfma_f32_16x16x32_bf16 v[0:3], v[170:173], v[220:223], v[0:3]
	s_setprio 0
	s_barrier
	s_add_i32 s59, s59, 2
	s_add_u32 s26, s26, 0x100
	s_addc_u32 s27, s27, 0
	s_add_u32 s53, s53, 0x100
	s_addc_u32 s58, s58, 0
	s_cmp_gt_u32 s59, 5
	s_cbranch_scc0 .LBB0_234
	s_and_b64 vcc, exec, s[10:11]
	s_cbranch_vccz .LBB0_237
	s_barrier

; #define PG8_STAGE(bufoff, gbase, voff) do { _Pragma("unroll") for (int _i = 0; _i < 2; ++_i) \
;         __builtin_amdgcn_global_load_lds((const unsigned*)((const char*)(gbase) + (voff)[_i]), (LAS unsigned*)(lds + (bufoff) + ldsw + _i * 8192), 16, 0, 0); } while (0)
; #define PG8_LDA(dst, b, h) do { _Pragma("unroll") for (int m = 0; m < 4; ++m) _Pragma("unroll") for (int k = 0; k < 2; ++k) dst[m][k] = *(const LAS bf16x8*)(lds + PG8_SA(b, h) + aoff + m * 2048 + k * 1024); } while (0)
; #define PG8_LDB(dst, b, h) do { _Pragma("unroll") for (int n = 0; n < 2; ++n) _Pragma("unroll") for (int k = 0; k < 2; ++k) dst[n][k] = *(const LAS bf16x8*)(lds + PG8_SB(b, h) + boff + n * 2048 + k * 1024); } while (0)
; #define PG8_WAIT_V(n) asm volatile("s_waitcnt vmcnt(" #n ")" ::: "memory")
; #define PG8_WAIT_L(n) asm volatile("s_waitcnt lgkmcnt(" #n ")" ::: "memory")
; #define PG8_BAR __builtin_amdgcn_s_barrier()
; #define PG8_SCHED __builtin_amdgcn_sched_barrier(0)
; template <bool F16, class Sched, class Epi>
; __device__ __forceinline__ void gemm_phase(LAS unsigned char* lds, const Gemm g, const Sched& S, const Epi& E, int wave_s) {
;     ...
;         const char* nA = has_next ? (const char*)g.A + PG8_AOFF(nxt) : cA + (size_t)(nt - 2) * kstep; const char* nB = has_next ? (const char*)g.Bt + (size_t)nxt.pn * tstepB : cB + (size_t)(nt - 2) * kstep;
;         for (int t = 0; t < nt; t += 2) {
;             const bool last = (t == nt - 2);
;             const char* a1 = cA + (size_t)(t + 1) * kstep;
;             const char* a2 = last ? nA : cA + (size_t)(t + 2) * kstep; const char* b2 = last ? nB : cB + (size_t)(t + 2) * kstep;
;             const char* a3 = a2 + kstep; const char* b3 = b2 + kstep;
;             PG8_LDB(B0, 0, 0); PG8_LDB(B1, 0, 1); PG8_SCHED; PG8_LDA(At, 0, 0); PG8_STAGE(PG8_SA(1, 1), a1 + hstepA, voffA);
;             PG8_WAIT_V(8); PG8_WAIT_L(0); PG8_BAR; PG8_MMA(0, 0, At, B0); PG8_MMA(0, 1, At, B1); PG8_BAR; PG8_SCHED;
;             PG8_LDA(At, 0, 1); PG8_STAGE(PG8_SB(0, 0), b2, voffB); PG8_STAGE(PG8_SB(0, 1), b2 + hstepB, voffB); PG8_STAGE(PG8_SA(0, 0), a2, voffA);
.LBB0_304:
	s_add_i32 s71, 0, 0x10000
	s_add_i32 s74, 0, 0x14000
	v_add_u32_e32 v150, s71, v162
	v_add_u32_e32 v158, s74, v162
	ds_read_b128 v[138:141], v150
	ds_read_b128 v[142:145], v150 offset:1024
	ds_read_b128 v[146:149], v150 offset:2048
	ds_read_b128 v[150:153], v150 offset:3072
	ds_read_b128 v[154:157], v158
	ds_read_b128 v[166:169], v158 offset:1024
	ds_read_b128 v[170:173], v158 offset:2048
	ds_read_b128 v[178:181], v158 offset:3072
	s_add_i32 m0, s49, 0xc000
	ds_read_b128 v[182:185], v164
	ds_read_b128 v[186:189], v164 offset:1024
	ds_read_b128 v[190:193], v164 offset:2048
	ds_read_b128 v[208:211], v164 offset:3072
	ds_read_b128 v[212:215], v164 offset:4096
	ds_read_b128 v[216:219], v164 offset:5120
	ds_read_b128 v[220:223], v164 offset:6144
	ds_read_b128 v[224:227], v164 offset:7168
	global_load_lds_dwordx4 v134, s[2:3]
	s_add_i32 m0, s49, 0xe000
	s_nop 0
	global_load_lds_dwordx4 v136, s[2:3]
	s_waitcnt vmcnt(8)
	s_waitcnt lgkmcnt(0)
	s_barrier
	s_setprio 1
	v_mfma_f32_16x16x32_bf16 v[124:127], v[138:141], v[182:185], v[124:127]
	v_mfma_f32_16x16x32_bf16 v[120:123], v[146:149], v[182:185], v[120:123]
	v_mfma_f32_16x16x32_bf16 v[108:111], v[138:141], v[190:193], v[108:111]
	v_mfma_f32_16x16x32_bf16 v[104:107], v[146:149], v[190:193], v[104:107]
	v_mfma_f32_16x16x32_bf16 v[92:95], v[138:141], v[212:215], v[92:95]
	v_mfma_f32_16x16x32_bf16 v[88:91], v[146:149], v[212:215], v[88:91]
	v_mfma_f32_16x16x32_bf16 v[76:79], v[138:141], v[220:223], v[76:79]
	v_mfma_f32_16x16x32_bf16 v[72:75], v[146:149], v[220:223], v[72:75]
	v_mfma_f32_16x16x32_bf16 v[124:127], v[142:145], v[186:189], v[124:127]
	v_mfma_f32_16x16x32_bf16 v[120:123], v[150:153], v[186:189], v[120:123]
	v_mfma_f32_16x16x32_bf16 v[108:111], v[142:145], v[208:211], v[108:111]
	v_mfma_f32_16x16x32_bf16 v[104:107], v[150:153], v[208:211], v[104:107]
	v_mfma_f32_16x16x32_bf16 v[92:95], v[142:145], v[216:219], v[92:95]
	v_mfma_f32_16x16x32_bf16 v[88:91], v[150:153], v[216:219], v[88:91]
	v_mfma_f32_16x16x32_bf16 v[76:79], v[142:145], v[224:227], v[76:79]
	v_mfma_f32_16x16x32_bf16 v[72:75], v[150:153], v[224:227], v[72:75]
	v_mfma_f32_16x16x32_bf16 v[116:119], v[154:157], v[182:185], v[116:119]
	v_mfma_f32_16x16x32_bf16 v[112:115], v[170:173], v[182:185], v[112:115]
	v_mfma_f32_16x16x32_bf16 v[100:103], v[154:157], v[190:193], v[100:103]
	v_mfma_f32_16x16x32_bf16 v[96:99], v[170:173], v[190:193], v[96:99]
	v_mfma_f32_16x16x32_bf16 v[84:87], v[154:157], v[212:215], v[84:87]
	v_mfma_f32_16x16x32_bf16 v[80:83], v[170:173], v[212:215], v[80:83]
	v_mfma_f32_16x16x32_bf16 v[68:71], v[154:157], v[220:223], v[68:71]
	v_mfma_f32_16x16x32_bf16 v[64:67], v[170:173], v[220:223], v[64:67]
	v_mfma_f32_16x16x32_bf16 v[116:119], v[166:169], v[186:189], v[116:119]
	v_mfma_f32_16x16x32_bf16 v[112:115], v[178:181], v[186:189], v[112:115]
	v_mfma_f32_16x16x32_bf16 v[100:103], v[166:169], v[208:211], v[100:103]
	v_mfma_f32_16x16x32_bf16 v[96:99], v[178:181], v[208:211], v[96:99]
	v_mfma_f32_16x16x32_bf16 v[84:87], v[166:169], v[216:219], v[84:87]
	v_mfma_f32_16x16x32_bf16 v[80:83], v[178:181], v[216:219], v[80:83]
	v_mfma_f32_16x16x32_bf16 v[68:71], v[166:169], v[224:227], v[68:71]
	v_mfma_f32_16x16x32_bf16 v[64:67], v[178:181], v[224:227], v[64:67]
	s_setprio 0
	s_barrier
	s_add_u32 s4, s2, 0xfff80080
	s_addc_u32 s5, s3, -1
	s_cmp_eq_u32 s70, 28
	s_cselect_b32 s39, s62, s5
	s_cselect_b32 s38, s63, s4
	s_cselect_b32 s5, s64, s69
	s_cselect_b32 s4, s65, s68
	s_add_i32 s71, s71, s46
	v_lshl_add_u64 v[158:159], s[4:5], 0, v[176:177]
	s_mov_b32 m0, s71
	ds_read_b128 v[182:185], v164 offset:16384
	ds_read_b128 v[186:189], v164 offset:17408
	ds_read_b128 v[190:193], v164 offset:18432
	ds_read_b128 v[208:211], v164 offset:19456
	ds_read_b128 v[212:215], v164 offset:20480
	ds_read_b128 v[216:219], v164 offset:21504
	ds_read_b128 v[220:223], v164 offset:22528
	ds_read_b128 v[224:227], v164 offset:23552
	global_load_lds_dwordx4 v[158:159], off
	s_add_i32 m0, s71, 0x2000
	s_add_u32 s72, s4, 0x80000
	v_lshl_add_u64 v[174:175], s[4:5], 0, v[128:129]
	s_addc_u32 s73, s5, 0
	s_add_i32 s71, s74, s46
	global_load_lds_dwordx4 v[174:175], off
	v_lshl_add_u64 v[194:195], s[72:73], 0, v[176:177]
	s_mov_b32 m0, s71
	v_lshl_add_u64 v[198:199], s[38:39], 0, v[130:131]
	global_load_lds_dwordx4 v[194:195], off
	v_lshl_add_u64 v[194:195], s[72:73], 0, v[128:129]
	s_add_i32 m0, s71, 0x2000
	s_nop 0
	global_load_lds_dwordx4 v[194:195], off
	v_lshl_add_u64 v[194:195], s[38:39], 0, v[132:133]
	s_mov_b32 m0, s49
	s_nop 0
	global_load_lds_dwordx4 v[194:195], off
	s_mov_b32 m0, s52
	s_nop 0
	global_load_lds_dwordx4 v[198:199], off
	s_add_u32 s38, s38, 0x80000
	s_addc_u32 s39, s39, 0
	s_waitcnt vmcnt(8)
	s_waitcnt lgkmcnt(0)
	s_barrier
; #define PG8_STAGE(bufoff, gbase, voff) do { _Pragma("unroll") for (int _i = 0; _i < 2; ++_i) \
;         __builtin_amdgcn_global_load_lds((const unsigned*)((const char*)(gbase) + (voff)[_i]), (LAS unsigned*)(lds + (bufoff) + ldsw + _i * 8192), 16, 0, 0); } while (0)
; #define PG8_LDA(dst, b, h) do { _Pragma("unroll") for (int m = 0; m < 4; ++m) _Pragma("unroll") for (int k = 0; k < 2; ++k) dst[m][k] = *(const LAS bf16x8*)(lds + PG8_SA(b, h) + aoff + m * 2048 + k * 1024); } while (0)
; #define PG8_LDB(dst, b, h) do { _Pragma("unroll") for (int n = 0; n < 2; ++n) _Pragma("unroll") for (int k = 0; k < 2; ++k) dst[n][k] = *(const LAS bf16x8*)(lds + PG8_SB(b, h) + boff + n * 2048 + k * 1024); } while (0)
; #define PG8_WAIT_V(n) asm volatile("s_waitcnt vmcnt(" #n ")" ::: "memory")
; #define PG8_WAIT_L(n) asm volatile("s_waitcnt lgkmcnt(" #n ")" ::: "memory")
; #define PG8_BAR __builtin_amdgcn_s_barrier()
; #define PG8_SCHED __builtin_amdgcn_sched_barrier(0)
; template <bool F16, class Sched, class Epi>
; __device__ __forceinline__ void gemm_phase(LAS unsigned char* lds, const Gemm g, const Sched& S, const Epi& E, int wave_s) {
;     ...
;             PG8_WAIT_V(8); PG8_WAIT_L(0); PG8_BAR; PG8_MMA(1, 0, At, B0); PG8_MMA(1, 1, At, B1); PG8_BAR; PG8_SCHED;
;             PG8_LDB(B0, 1, 0); PG8_LDB(B1, 1, 1); PG8_SCHED; PG8_LDA(At, 1, 0); PG8_STAGE(PG8_SA(0, 1), a2 + hstepA, voffA);
;             PG8_WAIT_V(8); PG8_WAIT_L(0); PG8_BAR; PG8_MMA(0, 0, At, B0); PG8_MMA(0, 1, At, B1); PG8_BAR; PG8_SCHED;
	s_setprio 1
	v_mfma_f32_16x16x32_bf16 v[60:63], v[138:141], v[182:185], v[60:63]
	v_mfma_f32_16x16x32_bf16 v[56:59], v[146:149], v[182:185], v[56:59]
	v_mfma_f32_16x16x32_bf16 v[44:47], v[138:141], v[190:193], v[44:47]
	v_mfma_f32_16x16x32_bf16 v[40:43], v[146:149], v[190:193], v[40:43]
	v_mfma_f32_16x16x32_bf16 v[28:31], v[138:141], v[212:215], v[28:31]
	v_mfma_f32_16x16x32_bf16 v[24:27], v[146:149], v[212:215], v[24:27]
	v_mfma_f32_16x16x32_bf16 v[12:15], v[138:141], v[220:223], v[12:15]
	v_mfma_f32_16x16x32_bf16 v[8:11], v[146:149], v[220:223], v[8:11]
	v_mfma_f32_16x16x32_bf16 v[60:63], v[142:145], v[186:189], v[60:63]
	v_mfma_f32_16x16x32_bf16 v[56:59], v[150:153], v[186:189], v[56:59]
	v_mfma_f32_16x16x32_bf16 v[44:47], v[142:145], v[208:211], v[44:47]
	v_mfma_f32_16x16x32_bf16 v[40:43], v[150:153], v[208:211], v[40:43]
	v_mfma_f32_16x16x32_bf16 v[28:31], v[142:145], v[216:219], v[28:31]
	v_mfma_f32_16x16x32_bf16 v[24:27], v[150:153], v[216:219], v[24:27]
	v_mfma_f32_16x16x32_bf16 v[12:15], v[142:145], v[224:227], v[12:15]
	v_mfma_f32_16x16x32_bf16 v[8:11], v[150:153], v[224:227], v[8:11]
	v_mfma_f32_16x16x32_bf16 v[52:55], v[154:157], v[182:185], v[52:55]
	v_mfma_f32_16x16x32_bf16 v[48:51], v[170:173], v[182:185], v[48:51]
	v_mfma_f32_16x16x32_bf16 v[36:39], v[154:157], v[190:193], v[36:39]
	v_mfma_f32_16x16x32_bf16 v[32:35], v[170:173], v[190:193], v[32:35]
	v_mfma_f32_16x16x32_bf16 v[20:23], v[154:157], v[212:215], v[20:23]
	v_mfma_f32_16x16x32_bf16 v[16:19], v[170:173], v[212:215], v[16:19]
	v_mfma_f32_16x16x32_bf16 v[4:7], v[154:157], v[220:223], v[4:7]
	v_mfma_f32_16x16x32_bf16 v[0:3], v[170:173], v[220:223], v[0:3]
	v_mfma_f32_16x16x32_bf16 v[52:55], v[166:169], v[186:189], v[52:55]
	v_mfma_f32_16x16x32_bf16 v[48:51], v[178:181], v[186:189], v[48:51]
	v_mfma_f32_16x16x32_bf16 v[36:39], v[166:169], v[208:211], v[36:39]
	v_mfma_f32_16x16x32_bf16 v[32:35], v[178:181], v[208:211], v[32:35]
	v_mfma_f32_16x16x32_bf16 v[20:23], v[166:169], v[216:219], v[20:23]
	v_mfma_f32_16x16x32_bf16 v[16:19], v[178:181], v[216:219], v[16:19]
	v_mfma_f32_16x16x32_bf16 v[4:7], v[166:169], v[224:227], v[4:7]
	v_mfma_f32_16x16x32_bf16 v[0:3], v[178:181], v[224:227], v[0:3]
	s_setprio 0
	s_barrier
	s_add_i32 s71, 0, 0x18000
	s_add_i32 s72, 0, 0x1c000
	v_add_u32_e32 v150, s71, v162
	v_add_u32_e32 v160, s72, v162
	ds_read_b128 v[138:141], v150
	ds_read_b128 v[142:145], v150 offset:1024
	ds_read_b128 v[146:149], v150 offset:2048
	ds_read_b128 v[150:153], v150 offset:3072
	ds_read_b128 v[154:157], v160
	ds_read_b128 v[166:169], v160 offset:1024
	ds_read_b128 v[170:173], v160 offset:2048
	ds_read_b128 v[178:181], v160 offset:3072
	s_mov_b32 m0, s53
	ds_read_b128 v[182:185], v164 offset:32768
	ds_read_b128 v[186:189], v164 offset:33792
	ds_read_b128 v[190:193], v164 offset:34816
	ds_read_b128 v[208:211], v164 offset:35840
	ds_read_b128 v[212:215], v164 offset:36864
	ds_read_b128 v[216:219], v164 offset:37888
	ds_read_b128 v[220:223], v164 offset:38912
	ds_read_b128 v[224:227], v164 offset:39936
	global_load_lds_dwordx4 v132, s[38:39]
	s_mov_b32 m0, s58
	s_nop 0
	global_load_lds_dwordx4 v130, s[38:39]
	s_waitcnt vmcnt(8)
	s_waitcnt lgkmcnt(0)
	s_barrier
	s_setprio 1
	v_mfma_f32_16x16x32_bf16 v[124:127], v[138:141], v[182:185], v[124:127]
	v_mfma_f32_16x16x32_bf16 v[120:123], v[146:149], v[182:185], v[120:123]
	v_mfma_f32_16x16x32_bf16 v[108:111], v[138:141], v[190:193], v[108:111]
	v_mfma_f32_16x16x32_bf16 v[104:107], v[146:149], v[190:193], v[104:107]
	v_mfma_f32_16x16x32_bf16 v[92:95], v[138:141], v[212:215], v[92:95]
	v_mfma_f32_16x16x32_bf16 v[88:91], v[146:149], v[212:215], v[88:91]
	v_mfma_f32_16x16x32_bf16 v[76:79], v[138:141], v[220:223], v[76:79]
	v_mfma_f32_16x16x32_bf16 v[72:75], v[146:149], v[220:223], v[72:75]
	v_mfma_f32_16x16x32_bf16 v[124:127], v[142:145], v[186:189], v[124:127]
	v_mfma_f32_16x16x32_bf16 v[120:123], v[150:153], v[186:189], v[120:123]
	v_mfma_f32_16x16x32_bf16 v[108:111], v[142:145], v[208:211], v[108:111]
	v_mfma_f32_16x16x32_bf16 v[104:107], v[150:153], v[208:211], v[104:107]
	v_mfma_f32_16x16x32_bf16 v[92:95], v[142:145], v[216:219], v[92:95]
	v_mfma_f32_16x16x32_bf16 v[88:91], v[150:153], v[216:219], v[88:91]
	v_mfma_f32_16x16x32_bf16 v[76:79], v[142:145], v[224:227], v[76:79]
	v_mfma_f32_16x16x32_bf16 v[72:75], v[150:153], v[224:227], v[72:75]
	v_mfma_f32_16x16x32_bf16 v[116:119], v[154:157], v[182:185], v[116:119]
	v_mfma_f32_16x16x32_bf16 v[112:115], v[170:173], v[182:185], v[112:115]
	v_mfma_f32_16x16x32_bf16 v[100:103], v[154:157], v[190:193], v[100:103]
	v_mfma_f32_16x16x32_bf16 v[96:99], v[170:173], v[190:193], v[96:99]
	v_mfma_f32_16x16x32_bf16 v[84:87], v[154:157], v[212:215], v[84:87]
	v_mfma_f32_16x16x32_bf16 v[80:83], v[170:173], v[212:215], v[80:83]
	v_mfma_f32_16x16x32_bf16 v[68:71], v[154:157], v[220:223], v[68:71]
	v_mfma_f32_16x16x32_bf16 v[64:67], v[170:173], v[220:223], v[64:67]
	v_mfma_f32_16x16x32_bf16 v[116:119], v[166:169], v[186:189], v[116:119]
	v_mfma_f32_16x16x32_bf16 v[112:115], v[178:181], v[186:189], v[112:115]
	v_mfma_f32_16x16x32_bf16 v[100:103], v[166:169], v[208:211], v[100:103]
	v_mfma_f32_16x16x32_bf16 v[96:99], v[178:181], v[208:211], v[96:99]
	v_mfma_f32_16x16x32_bf16 v[84:87], v[166:169], v[216:219], v[84:87]
	v_mfma_f32_16x16x32_bf16 v[80:83], v[178:181], v[216:219], v[80:83]
	v_mfma_f32_16x16x32_bf16 v[68:71], v[166:169], v[224:227], v[68:71]
	v_mfma_f32_16x16x32_bf16 v[64:67], v[178:181], v[224:227], v[64:67]
	s_setprio 0
	s_barrier
; #define PG8_STAGE(bufoff, gbase, voff) do { _Pragma("unroll") for (int _i = 0; _i < 2; ++_i) \
;         __builtin_amdgcn_global_load_lds((const unsigned*)((const char*)(gbase) + (voff)[_i]), (LAS unsigned*)(lds + (bufoff) + ldsw + _i * 8192), 16, 0, 0); } while (0)
; #define PG8_LDA(dst, b, h) do { _Pragma("unroll") for (int m = 0; m < 4; ++m) _Pragma("unroll") for (int k = 0; k < 2; ++k) dst[m][k] = *(const LAS bf16x8*)(lds + PG8_SA(b, h) + aoff + m * 2048 + k * 1024); } while (0)
; #define PG8_WAIT_V(n) asm volatile("s_waitcnt vmcnt(" #n ")" ::: "memory")
; #define PG8_WAIT_L(n) asm volatile("s_waitcnt lgkmcnt(" #n ")" ::: "memory")
; #define PG8_BAR __builtin_amdgcn_s_barrier()
; #define PG8_SCHED __builtin_amdgcn_sched_barrier(0)
; template <bool F16, class Sched, class Epi>
; __device__ __forceinline__ void gemm_phase(LAS unsigned char* lds, const Gemm g, const Sched& S, const Epi& E, int wave_s) {
;     ...
;             PG8_LDA(At, 1, 1); PG8_STAGE(PG8_SB(1, 0), b3, voffB); PG8_STAGE(PG8_SB(1, 1), b3 + hstepB, voffB); PG8_STAGE(PG8_SA(1, 0), a3, voffA);
;             PG8_WAIT_V(8); PG8_WAIT_L(0); PG8_BAR; PG8_MMA(1, 0, At, B0); PG8_MMA(1, 1, At, B1); PG8_BAR; PG8_SCHED;
;         }
;         if (wr == 0) PG8_BAR;
	s_add_i32 s38, s71, s46
	v_lshl_add_u64 v[158:159], v[158:159], 0, s[54:55]
	s_mov_b32 m0, s38
	ds_read_b128 v[182:185], v164 offset:49152
	ds_read_b128 v[186:189], v164 offset:50176
	ds_read_b128 v[190:193], v164 offset:51200
	ds_read_b128 v[208:211], v164 offset:52224
	ds_read_b128 v[212:215], v164 offset:53248
	ds_read_b128 v[216:219], v164 offset:54272
	ds_read_b128 v[220:223], v164 offset:55296
	ds_read_b128 v[224:227], v164 offset:56320
	global_load_lds_dwordx4 v[158:159], off
	s_add_i32 m0, s38, 0x2000
	s_add_u32 s4, s4, 0x80080
	v_lshl_add_u64 v[158:159], v[174:175], 0, s[54:55]
	s_addc_u32 s5, s5, 0
	s_add_i32 s38, s72, s46
	global_load_lds_dwordx4 v[158:159], off
	v_lshl_add_u64 v[158:159], s[4:5], 0, v[176:177]
	s_mov_b32 m0, s38
	s_nop 0
	global_load_lds_dwordx4 v[158:159], off
	v_lshl_add_u64 v[158:159], s[4:5], 0, v[128:129]
	s_add_i32 m0, s38, 0x2000
	s_nop 0
	global_load_lds_dwordx4 v[158:159], off
	v_lshl_add_u64 v[158:159], v[194:195], 0, s[54:55]
	s_mov_b32 m0, s59
	s_nop 0
	global_load_lds_dwordx4 v[158:159], off
	v_lshl_add_u64 v[158:159], v[198:199], 0, s[54:55]
	s_mov_b32 m0, s60
	s_nop 0
	global_load_lds_dwordx4 v[158:159], off
	s_waitcnt vmcnt(8)
	s_waitcnt lgkmcnt(0)
	s_barrier
	s_setprio 1
	v_mfma_f32_16x16x32_bf16 v[60:63], v[138:141], v[182:185], v[60:63]
	v_mfma_f32_16x16x32_bf16 v[56:59], v[146:149], v[182:185], v[56:59]
	v_mfma_f32_16x16x32_bf16 v[44:47], v[138:141], v[190:193], v[44:47]
	v_mfma_f32_16x16x32_bf16 v[40:43], v[146:149], v[190:193], v[40:43]
	v_mfma_f32_16x16x32_bf16 v[28:31], v[138:141], v[212:215], v[28:31]
	v_mfma_f32_16x16x32_bf16 v[24:27], v[146:149], v[212:215], v[24:27]
	v_mfma_f32_16x16x32_bf16 v[12:15], v[138:141], v[220:223], v[12:15]
	v_mfma_f32_16x16x32_bf16 v[8:11], v[146:149], v[220:223], v[8:11]
	v_mfma_f32_16x16x32_bf16 v[60:63], v[142:145], v[186:189], v[60:63]
	v_mfma_f32_16x16x32_bf16 v[56:59], v[150:153], v[186:189], v[56:59]
	v_mfma_f32_16x16x32_bf16 v[44:47], v[142:145], v[208:211], v[44:47]
	v_mfma_f32_16x16x32_bf16 v[40:43], v[150:153], v[208:211], v[40:43]
	v_mfma_f32_16x16x32_bf16 v[28:31], v[142:145], v[216:219], v[28:31]
	v_mfma_f32_16x16x32_bf16 v[24:27], v[150:153], v[216:219], v[24:27]
	v_mfma_f32_16x16x32_bf16 v[12:15], v[142:145], v[224:227], v[12:15]
	v_mfma_f32_16x16x32_bf16 v[8:11], v[150:153], v[224:227], v[8:11]
	v_mfma_f32_16x16x32_bf16 v[52:55], v[154:157], v[182:185], v[52:55]
	v_mfma_f32_16x16x32_bf16 v[48:51], v[170:173], v[182:185], v[48:51]
	v_mfma_f32_16x16x32_bf16 v[36:39], v[154:157], v[190:193], v[36:39]
	v_mfma_f32_16x16x32_bf16 v[32:35], v[170:173], v[190:193], v[32:35]
	v_mfma_f32_16x16x32_bf16 v[20:23], v[154:157], v[212:215], v[20:23]
	v_mfma_f32_16x16x32_bf16 v[16:19], v[170:173], v[212:215], v[16:19]
	v_mfma_f32_16x16x32_bf16 v[4:7], v[154:157], v[220:223], v[4:7]
	v_mfma_f32_16x16x32_bf16 v[0:3], v[170:173], v[220:223], v[0:3]
	v_mfma_f32_16x16x32_bf16 v[52:55], v[166:169], v[186:189], v[52:55]
	v_mfma_f32_16x16x32_bf16 v[48:51], v[178:181], v[186:189], v[48:51]
	v_mfma_f32_16x16x32_bf16 v[36:39], v[166:169], v[208:211], v[36:39]
	v_mfma_f32_16x16x32_bf16 v[32:35], v[178:181], v[208:211], v[32:35]
	v_mfma_f32_16x16x32_bf16 v[20:23], v[166:169], v[216:219], v[20:23]
	v_mfma_f32_16x16x32_bf16 v[16:19], v[178:181], v[216:219], v[16:19]
	v_mfma_f32_16x16x32_bf16 v[4:7], v[166:169], v[224:227], v[4:7]
	v_mfma_f32_16x16x32_bf16 v[0:3], v[178:181], v[224:227], v[0:3]
	s_setprio 0
	s_barrier
	s_add_i32 s70, s70, 2
	s_add_u32 s2, s2, 0x100
	s_addc_u32 s3, s3, 0
	s_add_u32 s68, s68, 0x100
	s_addc_u32 s69, s69, 0
	s_cmp_gt_u32 s70, 29
	s_cbranch_scc0 .LBB0_304
	s_and_b64 vcc, exec, s[28:29]
	s_cbranch_vccz .LBB0_307
	s_barrier

; #define PG8_STAGE(bufoff, gbase, voff) do { _Pragma("unroll") for (int _i = 0; _i < 2; ++_i) \
;         __builtin_amdgcn_global_load_lds((const unsigned*)((const char*)(gbase) + (voff)[_i]), (LAS unsigned*)(lds + (bufoff) + ldsw + _i * 8192), 16, 0, 0); } while (0)
; #define PG8_LDA(dst, b, h) do { _Pragma("unroll") for (int m = 0; m < 4; ++m) _Pragma("unroll") for (int k = 0; k < 2; ++k) dst[m][k] = *(const LAS bf16x8*)(lds + PG8_SA(b, h) + aoff + m * 2048 + k * 1024); } while (0)
; #define PG8_LDB(dst, b, h) do { _Pragma("unroll") for (int n = 0; n < 2; ++n) _Pragma("unroll") for (int k = 0; k < 2; ++k) dst[n][k] = *(const LAS bf16x8*)(lds + PG8_SB(b, h) + boff + n * 2048 + k * 1024); } while (0)
; #define PG8_WAIT_V(n) asm volatile("s_waitcnt vmcnt(" #n ")" ::: "memory")
; #define PG8_WAIT_L(n) asm volatile("s_waitcnt lgkmcnt(" #n ")" ::: "memory")
; #define PG8_BAR __builtin_amdgcn_s_barrier()
; #define PG8_SCHED __builtin_amdgcn_sched_barrier(0)
; template <bool F16, class Sched, class Epi>
; __device__ __forceinline__ void gemm_phase(LAS unsigned char* lds, const Gemm g, const Sched& S, const Epi& E, int wave_s) {
;     ...
;         const char* nA = has_next ? (const char*)g.A + PG8_AOFF(nxt) : cA + (size_t)(nt - 2) * kstep; const char* nB = has_next ? (const char*)g.Bt + (size_t)nxt.pn * tstepB : cB + (size_t)(nt - 2) * kstep;
;         for (int t = 0; t < nt; t += 2) {
;             const bool last = (t == nt - 2);
;             const char* a1 = cA + (size_t)(t + 1) * kstep;
;             const char* a2 = last ? nA : cA + (size_t)(t + 2) * kstep; const char* b2 = last ? nB : cB + (size_t)(t + 2) * kstep;
;             const char* a3 = a2 + kstep; const char* b3 = b2 + kstep;
;             PG8_LDB(B0, 0, 0); PG8_LDB(B1, 0, 1); PG8_SCHED; PG8_LDA(At, 0, 0); PG8_STAGE(PG8_SA(1, 1), a1 + hstepA, voffA);
;             PG8_WAIT_V(8); PG8_WAIT_L(0); PG8_BAR; PG8_MMA(0, 0, At, B0); PG8_MMA(0, 1, At, B1); PG8_BAR; PG8_SCHED;
;             PG8_LDA(At, 0, 1); PG8_STAGE(PG8_SB(0, 0), b2, voffB); PG8_STAGE(PG8_SB(0, 1), b2 + hstepB, voffB); PG8_STAGE(PG8_SA(0, 0), a2, voffA);
.LBB0_358:
	s_add_i32 s65, 0, 0x10000
	s_add_i32 s70, 0, 0x14000
	v_add_u32_e32 v150, s65, v163
	v_add_u32_e32 v158, s70, v163
	ds_read_b128 v[138:141], v150
	ds_read_b128 v[142:145], v150 offset:1024
	ds_read_b128 v[146:149], v150 offset:2048
	ds_read_b128 v[150:153], v150 offset:3072
	ds_read_b128 v[154:157], v158
	ds_read_b128 v[168:171], v158 offset:1024
	ds_read_b128 v[172:175], v158 offset:2048
	ds_read_b128 v[178:181], v158 offset:3072
	s_add_i32 m0, s44, 0xc000
	ds_read_b128 v[182:185], v167
	ds_read_b128 v[186:189], v167 offset:1024
	ds_read_b128 v[190:193], v167 offset:2048
	ds_read_b128 v[208:211], v167 offset:3072
	ds_read_b128 v[212:215], v167 offset:4096
	ds_read_b128 v[216:219], v167 offset:5120
	ds_read_b128 v[220:223], v167 offset:6144
	ds_read_b128 v[224:227], v167 offset:7168
	global_load_lds_dwordx4 v134, s[2:3]
	s_add_i32 m0, s44, 0xe000
	s_nop 0
	global_load_lds_dwordx4 v136, s[2:3]
	s_waitcnt vmcnt(8)
	s_waitcnt lgkmcnt(0)
	s_barrier
	s_setprio 1
	v_mfma_f32_16x16x32_bf16 v[124:127], v[138:141], v[182:185], v[124:127]
	v_mfma_f32_16x16x32_bf16 v[120:123], v[146:149], v[182:185], v[120:123]
	v_mfma_f32_16x16x32_bf16 v[108:111], v[138:141], v[190:193], v[108:111]
	v_mfma_f32_16x16x32_bf16 v[104:107], v[146:149], v[190:193], v[104:107]
	v_mfma_f32_16x16x32_bf16 v[92:95], v[138:141], v[212:215], v[92:95]
	v_mfma_f32_16x16x32_bf16 v[88:91], v[146:149], v[212:215], v[88:91]
	v_mfma_f32_16x16x32_bf16 v[76:79], v[138:141], v[220:223], v[76:79]
	v_mfma_f32_16x16x32_bf16 v[72:75], v[146:149], v[220:223], v[72:75]
	v_mfma_f32_16x16x32_bf16 v[124:127], v[142:145], v[186:189], v[124:127]
	v_mfma_f32_16x16x32_bf16 v[120:123], v[150:153], v[186:189], v[120:123]
	v_mfma_f32_16x16x32_bf16 v[108:111], v[142:145], v[208:211], v[108:111]
	v_mfma_f32_16x16x32_bf16 v[104:107], v[150:153], v[208:211], v[104:107]
	v_mfma_f32_16x16x32_bf16 v[92:95], v[142:145], v[216:219], v[92:95]
	v_mfma_f32_16x16x32_bf16 v[88:91], v[150:153], v[216:219], v[88:91]
	v_mfma_f32_16x16x32_bf16 v[76:79], v[142:145], v[224:227], v[76:79]
	v_mfma_f32_16x16x32_bf16 v[72:75], v[150:153], v[224:227], v[72:75]
	v_mfma_f32_16x16x32_bf16 v[116:119], v[154:157], v[182:185], v[116:119]
	v_mfma_f32_16x16x32_bf16 v[112:115], v[172:175], v[182:185], v[112:115]
	v_mfma_f32_16x16x32_bf16 v[100:103], v[154:157], v[190:193], v[100:103]
	v_mfma_f32_16x16x32_bf16 v[96:99], v[172:175], v[190:193], v[96:99]
	v_mfma_f32_16x16x32_bf16 v[84:87], v[154:157], v[212:215], v[84:87]
	v_mfma_f32_16x16x32_bf16 v[80:83], v[172:175], v[212:215], v[80:83]
	v_mfma_f32_16x16x32_bf16 v[68:71], v[154:157], v[220:223], v[68:71]
	v_mfma_f32_16x16x32_bf16 v[64:67], v[172:175], v[220:223], v[64:67]
	v_mfma_f32_16x16x32_bf16 v[116:119], v[168:171], v[186:189], v[116:119]
	v_mfma_f32_16x16x32_bf16 v[112:115], v[178:181], v[186:189], v[112:115]
	v_mfma_f32_16x16x32_bf16 v[100:103], v[168:171], v[208:211], v[100:103]
	v_mfma_f32_16x16x32_bf16 v[96:99], v[178:181], v[208:211], v[96:99]
	v_mfma_f32_16x16x32_bf16 v[84:87], v[168:171], v[216:219], v[84:87]
	v_mfma_f32_16x16x32_bf16 v[80:83], v[178:181], v[216:219], v[80:83]
	v_mfma_f32_16x16x32_bf16 v[68:71], v[168:171], v[224:227], v[68:71]
	v_mfma_f32_16x16x32_bf16 v[64:67], v[178:181], v[224:227], v[64:67]
	s_setprio 0
	s_barrier
	s_add_u32 s30, s2, 0xfff80080
	s_addc_u32 s31, s3, -1
	s_cmp_eq_u32 s64, 28
	s_cselect_b32 s35, s58, s31
	s_cselect_b32 s34, s59, s30
	s_cselect_b32 s31, s60, s63
	s_cselect_b32 s30, s61, s62
	s_add_i32 s65, s65, s42
	v_lshl_add_u64 v[158:159], s[30:31], 0, v[176:177]
	s_mov_b32 m0, s65
	ds_read_b128 v[182:185], v167 offset:16384
	ds_read_b128 v[186:189], v167 offset:17408
	ds_read_b128 v[190:193], v167 offset:18432
	ds_read_b128 v[208:211], v167 offset:19456
	ds_read_b128 v[212:215], v167 offset:20480
	ds_read_b128 v[216:219], v167 offset:21504
	ds_read_b128 v[220:223], v167 offset:22528
	ds_read_b128 v[224:227], v167 offset:23552
	global_load_lds_dwordx4 v[158:159], off
	s_add_i32 m0, s65, 0x2000
	s_add_u32 s68, s30, 0x80000
	v_lshl_add_u64 v[194:195], s[30:31], 0, v[128:129]
	s_addc_u32 s69, s31, 0
	s_add_i32 s65, s70, s42
	global_load_lds_dwordx4 v[194:195], off
	v_lshl_add_u64 v[198:199], s[68:69], 0, v[176:177]
	s_mov_b32 m0, s65
	v_lshl_add_u64 v[200:201], s[34:35], 0, v[130:131]
	global_load_lds_dwordx4 v[198:199], off
	v_lshl_add_u64 v[198:199], s[68:69], 0, v[128:129]
	s_add_i32 m0, s65, 0x2000
	s_nop 0
	global_load_lds_dwordx4 v[198:199], off
	v_lshl_add_u64 v[198:199], s[34:35], 0, v[132:133]
	s_mov_b32 m0, s44
	s_nop 0
	global_load_lds_dwordx4 v[198:199], off
	s_mov_b32 m0, s46
	s_nop 0
	global_load_lds_dwordx4 v[200:201], off
	s_add_u32 s34, s34, 0x80000
	s_addc_u32 s35, s35, 0
	s_waitcnt vmcnt(8)
	s_waitcnt lgkmcnt(0)
	s_barrier
; #define PG8_STAGE(bufoff, gbase, voff) do { _Pragma("unroll") for (int _i = 0; _i < 2; ++_i) \
;         __builtin_amdgcn_global_load_lds((const unsigned*)((const char*)(gbase) + (voff)[_i]), (LAS unsigned*)(lds + (bufoff) + ldsw + _i * 8192), 16, 0, 0); } while (0)
; #define PG8_LDA(dst, b, h) do { _Pragma("unroll") for (int m = 0; m < 4; ++m) _Pragma("unroll") for (int k = 0; k < 2; ++k) dst[m][k] = *(const LAS bf16x8*)(lds + PG8_SA(b, h) + aoff + m * 2048 + k * 1024); } while (0)
; #define PG8_LDB(dst, b, h) do { _Pragma("unroll") for (int n = 0; n < 2; ++n) _Pragma("unroll") for (int k = 0; k < 2; ++k) dst[n][k] = *(const LAS bf16x8*)(lds + PG8_SB(b, h) + boff + n * 2048 + k * 1024); } while (0)
; #define PG8_WAIT_V(n) asm volatile("s_waitcnt vmcnt(" #n ")" ::: "memory")
; #define PG8_WAIT_L(n) asm volatile("s_waitcnt lgkmcnt(" #n ")" ::: "memory")
; #define PG8_BAR __builtin_amdgcn_s_barrier()
; #define PG8_SCHED __builtin_amdgcn_sched_barrier(0)
; template <bool F16, class Sched, class Epi>
; __device__ __forceinline__ void gemm_phase(LAS unsigned char* lds, const Gemm g, const Sched& S, const Epi& E, int wave_s) {
;     ...
;             PG8_WAIT_V(8); PG8_WAIT_L(0); PG8_BAR; PG8_MMA(1, 0, At, B0); PG8_MMA(1, 1, At, B1); PG8_BAR; PG8_SCHED;
;             PG8_LDB(B0, 1, 0); PG8_LDB(B1, 1, 1); PG8_SCHED; PG8_LDA(At, 1, 0); PG8_STAGE(PG8_SA(0, 1), a2 + hstepA, voffA);
;             PG8_WAIT_V(8); PG8_WAIT_L(0); PG8_BAR; PG8_MMA(0, 0, At, B0); PG8_MMA(0, 1, At, B1); PG8_BAR; PG8_SCHED;
	s_setprio 1
	v_mfma_f32_16x16x32_bf16 v[60:63], v[138:141], v[182:185], v[60:63]
	v_mfma_f32_16x16x32_bf16 v[56:59], v[146:149], v[182:185], v[56:59]
	v_mfma_f32_16x16x32_bf16 v[48:51], v[138:141], v[190:193], v[48:51]
	v_mfma_f32_16x16x32_bf16 v[40:43], v[146:149], v[190:193], v[40:43]
	v_mfma_f32_16x16x32_bf16 v[32:35], v[138:141], v[212:215], v[32:35]
	v_mfma_f32_16x16x32_bf16 v[24:27], v[146:149], v[212:215], v[24:27]
	v_mfma_f32_16x16x32_bf16 v[16:19], v[138:141], v[220:223], v[16:19]
	v_mfma_f32_16x16x32_bf16 v[8:11], v[146:149], v[220:223], v[8:11]
	v_mfma_f32_16x16x32_bf16 v[60:63], v[142:145], v[186:189], v[60:63]
	v_mfma_f32_16x16x32_bf16 v[56:59], v[150:153], v[186:189], v[56:59]
	v_mfma_f32_16x16x32_bf16 v[48:51], v[142:145], v[208:211], v[48:51]
	v_mfma_f32_16x16x32_bf16 v[40:43], v[150:153], v[208:211], v[40:43]
	v_mfma_f32_16x16x32_bf16 v[32:35], v[142:145], v[216:219], v[32:35]
	v_mfma_f32_16x16x32_bf16 v[24:27], v[150:153], v[216:219], v[24:27]
	v_mfma_f32_16x16x32_bf16 v[16:19], v[142:145], v[224:227], v[16:19]
	v_mfma_f32_16x16x32_bf16 v[8:11], v[150:153], v[224:227], v[8:11]
	v_mfma_f32_16x16x32_bf16 v[52:55], v[154:157], v[182:185], v[52:55]
	v_mfma_f32_16x16x32_bf16 v[44:47], v[172:175], v[182:185], v[44:47]
	v_mfma_f32_16x16x32_bf16 v[36:39], v[154:157], v[190:193], v[36:39]
	v_mfma_f32_16x16x32_bf16 v[28:31], v[172:175], v[190:193], v[28:31]
	v_mfma_f32_16x16x32_bf16 v[20:23], v[154:157], v[212:215], v[20:23]
	v_mfma_f32_16x16x32_bf16 v[12:15], v[172:175], v[212:215], v[12:15]
	v_mfma_f32_16x16x32_bf16 v[4:7], v[154:157], v[220:223], v[4:7]
	v_mfma_f32_16x16x32_bf16 v[0:3], v[172:175], v[220:223], v[0:3]
	v_mfma_f32_16x16x32_bf16 v[52:55], v[168:171], v[186:189], v[52:55]
	v_mfma_f32_16x16x32_bf16 v[44:47], v[178:181], v[186:189], v[44:47]
	v_mfma_f32_16x16x32_bf16 v[36:39], v[168:171], v[208:211], v[36:39]
	v_mfma_f32_16x16x32_bf16 v[28:31], v[178:181], v[208:211], v[28:31]
	v_mfma_f32_16x16x32_bf16 v[20:23], v[168:171], v[216:219], v[20:23]
	v_mfma_f32_16x16x32_bf16 v[12:15], v[178:181], v[216:219], v[12:15]
	v_mfma_f32_16x16x32_bf16 v[4:7], v[168:171], v[224:227], v[4:7]
	v_mfma_f32_16x16x32_bf16 v[0:3], v[178:181], v[224:227], v[0:3]
	s_setprio 0
	s_barrier
	s_add_i32 s65, 0, 0x18000
	s_add_i32 s68, 0, 0x1c000
	v_add_u32_e32 v150, s65, v163
	v_add_u32_e32 v160, s68, v163
	ds_read_b128 v[138:141], v150
	ds_read_b128 v[142:145], v150 offset:1024
	ds_read_b128 v[146:149], v150 offset:2048
	ds_read_b128 v[150:153], v150 offset:3072
	ds_read_b128 v[154:157], v160
	ds_read_b128 v[168:171], v160 offset:1024
	ds_read_b128 v[172:175], v160 offset:2048
	ds_read_b128 v[178:181], v160 offset:3072
	s_mov_b32 m0, s47
	ds_read_b128 v[182:185], v167 offset:32768
	ds_read_b128 v[186:189], v167 offset:33792
	ds_read_b128 v[190:193], v167 offset:34816
	ds_read_b128 v[208:211], v167 offset:35840
	ds_read_b128 v[212:215], v167 offset:36864
	ds_read_b128 v[216:219], v167 offset:37888
	ds_read_b128 v[220:223], v167 offset:38912
	ds_read_b128 v[224:227], v167 offset:39936
	global_load_lds_dwordx4 v132, s[34:35]
	s_mov_b32 m0, s48
	s_nop 0
	global_load_lds_dwordx4 v130, s[34:35]
	s_waitcnt vmcnt(8)
	s_waitcnt lgkmcnt(0)
	s_barrier
	s_setprio 1
	v_mfma_f32_16x16x32_bf16 v[124:127], v[138:141], v[182:185], v[124:127]
	v_mfma_f32_16x16x32_bf16 v[120:123], v[146:149], v[182:185], v[120:123]
	v_mfma_f32_16x16x32_bf16 v[108:111], v[138:141], v[190:193], v[108:111]
	v_mfma_f32_16x16x32_bf16 v[104:107], v[146:149], v[190:193], v[104:107]
	v_mfma_f32_16x16x32_bf16 v[92:95], v[138:141], v[212:215], v[92:95]
	v_mfma_f32_16x16x32_bf16 v[88:91], v[146:149], v[212:215], v[88:91]
	v_mfma_f32_16x16x32_bf16 v[76:79], v[138:141], v[220:223], v[76:79]
	v_mfma_f32_16x16x32_bf16 v[72:75], v[146:149], v[220:223], v[72:75]
	v_mfma_f32_16x16x32_bf16 v[124:127], v[142:145], v[186:189], v[124:127]
	v_mfma_f32_16x16x32_bf16 v[120:123], v[150:153], v[186:189], v[120:123]
	v_mfma_f32_16x16x32_bf16 v[108:111], v[142:145], v[208:211], v[108:111]
	v_mfma_f32_16x16x32_bf16 v[104:107], v[150:153], v[208:211], v[104:107]
	v_mfma_f32_16x16x32_bf16 v[92:95], v[142:145], v[216:219], v[92:95]
	v_mfma_f32_16x16x32_bf16 v[88:91], v[150:153], v[216:219], v[88:91]
	v_mfma_f32_16x16x32_bf16 v[76:79], v[142:145], v[224:227], v[76:79]
	v_mfma_f32_16x16x32_bf16 v[72:75], v[150:153], v[224:227], v[72:75]
	v_mfma_f32_16x16x32_bf16 v[116:119], v[154:157], v[182:185], v[116:119]
	v_mfma_f32_16x16x32_bf16 v[112:115], v[172:175], v[182:185], v[112:115]
	v_mfma_f32_16x16x32_bf16 v[100:103], v[154:157], v[190:193], v[100:103]
	v_mfma_f32_16x16x32_bf16 v[96:99], v[172:175], v[190:193], v[96:99]
	v_mfma_f32_16x16x32_bf16 v[84:87], v[154:157], v[212:215], v[84:87]
	v_mfma_f32_16x16x32_bf16 v[80:83], v[172:175], v[212:215], v[80:83]
	v_mfma_f32_16x16x32_bf16 v[68:71], v[154:157], v[220:223], v[68:71]
	v_mfma_f32_16x16x32_bf16 v[64:67], v[172:175], v[220:223], v[64:67]
	v_mfma_f32_16x16x32_bf16 v[116:119], v[168:171], v[186:189], v[116:119]
	v_mfma_f32_16x16x32_bf16 v[112:115], v[178:181], v[186:189], v[112:115]
	v_mfma_f32_16x16x32_bf16 v[100:103], v[168:171], v[208:211], v[100:103]
	v_mfma_f32_16x16x32_bf16 v[96:99], v[178:181], v[208:211], v[96:99]
	v_mfma_f32_16x16x32_bf16 v[84:87], v[168:171], v[216:219], v[84:87]
	v_mfma_f32_16x16x32_bf16 v[80:83], v[178:181], v[216:219], v[80:83]
	v_mfma_f32_16x16x32_bf16 v[68:71], v[168:171], v[224:227], v[68:71]
	v_mfma_f32_16x16x32_bf16 v[64:67], v[178:181], v[224:227], v[64:67]
	s_setprio 0
	s_barrier
; #define PG8_STAGE(bufoff, gbase, voff) do { _Pragma("unroll") for (int _i = 0; _i < 2; ++_i) \
;         __builtin_amdgcn_global_load_lds((const unsigned*)((const char*)(gbase) + (voff)[_i]), (LAS unsigned*)(lds + (bufoff) + ldsw + _i * 8192), 16, 0, 0); } while (0)
; #define PG8_LDA(dst, b, h) do { _Pragma("unroll") for (int m = 0; m < 4; ++m) _Pragma("unroll") for (int k = 0; k < 2; ++k) dst[m][k] = *(const LAS bf16x8*)(lds + PG8_SA(b, h) + aoff + m * 2048 + k * 1024); } while (0)
; #define PG8_WAIT_V(n) asm volatile("s_waitcnt vmcnt(" #n ")" ::: "memory")
; #define PG8_WAIT_L(n) asm volatile("s_waitcnt lgkmcnt(" #n ")" ::: "memory")
; #define PG8_BAR __builtin_amdgcn_s_barrier()
; #define PG8_SCHED __builtin_amdgcn_sched_barrier(0)
; template <bool F16, class Sched, class Epi>
; __device__ __forceinline__ void gemm_phase(LAS unsigned char* lds, const Gemm g, const Sched& S, const Epi& E, int wave_s) {
;     ...
;             PG8_LDA(At, 1, 1); PG8_STAGE(PG8_SB(1, 0), b3, voffB); PG8_STAGE(PG8_SB(1, 1), b3 + hstepB, voffB); PG8_STAGE(PG8_SA(1, 0), a3, voffA);
;             PG8_WAIT_V(8); PG8_WAIT_L(0); PG8_BAR; PG8_MMA(1, 0, At, B0); PG8_MMA(1, 1, At, B1); PG8_BAR; PG8_SCHED;
;         }
;         if (wr == 0) PG8_BAR;
	s_add_i32 s34, s65, s42
	v_lshl_add_u64 v[158:159], v[158:159], 0, s[54:55]
	s_mov_b32 m0, s34
	ds_read_b128 v[182:185], v167 offset:49152
	ds_read_b128 v[186:189], v167 offset:50176
	ds_read_b128 v[190:193], v167 offset:51200
	ds_read_b128 v[208:211], v167 offset:52224
	ds_read_b128 v[212:215], v167 offset:53248
	ds_read_b128 v[216:219], v167 offset:54272
	ds_read_b128 v[220:223], v167 offset:55296
	ds_read_b128 v[224:227], v167 offset:56320
	global_load_lds_dwordx4 v[158:159], off
	s_add_i32 m0, s34, 0x2000
	s_add_u32 s30, s30, 0x80080
	v_lshl_add_u64 v[158:159], v[194:195], 0, s[54:55]
	s_addc_u32 s31, s31, 0
	s_add_i32 s34, s68, s42
	global_load_lds_dwordx4 v[158:159], off
	v_lshl_add_u64 v[158:159], s[30:31], 0, v[176:177]
	s_mov_b32 m0, s34
	s_nop 0
	global_load_lds_dwordx4 v[158:159], off
	v_lshl_add_u64 v[158:159], s[30:31], 0, v[128:129]
	s_add_i32 m0, s34, 0x2000
	s_nop 0
	global_load_lds_dwordx4 v[158:159], off
	v_lshl_add_u64 v[158:159], v[198:199], 0, s[54:55]
	s_mov_b32 m0, s49
	s_nop 0
	global_load_lds_dwordx4 v[158:159], off
	v_lshl_add_u64 v[158:159], v[200:201], 0, s[54:55]
	s_mov_b32 m0, s52
	s_nop 0
	global_load_lds_dwordx4 v[158:159], off
	s_waitcnt vmcnt(8)
	s_waitcnt lgkmcnt(0)
	s_barrier
	s_setprio 1
	v_mfma_f32_16x16x32_bf16 v[60:63], v[138:141], v[182:185], v[60:63]
	v_mfma_f32_16x16x32_bf16 v[56:59], v[146:149], v[182:185], v[56:59]
	v_mfma_f32_16x16x32_bf16 v[48:51], v[138:141], v[190:193], v[48:51]
	v_mfma_f32_16x16x32_bf16 v[40:43], v[146:149], v[190:193], v[40:43]
	v_mfma_f32_16x16x32_bf16 v[32:35], v[138:141], v[212:215], v[32:35]
	v_mfma_f32_16x16x32_bf16 v[24:27], v[146:149], v[212:215], v[24:27]
	v_mfma_f32_16x16x32_bf16 v[16:19], v[138:141], v[220:223], v[16:19]
	v_mfma_f32_16x16x32_bf16 v[8:11], v[146:149], v[220:223], v[8:11]
	v_mfma_f32_16x16x32_bf16 v[60:63], v[142:145], v[186:189], v[60:63]
	v_mfma_f32_16x16x32_bf16 v[56:59], v[150:153], v[186:189], v[56:59]
	v_mfma_f32_16x16x32_bf16 v[48:51], v[142:145], v[208:211], v[48:51]
	v_mfma_f32_16x16x32_bf16 v[40:43], v[150:153], v[208:211], v[40:43]
	v_mfma_f32_16x16x32_bf16 v[32:35], v[142:145], v[216:219], v[32:35]
	v_mfma_f32_16x16x32_bf16 v[24:27], v[150:153], v[216:219], v[24:27]
	v_mfma_f32_16x16x32_bf16 v[16:19], v[142:145], v[224:227], v[16:19]
	v_mfma_f32_16x16x32_bf16 v[8:11], v[150:153], v[224:227], v[8:11]
	v_mfma_f32_16x16x32_bf16 v[52:55], v[154:157], v[182:185], v[52:55]
	v_mfma_f32_16x16x32_bf16 v[44:47], v[172:175], v[182:185], v[44:47]
	v_mfma_f32_16x16x32_bf16 v[36:39], v[154:157], v[190:193], v[36:39]
	v_mfma_f32_16x16x32_bf16 v[28:31], v[172:175], v[190:193], v[28:31]
	v_mfma_f32_16x16x32_bf16 v[20:23], v[154:157], v[212:215], v[20:23]
	v_mfma_f32_16x16x32_bf16 v[12:15], v[172:175], v[212:215], v[12:15]
	v_mfma_f32_16x16x32_bf16 v[4:7], v[154:157], v[220:223], v[4:7]
	v_mfma_f32_16x16x32_bf16 v[0:3], v[172:175], v[220:223], v[0:3]
	v_mfma_f32_16x16x32_bf16 v[52:55], v[168:171], v[186:189], v[52:55]
	v_mfma_f32_16x16x32_bf16 v[44:47], v[178:181], v[186:189], v[44:47]
	v_mfma_f32_16x16x32_bf16 v[36:39], v[168:171], v[208:211], v[36:39]
	v_mfma_f32_16x16x32_bf16 v[28:31], v[178:181], v[208:211], v[28:31]
	v_mfma_f32_16x16x32_bf16 v[20:23], v[168:171], v[216:219], v[20:23]
	v_mfma_f32_16x16x32_bf16 v[12:15], v[178:181], v[216:219], v[12:15]
	v_mfma_f32_16x16x32_bf16 v[4:7], v[168:171], v[224:227], v[4:7]
	v_mfma_f32_16x16x32_bf16 v[0:3], v[178:181], v[224:227], v[0:3]
	s_setprio 0
	s_barrier
	s_add_i32 s64, s64, 2
	s_add_u32 s2, s2, 0x100
	s_addc_u32 s3, s3, 0
	s_add_u32 s62, s62, 0x100
	s_addc_u32 s63, s63, 0
	s_cmp_gt_u32 s64, 29
	s_cbranch_scc0 .LBB0_358
	s_and_b64 vcc, exec, s[26:27]
	s_cbranch_vccz .LBB0_361
	s_barrier

; #define PG8_STAGE(bufoff, gbase, voff) do { _Pragma("unroll") for (int _i = 0; _i < 2; ++_i) \
;         __builtin_amdgcn_global_load_lds((const unsigned*)((const char*)(gbase) + (voff)[_i]), (LAS unsigned*)(lds + (bufoff) + ldsw + _i * 8192), 16, 0, 0); } while (0)
; #define PG8_LDA(dst, b, h) do { _Pragma("unroll") for (int m = 0; m < 4; ++m) _Pragma("unroll") for (int k = 0; k < 2; ++k) dst[m][k] = *(const LAS bf16x8*)(lds + PG8_SA(b, h) + aoff + m * 2048 + k * 1024); } while (0)
; #define PG8_LDB(dst, b, h) do { _Pragma("unroll") for (int n = 0; n < 2; ++n) _Pragma("unroll") for (int k = 0; k < 2; ++k) dst[n][k] = *(const LAS bf16x8*)(lds + PG8_SB(b, h) + boff + n * 2048 + k * 1024); } while (0)
; #define PG8_WAIT_V(n) asm volatile("s_waitcnt vmcnt(" #n ")" ::: "memory")
; #define PG8_WAIT_L(n) asm volatile("s_waitcnt lgkmcnt(" #n ")" ::: "memory")
; #define PG8_BAR __builtin_amdgcn_s_barrier()
; #define PG8_SCHED __builtin_amdgcn_sched_barrier(0)
; template <bool F16, class Sched, class Epi>
; __device__ __forceinline__ void gemm_phase(LAS unsigned char* lds, const Gemm g, const Sched& S, const Epi& E, int wave_s) {
;     ...
;         const char* nA = has_next ? (const char*)g.A + PG8_AOFF(nxt) : cA + (size_t)(nt - 2) * kstep; const char* nB = has_next ? (const char*)g.Bt + (size_t)nxt.pn * tstepB : cB + (size_t)(nt - 2) * kstep;
;         for (int t = 0; t < nt; t += 2) {
;             const bool last = (t == nt - 2);
;             const char* a1 = cA + (size_t)(t + 1) * kstep;
;             const char* a2 = last ? nA : cA + (size_t)(t + 2) * kstep; const char* b2 = last ? nB : cB + (size_t)(t + 2) * kstep;
;             const char* a3 = a2 + kstep; const char* b3 = b2 + kstep;
;             PG8_LDB(B0, 0, 0); PG8_LDB(B1, 0, 1); PG8_SCHED; PG8_LDA(At, 0, 0); PG8_STAGE(PG8_SA(1, 1), a1 + hstepA, voffA);
;             PG8_WAIT_V(8); PG8_WAIT_L(0); PG8_BAR; PG8_MMA(0, 0, At, B0); PG8_MMA(0, 1, At, B1); PG8_BAR; PG8_SCHED;
;             PG8_LDA(At, 0, 1); PG8_STAGE(PG8_SB(0, 0), b2, voffB); PG8_STAGE(PG8_SB(0, 1), b2 + hstepB, voffB); PG8_STAGE(PG8_SA(0, 0), a2, voffA);
.LBB0_598:
	s_add_i32 s61, 0, 0x10000
	s_add_i32 s64, 0, 0x14000
	v_add_u32_e32 v150, s61, v163
	v_add_u32_e32 v170, s64, v163
	ds_read_b128 v[138:141], v150
	ds_read_b128 v[142:145], v150 offset:1024
	ds_read_b128 v[146:149], v150 offset:2048
	ds_read_b128 v[150:153], v150 offset:3072
	ds_read_b128 v[154:157], v170
	ds_read_b128 v[158:161], v170 offset:1024
	ds_read_b128 v[166:169], v170 offset:2048
	ds_read_b128 v[170:173], v170 offset:3072
	s_add_i32 m0, s43, 0xc000
	ds_read_b128 v[178:181], v165
	ds_read_b128 v[182:185], v165 offset:1024
	ds_read_b128 v[186:189], v165 offset:2048
	ds_read_b128 v[190:193], v165 offset:3072
	ds_read_b128 v[208:211], v165 offset:4096
	ds_read_b128 v[212:215], v165 offset:5120
	ds_read_b128 v[216:219], v165 offset:6144
	ds_read_b128 v[220:223], v165 offset:7168
	global_load_lds_dwordx4 v134, s[26:27]
	s_add_i32 m0, s43, 0xe000
	s_nop 0
	global_load_lds_dwordx4 v136, s[26:27]
	s_waitcnt vmcnt(8)
	s_waitcnt lgkmcnt(0)
	s_barrier
	s_setprio 1
	v_mfma_f32_16x16x32_bf16 v[124:127], v[138:141], v[178:181], v[124:127]
	v_mfma_f32_16x16x32_bf16 v[120:123], v[146:149], v[178:181], v[120:123]
	v_mfma_f32_16x16x32_bf16 v[108:111], v[138:141], v[186:189], v[108:111]
	v_mfma_f32_16x16x32_bf16 v[104:107], v[146:149], v[186:189], v[104:107]
	v_mfma_f32_16x16x32_bf16 v[96:99], v[138:141], v[208:211], v[96:99]
	v_mfma_f32_16x16x32_bf16 v[92:95], v[146:149], v[208:211], v[92:95]
	v_mfma_f32_16x16x32_bf16 v[84:87], v[138:141], v[216:219], v[84:87]
	v_mfma_f32_16x16x32_bf16 v[76:79], v[146:149], v[216:219], v[76:79]
	v_mfma_f32_16x16x32_bf16 v[124:127], v[142:145], v[182:185], v[124:127]
	v_mfma_f32_16x16x32_bf16 v[120:123], v[150:153], v[182:185], v[120:123]
	v_mfma_f32_16x16x32_bf16 v[108:111], v[142:145], v[190:193], v[108:111]
	v_mfma_f32_16x16x32_bf16 v[104:107], v[150:153], v[190:193], v[104:107]
	v_mfma_f32_16x16x32_bf16 v[96:99], v[142:145], v[212:215], v[96:99]
	v_mfma_f32_16x16x32_bf16 v[92:95], v[150:153], v[212:215], v[92:95]
	v_mfma_f32_16x16x32_bf16 v[84:87], v[142:145], v[220:223], v[84:87]
	v_mfma_f32_16x16x32_bf16 v[76:79], v[150:153], v[220:223], v[76:79]
	v_mfma_f32_16x16x32_bf16 v[116:119], v[154:157], v[178:181], v[116:119]
	v_mfma_f32_16x16x32_bf16 v[112:115], v[166:169], v[178:181], v[112:115]
	v_mfma_f32_16x16x32_bf16 v[100:103], v[154:157], v[186:189], v[100:103]
	v_mfma_f32_16x16x32_bf16 v[88:91], v[166:169], v[186:189], v[88:91]
	v_mfma_f32_16x16x32_bf16 v[80:83], v[154:157], v[208:211], v[80:83]
	v_mfma_f32_16x16x32_bf16 v[72:75], v[166:169], v[208:211], v[72:75]
	v_mfma_f32_16x16x32_bf16 v[68:71], v[154:157], v[216:219], v[68:71]
	v_mfma_f32_16x16x32_bf16 v[64:67], v[166:169], v[216:219], v[64:67]
	v_mfma_f32_16x16x32_bf16 v[116:119], v[158:161], v[182:185], v[116:119]
	v_mfma_f32_16x16x32_bf16 v[112:115], v[170:173], v[182:185], v[112:115]
	v_mfma_f32_16x16x32_bf16 v[100:103], v[158:161], v[190:193], v[100:103]
	v_mfma_f32_16x16x32_bf16 v[88:91], v[170:173], v[190:193], v[88:91]
	v_mfma_f32_16x16x32_bf16 v[80:83], v[158:161], v[212:215], v[80:83]
	v_mfma_f32_16x16x32_bf16 v[72:75], v[170:173], v[212:215], v[72:75]
	v_mfma_f32_16x16x32_bf16 v[68:71], v[158:161], v[220:223], v[68:71]
	v_mfma_f32_16x16x32_bf16 v[64:67], v[170:173], v[220:223], v[64:67]
	s_setprio 0
	s_barrier
	s_add_u32 s28, s26, 0xfff80080
	s_addc_u32 s29, s27, -1
	s_cmp_eq_u32 s60, 28
	s_cselect_b32 s31, s49, s29
	s_cselect_b32 s30, s50, s28
	s_cselect_b32 s29, s52, s59
	s_cselect_b32 s28, s53, s58
	s_add_i32 s61, s61, s39
	v_lshl_add_u64 v[174:175], s[28:29], 0, v[176:177]
	s_mov_b32 m0, s61
	ds_read_b128 v[178:181], v165 offset:16384
	ds_read_b128 v[182:185], v165 offset:17408
	ds_read_b128 v[186:189], v165 offset:18432
	ds_read_b128 v[190:193], v165 offset:19456
	ds_read_b128 v[208:211], v165 offset:20480
	ds_read_b128 v[212:215], v165 offset:21504
	ds_read_b128 v[216:219], v165 offset:22528
	ds_read_b128 v[220:223], v165 offset:23552
	global_load_lds_dwordx4 v[174:175], off
	s_add_i32 m0, s61, 0x2000
	s_add_u32 s62, s28, 0x80000
	v_lshl_add_u64 v[194:195], s[28:29], 0, v[128:129]
	s_addc_u32 s63, s29, 0
	s_add_i32 s61, s64, s39
	global_load_lds_dwordx4 v[194:195], off
	v_lshl_add_u64 v[198:199], s[62:63], 0, v[176:177]
	s_mov_b32 m0, s61
	v_lshl_add_u64 v[200:201], s[30:31], 0, v[130:131]
	global_load_lds_dwordx4 v[198:199], off
	v_lshl_add_u64 v[198:199], s[62:63], 0, v[128:129]
	s_add_i32 m0, s61, 0x2000
	s_nop 0
	global_load_lds_dwordx4 v[198:199], off
	v_lshl_add_u64 v[198:199], s[30:31], 0, v[132:133]
	s_mov_b32 m0, s43
	s_nop 0
	global_load_lds_dwordx4 v[198:199], off
	s_mov_b32 m0, s44
	s_nop 0
	global_load_lds_dwordx4 v[200:201], off
	s_add_u32 s30, s30, 0x80000
	s_addc_u32 s31, s31, 0
	s_waitcnt vmcnt(8)
	s_waitcnt lgkmcnt(0)
	s_barrier
; #define PG8_STAGE(bufoff, gbase, voff) do { _Pragma("unroll") for (int _i = 0; _i < 2; ++_i) \
;         __builtin_amdgcn_global_load_lds((const unsigned*)((const char*)(gbase) + (voff)[_i]), (LAS unsigned*)(lds + (bufoff) + ldsw + _i * 8192), 16, 0, 0); } while (0)
; #define PG8_LDA(dst, b, h) do { _Pragma("unroll") for (int m = 0; m < 4; ++m) _Pragma("unroll") for (int k = 0; k < 2; ++k) dst[m][k] = *(const LAS bf16x8*)(lds + PG8_SA(b, h) + aoff + m * 2048 + k * 1024); } while (0)
; #define PG8_LDB(dst, b, h) do { _Pragma("unroll") for (int n = 0; n < 2; ++n) _Pragma("unroll") for (int k = 0; k < 2; ++k) dst[n][k] = *(const LAS bf16x8*)(lds + PG8_SB(b, h) + boff + n * 2048 + k * 1024); } while (0)
; #define PG8_WAIT_V(n) asm volatile("s_waitcnt vmcnt(" #n ")" ::: "memory")
; #define PG8_WAIT_L(n) asm volatile("s_waitcnt lgkmcnt(" #n ")" ::: "memory")
; #define PG8_BAR __builtin_amdgcn_s_barrier()
; #define PG8_SCHED __builtin_amdgcn_sched_barrier(0)
; template <bool F16, class Sched, class Epi>
; __device__ __forceinline__ void gemm_phase(LAS unsigned char* lds, const Gemm g, const Sched& S, const Epi& E, int wave_s) {
;     ...
;             PG8_WAIT_V(8); PG8_WAIT_L(0); PG8_BAR; PG8_MMA(1, 0, At, B0); PG8_MMA(1, 1, At, B1); PG8_BAR; PG8_SCHED;
;             PG8_LDB(B0, 1, 0); PG8_LDB(B1, 1, 1); PG8_SCHED; PG8_LDA(At, 1, 0); PG8_STAGE(PG8_SA(0, 1), a2 + hstepA, voffA);
;             PG8_WAIT_V(8); PG8_WAIT_L(0); PG8_BAR; PG8_MMA(0, 0, At, B0); PG8_MMA(0, 1, At, B1); PG8_BAR; PG8_SCHED;
	s_setprio 1
	v_mfma_f32_16x16x32_bf16 v[60:63], v[138:141], v[178:181], v[60:63]
	v_mfma_f32_16x16x32_bf16 v[56:59], v[146:149], v[178:181], v[56:59]
	v_mfma_f32_16x16x32_bf16 v[52:55], v[138:141], v[186:189], v[52:55]
	v_mfma_f32_16x16x32_bf16 v[44:47], v[146:149], v[186:189], v[44:47]
	v_mfma_f32_16x16x32_bf16 v[36:39], v[138:141], v[208:211], v[36:39]
	v_mfma_f32_16x16x32_bf16 v[28:31], v[146:149], v[208:211], v[28:31]
	v_mfma_f32_16x16x32_bf16 v[20:23], v[138:141], v[216:219], v[20:23]
	v_mfma_f32_16x16x32_bf16 v[12:15], v[146:149], v[216:219], v[12:15]
	v_mfma_f32_16x16x32_bf16 v[60:63], v[142:145], v[182:185], v[60:63]
	v_mfma_f32_16x16x32_bf16 v[56:59], v[150:153], v[182:185], v[56:59]
	v_mfma_f32_16x16x32_bf16 v[52:55], v[142:145], v[190:193], v[52:55]
	v_mfma_f32_16x16x32_bf16 v[44:47], v[150:153], v[190:193], v[44:47]
	v_mfma_f32_16x16x32_bf16 v[36:39], v[142:145], v[212:215], v[36:39]
	v_mfma_f32_16x16x32_bf16 v[28:31], v[150:153], v[212:215], v[28:31]
	v_mfma_f32_16x16x32_bf16 v[20:23], v[142:145], v[220:223], v[20:23]
	v_mfma_f32_16x16x32_bf16 v[12:15], v[150:153], v[220:223], v[12:15]
	v_mfma_f32_16x16x32_bf16 v[48:51], v[154:157], v[178:181], v[48:51]
	v_mfma_f32_16x16x32_bf16 v[40:43], v[166:169], v[178:181], v[40:43]
	v_mfma_f32_16x16x32_bf16 v[32:35], v[154:157], v[186:189], v[32:35]
	v_mfma_f32_16x16x32_bf16 v[24:27], v[166:169], v[186:189], v[24:27]
	v_mfma_f32_16x16x32_bf16 v[16:19], v[154:157], v[208:211], v[16:19]
	v_mfma_f32_16x16x32_bf16 v[8:11], v[166:169], v[208:211], v[8:11]
	v_mfma_f32_16x16x32_bf16 v[4:7], v[154:157], v[216:219], v[4:7]
	v_mfma_f32_16x16x32_bf16 v[0:3], v[166:169], v[216:219], v[0:3]
	v_mfma_f32_16x16x32_bf16 v[48:51], v[158:161], v[182:185], v[48:51]
	v_mfma_f32_16x16x32_bf16 v[40:43], v[170:173], v[182:185], v[40:43]
	v_mfma_f32_16x16x32_bf16 v[32:35], v[158:161], v[190:193], v[32:35]
	v_mfma_f32_16x16x32_bf16 v[24:27], v[170:173], v[190:193], v[24:27]
	v_mfma_f32_16x16x32_bf16 v[16:19], v[158:161], v[212:215], v[16:19]
	v_mfma_f32_16x16x32_bf16 v[8:11], v[170:173], v[212:215], v[8:11]
	v_mfma_f32_16x16x32_bf16 v[4:7], v[158:161], v[220:223], v[4:7]
	v_mfma_f32_16x16x32_bf16 v[0:3], v[170:173], v[220:223], v[0:3]
	s_setprio 0
	s_barrier
	s_add_i32 s61, 0, 0x18000
	s_add_i32 s62, 0, 0x1c000
	v_add_u32_e32 v150, s61, v163
	v_add_u32_e32 v170, s62, v163
	ds_read_b128 v[138:141], v150
	ds_read_b128 v[142:145], v150 offset:1024
	ds_read_b128 v[146:149], v150 offset:2048
	ds_read_b128 v[150:153], v150 offset:3072
	ds_read_b128 v[154:157], v170
	ds_read_b128 v[158:161], v170 offset:1024
	ds_read_b128 v[166:169], v170 offset:2048
	ds_read_b128 v[170:173], v170 offset:3072
	s_mov_b32 m0, s45
	ds_read_b128 v[178:181], v165 offset:32768
	ds_read_b128 v[182:185], v165 offset:33792
	ds_read_b128 v[186:189], v165 offset:34816
	ds_read_b128 v[190:193], v165 offset:35840
	ds_read_b128 v[208:211], v165 offset:36864
	ds_read_b128 v[212:215], v165 offset:37888
	ds_read_b128 v[216:219], v165 offset:38912
	ds_read_b128 v[220:223], v165 offset:39936
	global_load_lds_dwordx4 v132, s[30:31]
	s_mov_b32 m0, s46
	s_nop 0
	global_load_lds_dwordx4 v130, s[30:31]
	s_waitcnt vmcnt(8)
	s_waitcnt lgkmcnt(0)
	s_barrier
	s_setprio 1
	v_mfma_f32_16x16x32_bf16 v[124:127], v[138:141], v[178:181], v[124:127]
	v_mfma_f32_16x16x32_bf16 v[120:123], v[146:149], v[178:181], v[120:123]
	v_mfma_f32_16x16x32_bf16 v[108:111], v[138:141], v[186:189], v[108:111]
	v_mfma_f32_16x16x32_bf16 v[104:107], v[146:149], v[186:189], v[104:107]
	v_mfma_f32_16x16x32_bf16 v[96:99], v[138:141], v[208:211], v[96:99]
	v_mfma_f32_16x16x32_bf16 v[92:95], v[146:149], v[208:211], v[92:95]
	v_mfma_f32_16x16x32_bf16 v[84:87], v[138:141], v[216:219], v[84:87]
	v_mfma_f32_16x16x32_bf16 v[76:79], v[146:149], v[216:219], v[76:79]
	v_mfma_f32_16x16x32_bf16 v[124:127], v[142:145], v[182:185], v[124:127]
	v_mfma_f32_16x16x32_bf16 v[120:123], v[150:153], v[182:185], v[120:123]
	v_mfma_f32_16x16x32_bf16 v[108:111], v[142:145], v[190:193], v[108:111]
	v_mfma_f32_16x16x32_bf16 v[104:107], v[150:153], v[190:193], v[104:107]
	v_mfma_f32_16x16x32_bf16 v[96:99], v[142:145], v[212:215], v[96:99]
	v_mfma_f32_16x16x32_bf16 v[92:95], v[150:153], v[212:215], v[92:95]
	v_mfma_f32_16x16x32_bf16 v[84:87], v[142:145], v[220:223], v[84:87]
	v_mfma_f32_16x16x32_bf16 v[76:79], v[150:153], v[220:223], v[76:79]
	v_mfma_f32_16x16x32_bf16 v[116:119], v[154:157], v[178:181], v[116:119]
	v_mfma_f32_16x16x32_bf16 v[112:115], v[166:169], v[178:181], v[112:115]
	v_mfma_f32_16x16x32_bf16 v[100:103], v[154:157], v[186:189], v[100:103]
	v_mfma_f32_16x16x32_bf16 v[88:91], v[166:169], v[186:189], v[88:91]
	v_mfma_f32_16x16x32_bf16 v[80:83], v[154:157], v[208:211], v[80:83]
	v_mfma_f32_16x16x32_bf16 v[72:75], v[166:169], v[208:211], v[72:75]
	v_mfma_f32_16x16x32_bf16 v[68:71], v[154:157], v[216:219], v[68:71]
	v_mfma_f32_16x16x32_bf16 v[64:67], v[166:169], v[216:219], v[64:67]
	v_mfma_f32_16x16x32_bf16 v[116:119], v[158:161], v[182:185], v[116:119]
	v_mfma_f32_16x16x32_bf16 v[112:115], v[170:173], v[182:185], v[112:115]
	v_mfma_f32_16x16x32_bf16 v[100:103], v[158:161], v[190:193], v[100:103]
	v_mfma_f32_16x16x32_bf16 v[88:91], v[170:173], v[190:193], v[88:91]
	v_mfma_f32_16x16x32_bf16 v[80:83], v[158:161], v[212:215], v[80:83]
	v_mfma_f32_16x16x32_bf16 v[72:75], v[170:173], v[212:215], v[72:75]
	v_mfma_f32_16x16x32_bf16 v[68:71], v[158:161], v[220:223], v[68:71]
	v_mfma_f32_16x16x32_bf16 v[64:67], v[170:173], v[220:223], v[64:67]
	s_setprio 0
	s_barrier
; #define PG8_STAGE(bufoff, gbase, voff) do { _Pragma("unroll") for (int _i = 0; _i < 2; ++_i) \
;         __builtin_amdgcn_global_load_lds((const unsigned*)((const char*)(gbase) + (voff)[_i]), (LAS unsigned*)(lds + (bufoff) + ldsw + _i * 8192), 16, 0, 0); } while (0)
; #define PG8_LDA(dst, b, h) do { _Pragma("unroll") for (int m = 0; m < 4; ++m) _Pragma("unroll") for (int k = 0; k < 2; ++k) dst[m][k] = *(const LAS bf16x8*)(lds + PG8_SA(b, h) + aoff + m * 2048 + k * 1024); } while (0)
; #define PG8_WAIT_V(n) asm volatile("s_waitcnt vmcnt(" #n ")" ::: "memory")
; #define PG8_WAIT_L(n) asm volatile("s_waitcnt lgkmcnt(" #n ")" ::: "memory")
; #define PG8_BAR __builtin_amdgcn_s_barrier()
; #define PG8_SCHED __builtin_amdgcn_sched_barrier(0)
; template <bool F16, class Sched, class Epi>
; __device__ __forceinline__ void gemm_phase(LAS unsigned char* lds, const Gemm g, const Sched& S, const Epi& E, int wave_s) {
;     ...
;             PG8_LDA(At, 1, 1); PG8_STAGE(PG8_SB(1, 0), b3, voffB); PG8_STAGE(PG8_SB(1, 1), b3 + hstepB, voffB); PG8_STAGE(PG8_SA(1, 0), a3, voffA);
;             PG8_WAIT_V(8); PG8_WAIT_L(0); PG8_BAR; PG8_MMA(1, 0, At, B0); PG8_MMA(1, 1, At, B1); PG8_BAR; PG8_SCHED;
;         }
;         if (wr == 0) PG8_BAR;
	s_add_i32 s30, s61, s39
	v_lshl_add_u64 v[174:175], v[174:175], 0, s[54:55]
	s_mov_b32 m0, s30
	ds_read_b128 v[178:181], v165 offset:49152
	ds_read_b128 v[182:185], v165 offset:50176
	ds_read_b128 v[186:189], v165 offset:51200
	ds_read_b128 v[190:193], v165 offset:52224
	ds_read_b128 v[208:211], v165 offset:53248
	ds_read_b128 v[212:215], v165 offset:54272
	ds_read_b128 v[216:219], v165 offset:55296
	ds_read_b128 v[220:223], v165 offset:56320
	global_load_lds_dwordx4 v[174:175], off
	s_add_i32 m0, s30, 0x2000
	s_add_u32 s28, s28, 0x80080
	v_lshl_add_u64 v[174:175], v[194:195], 0, s[54:55]
	s_addc_u32 s29, s29, 0
	s_add_i32 s30, s62, s39
	global_load_lds_dwordx4 v[174:175], off
	v_lshl_add_u64 v[174:175], s[28:29], 0, v[176:177]
	s_mov_b32 m0, s30
	s_nop 0
	global_load_lds_dwordx4 v[174:175], off
	v_lshl_add_u64 v[174:175], s[28:29], 0, v[128:129]
	s_add_i32 m0, s30, 0x2000
	s_nop 0
	global_load_lds_dwordx4 v[174:175], off
	v_lshl_add_u64 v[174:175], v[198:199], 0, s[54:55]
	s_mov_b32 m0, s19
	s_nop 0
	global_load_lds_dwordx4 v[174:175], off
	v_lshl_add_u64 v[174:175], v[200:201], 0, s[54:55]
	s_mov_b32 m0, s47
	s_nop 0
	global_load_lds_dwordx4 v[174:175], off
	s_waitcnt vmcnt(8)
	s_waitcnt lgkmcnt(0)
	s_barrier
	s_setprio 1
	v_mfma_f32_16x16x32_bf16 v[60:63], v[138:141], v[178:181], v[60:63]
	v_mfma_f32_16x16x32_bf16 v[56:59], v[146:149], v[178:181], v[56:59]
	v_mfma_f32_16x16x32_bf16 v[52:55], v[138:141], v[186:189], v[52:55]
	v_mfma_f32_16x16x32_bf16 v[44:47], v[146:149], v[186:189], v[44:47]
	v_mfma_f32_16x16x32_bf16 v[36:39], v[138:141], v[208:211], v[36:39]
	v_mfma_f32_16x16x32_bf16 v[28:31], v[146:149], v[208:211], v[28:31]
	v_mfma_f32_16x16x32_bf16 v[20:23], v[138:141], v[216:219], v[20:23]
	v_mfma_f32_16x16x32_bf16 v[12:15], v[146:149], v[216:219], v[12:15]
	v_mfma_f32_16x16x32_bf16 v[60:63], v[142:145], v[182:185], v[60:63]
	v_mfma_f32_16x16x32_bf16 v[56:59], v[150:153], v[182:185], v[56:59]
	v_mfma_f32_16x16x32_bf16 v[52:55], v[142:145], v[190:193], v[52:55]
	v_mfma_f32_16x16x32_bf16 v[44:47], v[150:153], v[190:193], v[44:47]
	v_mfma_f32_16x16x32_bf16 v[36:39], v[142:145], v[212:215], v[36:39]
	v_mfma_f32_16x16x32_bf16 v[28:31], v[150:153], v[212:215], v[28:31]
	v_mfma_f32_16x16x32_bf16 v[20:23], v[142:145], v[220:223], v[20:23]
	v_mfma_f32_16x16x32_bf16 v[12:15], v[150:153], v[220:223], v[12:15]
	v_mfma_f32_16x16x32_bf16 v[48:51], v[154:157], v[178:181], v[48:51]
	v_mfma_f32_16x16x32_bf16 v[40:43], v[166:169], v[178:181], v[40:43]
	v_mfma_f32_16x16x32_bf16 v[32:35], v[154:157], v[186:189], v[32:35]
	v_mfma_f32_16x16x32_bf16 v[24:27], v[166:169], v[186:189], v[24:27]
	v_mfma_f32_16x16x32_bf16 v[16:19], v[154:157], v[208:211], v[16:19]
	v_mfma_f32_16x16x32_bf16 v[8:11], v[166:169], v[208:211], v[8:11]
	v_mfma_f32_16x16x32_bf16 v[4:7], v[154:157], v[216:219], v[4:7]
	v_mfma_f32_16x16x32_bf16 v[0:3], v[166:169], v[216:219], v[0:3]
	v_mfma_f32_16x16x32_bf16 v[48:51], v[158:161], v[182:185], v[48:51]
	v_mfma_f32_16x16x32_bf16 v[40:43], v[170:173], v[182:185], v[40:43]
	v_mfma_f32_16x16x32_bf16 v[32:35], v[158:161], v[190:193], v[32:35]
	v_mfma_f32_16x16x32_bf16 v[24:27], v[170:173], v[190:193], v[24:27]
	v_mfma_f32_16x16x32_bf16 v[16:19], v[158:161], v[212:215], v[16:19]
	v_mfma_f32_16x16x32_bf16 v[8:11], v[170:173], v[212:215], v[8:11]
	v_mfma_f32_16x16x32_bf16 v[4:7], v[158:161], v[220:223], v[4:7]
	v_mfma_f32_16x16x32_bf16 v[0:3], v[170:173], v[220:223], v[0:3]
	s_setprio 0
	s_barrier
	s_add_i32 s60, s60, 2
	s_add_u32 s26, s26, 0x100
	s_addc_u32 s27, s27, 0
	s_add_u32 s58, s58, 0x100
	s_addc_u32 s59, s59, 0
	s_cmp_gt_u32 s60, 29
	s_cbranch_scc0 .LBB0_598
	s_and_b64 vcc, exec, s[14:15]
	s_cbranch_vccz .LBB0_601
	s_barrier

; #define PG8_STAGE(bufoff, gbase, voff) do { _Pragma("unroll") for (int _i = 0; _i < 2; ++_i) \
;         __builtin_amdgcn_global_load_lds((const unsigned*)((const char*)(gbase) + (voff)[_i]), (LAS unsigned*)(lds + (bufoff) + ldsw + _i * 8192), 16, 0, 0); } while (0)
; #define PG8_LDA(dst, b, h) do { _Pragma("unroll") for (int m = 0; m < 4; ++m) _Pragma("unroll") for (int k = 0; k < 2; ++k) dst[m][k] = *(const LAS bf16x8*)(lds + PG8_SA(b, h) + aoff + m * 2048 + k * 1024); } while (0)
; #define PG8_LDB(dst, b, h) do { _Pragma("unroll") for (int n = 0; n < 2; ++n) _Pragma("unroll") for (int k = 0; k < 2; ++k) dst[n][k] = *(const LAS bf16x8*)(lds + PG8_SB(b, h) + boff + n * 2048 + k * 1024); } while (0)
; #define PG8_WAIT_V(n) asm volatile("s_waitcnt vmcnt(" #n ")" ::: "memory")
; #define PG8_WAIT_L(n) asm volatile("s_waitcnt lgkmcnt(" #n ")" ::: "memory")
; #define PG8_BAR __builtin_amdgcn_s_barrier()
; #define PG8_SCHED __builtin_amdgcn_sched_barrier(0)
; template <bool F16, class Sched, class Epi>
; __device__ __forceinline__ void gemm_phase(LAS unsigned char* lds, const Gemm g, const Sched& S, const Epi& E, int wave_s) {
;     ...
;         const char* nA = has_next ? (const char*)g.A + PG8_AOFF(nxt) : cA + (size_t)(nt - 2) * kstep; const char* nB = has_next ? (const char*)g.Bt + (size_t)nxt.pn * tstepB : cB + (size_t)(nt - 2) * kstep;
;         for (int t = 0; t < nt; t += 2) {
;             const bool last = (t == nt - 2);
;             const char* a1 = cA + (size_t)(t + 1) * kstep;
;             const char* a2 = last ? nA : cA + (size_t)(t + 2) * kstep; const char* b2 = last ? nB : cB + (size_t)(t + 2) * kstep;
;             const char* a3 = a2 + kstep; const char* b3 = b2 + kstep;
;             PG8_LDB(B0, 0, 0); PG8_LDB(B1, 0, 1); PG8_SCHED; PG8_LDA(At, 0, 0); PG8_STAGE(PG8_SA(1, 1), a1 + hstepA, voffA);
;             PG8_WAIT_V(8); PG8_WAIT_L(0); PG8_BAR; PG8_MMA(0, 0, At, B0); PG8_MMA(0, 1, At, B1); PG8_BAR; PG8_SCHED;
;             PG8_LDA(At, 0, 1); PG8_STAGE(PG8_SB(0, 0), b2, voffB); PG8_STAGE(PG8_SB(0, 1), b2 + hstepB, voffB); PG8_STAGE(PG8_SA(0, 0), a2, voffA);
.LBB0_681:
	s_add_i32 s61, 0, 0x10000
	v_add_u32_e32 v146, s61, v149
	s_add_i32 s64, 0, 0x14000
	ds_read_b128 v[138:141], v146
	ds_read_b128 v[142:145], v146 offset:1024
	ds_read_b128 v[154:157], v146 offset:2048
	ds_read_b128 v[158:161], v146 offset:3072
	v_add_u32_e32 v146, s64, v149
	ds_read_b128 v[162:165], v146
	ds_read_b128 v[166:169], v146 offset:1024
	ds_read_b128 v[170:173], v146 offset:2048
	ds_read_b128 v[178:181], v146 offset:3072
	s_add_i32 m0, s39, 0xc000
	ds_read_b128 v[182:185], v152
	ds_read_b128 v[186:189], v152 offset:1024
	ds_read_b128 v[190:193], v152 offset:2048
	ds_read_b128 v[208:211], v152 offset:3072
	ds_read_b128 v[212:215], v152 offset:4096
	ds_read_b128 v[216:219], v152 offset:5120
	ds_read_b128 v[220:223], v152 offset:6144
	ds_read_b128 v[224:227], v152 offset:7168
	global_load_lds_dwordx4 v134, s[24:25]
	s_add_i32 m0, s39, 0xe000
	s_nop 0
	global_load_lds_dwordx4 v136, s[24:25]
	s_waitcnt vmcnt(8)
	s_waitcnt lgkmcnt(0)
	s_barrier
	s_setprio 1
	v_mfma_f32_16x16x32_bf16 v[124:127], v[138:141], v[182:185], v[124:127]
	v_mfma_f32_16x16x32_bf16 v[116:119], v[154:157], v[182:185], v[116:119]
	v_mfma_f32_16x16x32_bf16 v[108:111], v[138:141], v[190:193], v[108:111]
	v_mfma_f32_16x16x32_bf16 v[100:103], v[154:157], v[190:193], v[100:103]
	v_mfma_f32_16x16x32_bf16 v[92:95], v[138:141], v[212:215], v[92:95]
	v_mfma_f32_16x16x32_bf16 v[84:87], v[154:157], v[212:215], v[84:87]
	v_mfma_f32_16x16x32_bf16 v[76:79], v[138:141], v[220:223], v[76:79]
	v_mfma_f32_16x16x32_bf16 v[68:71], v[154:157], v[220:223], v[68:71]
	v_mfma_f32_16x16x32_bf16 v[124:127], v[142:145], v[186:189], v[124:127]
	v_mfma_f32_16x16x32_bf16 v[116:119], v[158:161], v[186:189], v[116:119]
	v_mfma_f32_16x16x32_bf16 v[108:111], v[142:145], v[208:211], v[108:111]
	v_mfma_f32_16x16x32_bf16 v[100:103], v[158:161], v[208:211], v[100:103]
	v_mfma_f32_16x16x32_bf16 v[92:95], v[142:145], v[216:219], v[92:95]
	v_mfma_f32_16x16x32_bf16 v[84:87], v[158:161], v[216:219], v[84:87]
	v_mfma_f32_16x16x32_bf16 v[76:79], v[142:145], v[224:227], v[76:79]
	v_mfma_f32_16x16x32_bf16 v[68:71], v[158:161], v[224:227], v[68:71]
	v_mfma_f32_16x16x32_bf16 v[120:123], v[162:165], v[182:185], v[120:123]
	v_mfma_f32_16x16x32_bf16 v[112:115], v[170:173], v[182:185], v[112:115]
	v_mfma_f32_16x16x32_bf16 v[104:107], v[162:165], v[190:193], v[104:107]
	v_mfma_f32_16x16x32_bf16 v[96:99], v[170:173], v[190:193], v[96:99]
	v_mfma_f32_16x16x32_bf16 v[88:91], v[162:165], v[212:215], v[88:91]
	v_mfma_f32_16x16x32_bf16 v[80:83], v[170:173], v[212:215], v[80:83]
	v_mfma_f32_16x16x32_bf16 v[72:75], v[162:165], v[220:223], v[72:75]
	v_mfma_f32_16x16x32_bf16 v[64:67], v[170:173], v[220:223], v[64:67]
	v_mfma_f32_16x16x32_bf16 v[120:123], v[166:169], v[186:189], v[120:123]
	v_mfma_f32_16x16x32_bf16 v[112:115], v[178:181], v[186:189], v[112:115]
	v_mfma_f32_16x16x32_bf16 v[104:107], v[166:169], v[208:211], v[104:107]
	v_mfma_f32_16x16x32_bf16 v[96:99], v[178:181], v[208:211], v[96:99]
	v_mfma_f32_16x16x32_bf16 v[88:91], v[166:169], v[216:219], v[88:91]
	v_mfma_f32_16x16x32_bf16 v[80:83], v[178:181], v[216:219], v[80:83]
	v_mfma_f32_16x16x32_bf16 v[72:75], v[166:169], v[224:227], v[72:75]
	v_mfma_f32_16x16x32_bf16 v[64:67], v[178:181], v[224:227], v[64:67]
	s_setprio 0
	s_barrier
	s_add_u32 s26, s24, 0xfff80080
	s_addc_u32 s27, s25, -1
	s_cmp_eq_u32 s60, 28
	s_cselect_b32 s29, s49, s27
	s_cselect_b32 s28, s50, s26
	s_cselect_b32 s27, s52, s59
	s_cselect_b32 s26, s53, s58
	s_add_i32 s61, s61, s38
	v_lshl_add_u64 v[146:147], s[26:27], 0, v[176:177]
	s_mov_b32 m0, s61
	ds_read_b128 v[182:185], v152 offset:16384
	ds_read_b128 v[186:189], v152 offset:17408
	ds_read_b128 v[190:193], v152 offset:18432
	ds_read_b128 v[208:211], v152 offset:19456
	ds_read_b128 v[212:215], v152 offset:20480
	ds_read_b128 v[216:219], v152 offset:21504
	ds_read_b128 v[220:223], v152 offset:22528
	ds_read_b128 v[224:227], v152 offset:23552
	global_load_lds_dwordx4 v[146:147], off
	s_add_i32 m0, s61, 0x2000
	s_add_u32 s62, s26, 0x80000
	v_lshl_add_u64 v[174:175], s[26:27], 0, v[128:129]
	s_addc_u32 s63, s27, 0
	s_add_i32 s61, s64, s38
	global_load_lds_dwordx4 v[174:175], off
	v_lshl_add_u64 v[194:195], s[62:63], 0, v[176:177]
	s_mov_b32 m0, s61
	v_lshl_add_u64 v[198:199], s[28:29], 0, v[130:131]
	global_load_lds_dwordx4 v[194:195], off
	v_lshl_add_u64 v[194:195], s[62:63], 0, v[128:129]
	s_add_i32 m0, s61, 0x2000
	s_nop 0
	global_load_lds_dwordx4 v[194:195], off
	v_lshl_add_u64 v[194:195], s[28:29], 0, v[132:133]
	s_mov_b32 m0, s39
	s_nop 0
	global_load_lds_dwordx4 v[194:195], off
	s_mov_b32 m0, s43
	s_nop 0
	global_load_lds_dwordx4 v[198:199], off
	s_add_u32 s28, s28, 0x80000
	s_addc_u32 s29, s29, 0
	s_waitcnt vmcnt(8)
	s_waitcnt lgkmcnt(0)
	s_barrier
; #define PG8_STAGE(bufoff, gbase, voff) do { _Pragma("unroll") for (int _i = 0; _i < 2; ++_i) \
;         __builtin_amdgcn_global_load_lds((const unsigned*)((const char*)(gbase) + (voff)[_i]), (LAS unsigned*)(lds + (bufoff) + ldsw + _i * 8192), 16, 0, 0); } while (0)
; #define PG8_LDA(dst, b, h) do { _Pragma("unroll") for (int m = 0; m < 4; ++m) _Pragma("unroll") for (int k = 0; k < 2; ++k) dst[m][k] = *(const LAS bf16x8*)(lds + PG8_SA(b, h) + aoff + m * 2048 + k * 1024); } while (0)
; #define PG8_LDB(dst, b, h) do { _Pragma("unroll") for (int n = 0; n < 2; ++n) _Pragma("unroll") for (int k = 0; k < 2; ++k) dst[n][k] = *(const LAS bf16x8*)(lds + PG8_SB(b, h) + boff + n * 2048 + k * 1024); } while (0)
; #define PG8_WAIT_V(n) asm volatile("s_waitcnt vmcnt(" #n ")" ::: "memory")
; #define PG8_WAIT_L(n) asm volatile("s_waitcnt lgkmcnt(" #n ")" ::: "memory")
; #define PG8_BAR __builtin_amdgcn_s_barrier()
; #define PG8_SCHED __builtin_amdgcn_sched_barrier(0)
; template <bool F16, class Sched, class Epi>
; __device__ __forceinline__ void gemm_phase(LAS unsigned char* lds, const Gemm g, const Sched& S, const Epi& E, int wave_s) {
;     ...
;             PG8_WAIT_V(8); PG8_WAIT_L(0); PG8_BAR; PG8_MMA(1, 0, At, B0); PG8_MMA(1, 1, At, B1); PG8_BAR; PG8_SCHED;
;             PG8_LDB(B0, 1, 0); PG8_LDB(B1, 1, 1); PG8_SCHED; PG8_LDA(At, 1, 0); PG8_STAGE(PG8_SA(0, 1), a2 + hstepA, voffA);
;             PG8_WAIT_V(8); PG8_WAIT_L(0); PG8_BAR; PG8_MMA(0, 0, At, B0); PG8_MMA(0, 1, At, B1); PG8_BAR; PG8_SCHED;
	s_setprio 1
	v_mfma_f32_16x16x32_bf16 v[60:63], v[138:141], v[182:185], v[60:63]
	v_mfma_f32_16x16x32_bf16 v[52:55], v[154:157], v[182:185], v[52:55]
	v_mfma_f32_16x16x32_bf16 v[44:47], v[138:141], v[190:193], v[44:47]
	v_mfma_f32_16x16x32_bf16 v[36:39], v[154:157], v[190:193], v[36:39]
	v_mfma_f32_16x16x32_bf16 v[28:31], v[138:141], v[212:215], v[28:31]
	v_mfma_f32_16x16x32_bf16 v[20:23], v[154:157], v[212:215], v[20:23]
	v_mfma_f32_16x16x32_bf16 v[12:15], v[138:141], v[220:223], v[12:15]
	v_mfma_f32_16x16x32_bf16 v[4:7], v[154:157], v[220:223], v[4:7]
	v_mfma_f32_16x16x32_bf16 v[60:63], v[142:145], v[186:189], v[60:63]
	v_mfma_f32_16x16x32_bf16 v[52:55], v[158:161], v[186:189], v[52:55]
	v_mfma_f32_16x16x32_bf16 v[44:47], v[142:145], v[208:211], v[44:47]
	v_mfma_f32_16x16x32_bf16 v[36:39], v[158:161], v[208:211], v[36:39]
	v_mfma_f32_16x16x32_bf16 v[28:31], v[142:145], v[216:219], v[28:31]
	v_mfma_f32_16x16x32_bf16 v[20:23], v[158:161], v[216:219], v[20:23]
	v_mfma_f32_16x16x32_bf16 v[12:15], v[142:145], v[224:227], v[12:15]
	v_mfma_f32_16x16x32_bf16 v[4:7], v[158:161], v[224:227], v[4:7]
	v_mfma_f32_16x16x32_bf16 v[56:59], v[162:165], v[182:185], v[56:59]
	v_mfma_f32_16x16x32_bf16 v[48:51], v[170:173], v[182:185], v[48:51]
	v_mfma_f32_16x16x32_bf16 v[40:43], v[162:165], v[190:193], v[40:43]
	v_mfma_f32_16x16x32_bf16 v[32:35], v[170:173], v[190:193], v[32:35]
	v_mfma_f32_16x16x32_bf16 v[24:27], v[162:165], v[212:215], v[24:27]
	v_mfma_f32_16x16x32_bf16 v[16:19], v[170:173], v[212:215], v[16:19]
	v_mfma_f32_16x16x32_bf16 v[8:11], v[162:165], v[220:223], v[8:11]
	v_mfma_f32_16x16x32_bf16 v[0:3], v[170:173], v[220:223], v[0:3]
	v_mfma_f32_16x16x32_bf16 v[56:59], v[166:169], v[186:189], v[56:59]
	v_mfma_f32_16x16x32_bf16 v[48:51], v[178:181], v[186:189], v[48:51]
	v_mfma_f32_16x16x32_bf16 v[40:43], v[166:169], v[208:211], v[40:43]
	v_mfma_f32_16x16x32_bf16 v[32:35], v[178:181], v[208:211], v[32:35]
	v_mfma_f32_16x16x32_bf16 v[24:27], v[166:169], v[216:219], v[24:27]
	v_mfma_f32_16x16x32_bf16 v[16:19], v[178:181], v[216:219], v[16:19]
	v_mfma_f32_16x16x32_bf16 v[8:11], v[166:169], v[224:227], v[8:11]
	v_mfma_f32_16x16x32_bf16 v[0:3], v[178:181], v[224:227], v[0:3]
	s_setprio 0
	s_barrier
	s_add_i32 s61, 0, 0x18000
	v_add_u32_e32 v153, s61, v149
	s_add_i32 s62, 0, 0x1c000
	ds_read_b128 v[138:141], v153
	ds_read_b128 v[142:145], v153 offset:1024
	ds_read_b128 v[154:157], v153 offset:2048
	ds_read_b128 v[158:161], v153 offset:3072
	v_add_u32_e32 v153, s62, v149
	ds_read_b128 v[162:165], v153
	ds_read_b128 v[166:169], v153 offset:1024
	ds_read_b128 v[170:173], v153 offset:2048
	ds_read_b128 v[178:181], v153 offset:3072
	s_mov_b32 m0, s44
	ds_read_b128 v[182:185], v152 offset:32768
	ds_read_b128 v[186:189], v152 offset:33792
	ds_read_b128 v[190:193], v152 offset:34816
	ds_read_b128 v[208:211], v152 offset:35840
	ds_read_b128 v[212:215], v152 offset:36864
	ds_read_b128 v[216:219], v152 offset:37888
	ds_read_b128 v[220:223], v152 offset:38912
	ds_read_b128 v[224:227], v152 offset:39936
	global_load_lds_dwordx4 v132, s[28:29]
	s_mov_b32 m0, s45
	s_nop 0
	global_load_lds_dwordx4 v130, s[28:29]
	s_waitcnt vmcnt(8)
	s_waitcnt lgkmcnt(0)
	s_barrier
	s_setprio 1
	v_mfma_f32_16x16x32_bf16 v[124:127], v[138:141], v[182:185], v[124:127]
	v_mfma_f32_16x16x32_bf16 v[116:119], v[154:157], v[182:185], v[116:119]
	v_mfma_f32_16x16x32_bf16 v[108:111], v[138:141], v[190:193], v[108:111]
	v_mfma_f32_16x16x32_bf16 v[100:103], v[154:157], v[190:193], v[100:103]
	v_mfma_f32_16x16x32_bf16 v[92:95], v[138:141], v[212:215], v[92:95]
	v_mfma_f32_16x16x32_bf16 v[84:87], v[154:157], v[212:215], v[84:87]
	v_mfma_f32_16x16x32_bf16 v[76:79], v[138:141], v[220:223], v[76:79]
	v_mfma_f32_16x16x32_bf16 v[68:71], v[154:157], v[220:223], v[68:71]
	v_mfma_f32_16x16x32_bf16 v[124:127], v[142:145], v[186:189], v[124:127]
	v_mfma_f32_16x16x32_bf16 v[116:119], v[158:161], v[186:189], v[116:119]
	v_mfma_f32_16x16x32_bf16 v[108:111], v[142:145], v[208:211], v[108:111]
	v_mfma_f32_16x16x32_bf16 v[100:103], v[158:161], v[208:211], v[100:103]
	v_mfma_f32_16x16x32_bf16 v[92:95], v[142:145], v[216:219], v[92:95]
	v_mfma_f32_16x16x32_bf16 v[84:87], v[158:161], v[216:219], v[84:87]
	v_mfma_f32_16x16x32_bf16 v[76:79], v[142:145], v[224:227], v[76:79]
	v_mfma_f32_16x16x32_bf16 v[68:71], v[158:161], v[224:227], v[68:71]
	v_mfma_f32_16x16x32_bf16 v[120:123], v[162:165], v[182:185], v[120:123]
	v_mfma_f32_16x16x32_bf16 v[112:115], v[170:173], v[182:185], v[112:115]
	v_mfma_f32_16x16x32_bf16 v[104:107], v[162:165], v[190:193], v[104:107]
	v_mfma_f32_16x16x32_bf16 v[96:99], v[170:173], v[190:193], v[96:99]
	v_mfma_f32_16x16x32_bf16 v[88:91], v[162:165], v[212:215], v[88:91]
	v_mfma_f32_16x16x32_bf16 v[80:83], v[170:173], v[212:215], v[80:83]
	v_mfma_f32_16x16x32_bf16 v[72:75], v[162:165], v[220:223], v[72:75]
	v_mfma_f32_16x16x32_bf16 v[64:67], v[170:173], v[220:223], v[64:67]
	v_mfma_f32_16x16x32_bf16 v[120:123], v[166:169], v[186:189], v[120:123]
	v_mfma_f32_16x16x32_bf16 v[112:115], v[178:181], v[186:189], v[112:115]
	v_mfma_f32_16x16x32_bf16 v[104:107], v[166:169], v[208:211], v[104:107]
	v_mfma_f32_16x16x32_bf16 v[96:99], v[178:181], v[208:211], v[96:99]
	v_mfma_f32_16x16x32_bf16 v[88:91], v[166:169], v[216:219], v[88:91]
	v_mfma_f32_16x16x32_bf16 v[80:83], v[178:181], v[216:219], v[80:83]
	v_mfma_f32_16x16x32_bf16 v[72:75], v[166:169], v[224:227], v[72:75]
	v_mfma_f32_16x16x32_bf16 v[64:67], v[178:181], v[224:227], v[64:67]
	s_setprio 0
	s_barrier
; #define PG8_STAGE(bufoff, gbase, voff) do { _Pragma("unroll") for (int _i = 0; _i < 2; ++_i) \
;         __builtin_amdgcn_global_load_lds((const unsigned*)((const char*)(gbase) + (voff)[_i]), (LAS unsigned*)(lds + (bufoff) + ldsw + _i * 8192), 16, 0, 0); } while (0)
; #define PG8_LDA(dst, b, h) do { _Pragma("unroll") for (int m = 0; m < 4; ++m) _Pragma("unroll") for (int k = 0; k < 2; ++k) dst[m][k] = *(const LAS bf16x8*)(lds + PG8_SA(b, h) + aoff + m * 2048 + k * 1024); } while (0)
; #define PG8_WAIT_V(n) asm volatile("s_waitcnt vmcnt(" #n ")" ::: "memory")
; #define PG8_WAIT_L(n) asm volatile("s_waitcnt lgkmcnt(" #n ")" ::: "memory")
; #define PG8_BAR __builtin_amdgcn_s_barrier()
; #define PG8_SCHED __builtin_amdgcn_sched_barrier(0)
; template <bool F16, class Sched, class Epi>
; __device__ __forceinline__ void gemm_phase(LAS unsigned char* lds, const Gemm g, const Sched& S, const Epi& E, int wave_s) {
;     ...
;             PG8_LDA(At, 1, 1); PG8_STAGE(PG8_SB(1, 0), b3, voffB); PG8_STAGE(PG8_SB(1, 1), b3 + hstepB, voffB); PG8_STAGE(PG8_SA(1, 0), a3, voffA);
;             PG8_WAIT_V(8); PG8_WAIT_L(0); PG8_BAR; PG8_MMA(1, 0, At, B0); PG8_MMA(1, 1, At, B1); PG8_BAR; PG8_SCHED;
;         }
;         if (wr == 0) PG8_BAR;
	s_add_i32 s28, s61, s38
	v_lshl_add_u64 v[146:147], v[146:147], 0, s[54:55]
	s_mov_b32 m0, s28
	ds_read_b128 v[182:185], v152 offset:49152
	ds_read_b128 v[186:189], v152 offset:50176
	ds_read_b128 v[190:193], v152 offset:51200
	ds_read_b128 v[208:211], v152 offset:52224
	ds_read_b128 v[212:215], v152 offset:53248
	ds_read_b128 v[216:219], v152 offset:54272
	ds_read_b128 v[220:223], v152 offset:55296
	ds_read_b128 v[224:227], v152 offset:56320
	global_load_lds_dwordx4 v[146:147], off
	s_add_i32 m0, s28, 0x2000
	s_add_u32 s26, s26, 0x80080
	v_lshl_add_u64 v[146:147], v[174:175], 0, s[54:55]
	s_addc_u32 s27, s27, 0
	s_add_i32 s28, s62, s38
	global_load_lds_dwordx4 v[146:147], off
	v_lshl_add_u64 v[146:147], s[26:27], 0, v[176:177]
	s_mov_b32 m0, s28
	s_nop 0
	global_load_lds_dwordx4 v[146:147], off
	v_lshl_add_u64 v[146:147], s[26:27], 0, v[128:129]
	s_add_i32 m0, s28, 0x2000
	s_nop 0
	global_load_lds_dwordx4 v[146:147], off
	v_lshl_add_u64 v[146:147], v[194:195], 0, s[54:55]
	s_mov_b32 m0, s46
	s_nop 0
	global_load_lds_dwordx4 v[146:147], off
	v_lshl_add_u64 v[146:147], v[198:199], 0, s[54:55]
	s_mov_b32 m0, s47
	s_nop 0
	global_load_lds_dwordx4 v[146:147], off
	s_waitcnt vmcnt(8)
	s_waitcnt lgkmcnt(0)
	s_barrier
	s_setprio 1
	v_mfma_f32_16x16x32_bf16 v[60:63], v[138:141], v[182:185], v[60:63]
	v_mfma_f32_16x16x32_bf16 v[52:55], v[154:157], v[182:185], v[52:55]
	v_mfma_f32_16x16x32_bf16 v[44:47], v[138:141], v[190:193], v[44:47]
	v_mfma_f32_16x16x32_bf16 v[36:39], v[154:157], v[190:193], v[36:39]
	v_mfma_f32_16x16x32_bf16 v[28:31], v[138:141], v[212:215], v[28:31]
	v_mfma_f32_16x16x32_bf16 v[20:23], v[154:157], v[212:215], v[20:23]
	v_mfma_f32_16x16x32_bf16 v[12:15], v[138:141], v[220:223], v[12:15]
	v_mfma_f32_16x16x32_bf16 v[4:7], v[154:157], v[220:223], v[4:7]
	v_mfma_f32_16x16x32_bf16 v[60:63], v[142:145], v[186:189], v[60:63]
	v_mfma_f32_16x16x32_bf16 v[52:55], v[158:161], v[186:189], v[52:55]
	v_mfma_f32_16x16x32_bf16 v[44:47], v[142:145], v[208:211], v[44:47]
	v_mfma_f32_16x16x32_bf16 v[36:39], v[158:161], v[208:211], v[36:39]
	v_mfma_f32_16x16x32_bf16 v[28:31], v[142:145], v[216:219], v[28:31]
	v_mfma_f32_16x16x32_bf16 v[20:23], v[158:161], v[216:219], v[20:23]
	v_mfma_f32_16x16x32_bf16 v[12:15], v[142:145], v[224:227], v[12:15]
	v_mfma_f32_16x16x32_bf16 v[4:7], v[158:161], v[224:227], v[4:7]
	v_mfma_f32_16x16x32_bf16 v[56:59], v[162:165], v[182:185], v[56:59]
	v_mfma_f32_16x16x32_bf16 v[48:51], v[170:173], v[182:185], v[48:51]
	v_mfma_f32_16x16x32_bf16 v[40:43], v[162:165], v[190:193], v[40:43]
	v_mfma_f32_16x16x32_bf16 v[32:35], v[170:173], v[190:193], v[32:35]
	v_mfma_f32_16x16x32_bf16 v[24:27], v[162:165], v[212:215], v[24:27]
	v_mfma_f32_16x16x32_bf16 v[16:19], v[170:173], v[212:215], v[16:19]
	v_mfma_f32_16x16x32_bf16 v[8:11], v[162:165], v[220:223], v[8:11]
	v_mfma_f32_16x16x32_bf16 v[0:3], v[170:173], v[220:223], v[0:3]
	v_mfma_f32_16x16x32_bf16 v[56:59], v[166:169], v[186:189], v[56:59]
	v_mfma_f32_16x16x32_bf16 v[48:51], v[178:181], v[186:189], v[48:51]
	v_mfma_f32_16x16x32_bf16 v[40:43], v[166:169], v[208:211], v[40:43]
	v_mfma_f32_16x16x32_bf16 v[32:35], v[178:181], v[208:211], v[32:35]
	v_mfma_f32_16x16x32_bf16 v[24:27], v[166:169], v[216:219], v[24:27]
	v_mfma_f32_16x16x32_bf16 v[16:19], v[178:181], v[216:219], v[16:19]
	v_mfma_f32_16x16x32_bf16 v[8:11], v[166:169], v[224:227], v[8:11]
	v_mfma_f32_16x16x32_bf16 v[0:3], v[178:181], v[224:227], v[0:3]
	s_setprio 0
	s_barrier
	s_add_i32 s60, s60, 2
	s_add_u32 s24, s24, 0x100
	s_addc_u32 s25, s25, 0
	s_add_u32 s58, s58, 0x100
	s_addc_u32 s59, s59, 0
	s_cmp_gt_u32 s60, 29
	s_cbranch_scc0 .LBB0_681
	s_and_b64 vcc, exec, s[12:13]
	s_cbranch_vccz .LBB0_684
	s_barrier

; #define PG8_STAGE(bufoff, gbase, voff) do { _Pragma("unroll") for (int _i = 0; _i < 2; ++_i) \
;         __builtin_amdgcn_global_load_lds((const unsigned*)((const char*)(gbase) + (voff)[_i]), (LAS unsigned*)(lds + (bufoff) + ldsw + _i * 8192), 16, 0, 0); } while (0)
; #define PG8_LDA(dst, b, h) do { _Pragma("unroll") for (int m = 0; m < 4; ++m) _Pragma("unroll") for (int k = 0; k < 2; ++k) dst[m][k] = *(const LAS bf16x8*)(lds + PG8_SA(b, h) + aoff + m * 2048 + k * 1024); } while (0)
; #define PG8_LDB(dst, b, h) do { _Pragma("unroll") for (int n = 0; n < 2; ++n) _Pragma("unroll") for (int k = 0; k < 2; ++k) dst[n][k] = *(const LAS bf16x8*)(lds + PG8_SB(b, h) + boff + n * 2048 + k * 1024); } while (0)
; #define PG8_WAIT_V(n) asm volatile("s_waitcnt vmcnt(" #n ")" ::: "memory")
; #define PG8_WAIT_L(n) asm volatile("s_waitcnt lgkmcnt(" #n ")" ::: "memory")
; #define PG8_BAR __builtin_amdgcn_s_barrier()
; #define PG8_SCHED __builtin_amdgcn_sched_barrier(0)
; template <bool F16, class Sched, class Epi>
; __device__ __forceinline__ void gemm_phase(LAS unsigned char* lds, const Gemm g, const Sched& S, const Epi& E, int wave_s) {
;     ...
;         const char* nA = has_next ? (const char*)g.A + PG8_AOFF(nxt) : cA + (size_t)(nt - 2) * kstep; const char* nB = has_next ? (const char*)g.Bt + (size_t)nxt.pn * tstepB : cB + (size_t)(nt - 2) * kstep;
;         for (int t = 0; t < nt; t += 2) {
;             const bool last = (t == nt - 2);
;             const char* a1 = cA + (size_t)(t + 1) * kstep;
;             const char* a2 = last ? nA : cA + (size_t)(t + 2) * kstep; const char* b2 = last ? nB : cB + (size_t)(t + 2) * kstep;
;             const char* a3 = a2 + kstep; const char* b3 = b2 + kstep;
;             PG8_LDB(B0, 0, 0); PG8_LDB(B1, 0, 1); PG8_SCHED; PG8_LDA(At, 0, 0); PG8_STAGE(PG8_SA(1, 1), a1 + hstepA, voffA);
;             PG8_WAIT_V(8); PG8_WAIT_L(0); PG8_BAR; PG8_MMA(0, 0, At, B0); PG8_MMA(0, 1, At, B1); PG8_BAR; PG8_SCHED;
;             PG8_LDA(At, 0, 1); PG8_STAGE(PG8_SB(0, 0), b2, voffB); PG8_STAGE(PG8_SB(0, 1), b2 + hstepB, voffB); PG8_STAGE(PG8_SA(0, 0), a2, voffA);
.LBB0_795:
	s_add_i32 s64, 0, 0x10000
	s_add_i32 s65, 0, 0x14000
	v_add_u32_e32 v150, s64, v163
	v_add_u32_e32 v170, s65, v163
	ds_read_b128 v[138:141], v150
	ds_read_b128 v[142:145], v150 offset:1024
	ds_read_b128 v[146:149], v150 offset:2048
	ds_read_b128 v[150:153], v150 offset:3072
	ds_read_b128 v[154:157], v170
	ds_read_b128 v[158:161], v170 offset:1024
	ds_read_b128 v[166:169], v170 offset:2048
	ds_read_b128 v[170:173], v170 offset:3072
	v_lshl_add_u64 v[174:175], s[28:29], 0, v[134:135]
	s_add_i32 m0, s46, 0xc000
	ds_read_b128 v[178:181], v165
	ds_read_b128 v[182:185], v165 offset:1024
	ds_read_b128 v[186:189], v165 offset:2048
	ds_read_b128 v[190:193], v165 offset:3072
	ds_read_b128 v[198:201], v165 offset:4096
	ds_read_b128 v[208:211], v165 offset:5120
	ds_read_b128 v[212:215], v165 offset:6144
	ds_read_b128 v[216:219], v165 offset:7168
	global_load_lds_dwordx4 v[174:175], off
	v_lshl_add_u64 v[174:175], s[28:29], 0, v[136:137]
	s_add_i32 m0, s46, 0xe000
	s_nop 0
	global_load_lds_dwordx4 v[174:175], off
	s_waitcnt vmcnt(8)
	s_waitcnt lgkmcnt(0)
	s_barrier
	s_setprio 1
	v_mfma_f32_16x16x32_bf16 v[124:127], v[138:141], v[178:181], v[124:127]
	v_mfma_f32_16x16x32_bf16 v[120:123], v[146:149], v[178:181], v[120:123]
	v_mfma_f32_16x16x32_bf16 v[108:111], v[138:141], v[186:189], v[108:111]
	v_mfma_f32_16x16x32_bf16 v[104:107], v[146:149], v[186:189], v[104:107]
	v_mfma_f32_16x16x32_bf16 v[96:99], v[138:141], v[198:201], v[96:99]
	v_mfma_f32_16x16x32_bf16 v[92:95], v[146:149], v[198:201], v[92:95]
	v_mfma_f32_16x16x32_bf16 v[84:87], v[138:141], v[212:215], v[84:87]
	v_mfma_f32_16x16x32_bf16 v[76:79], v[146:149], v[212:215], v[76:79]
	v_mfma_f32_16x16x32_bf16 v[124:127], v[142:145], v[182:185], v[124:127]
	v_mfma_f32_16x16x32_bf16 v[120:123], v[150:153], v[182:185], v[120:123]
	v_mfma_f32_16x16x32_bf16 v[108:111], v[142:145], v[190:193], v[108:111]
	v_mfma_f32_16x16x32_bf16 v[104:107], v[150:153], v[190:193], v[104:107]
	v_mfma_f32_16x16x32_bf16 v[96:99], v[142:145], v[208:211], v[96:99]
	v_mfma_f32_16x16x32_bf16 v[92:95], v[150:153], v[208:211], v[92:95]
	v_mfma_f32_16x16x32_bf16 v[84:87], v[142:145], v[216:219], v[84:87]
	v_mfma_f32_16x16x32_bf16 v[76:79], v[150:153], v[216:219], v[76:79]
	v_mfma_f32_16x16x32_bf16 v[116:119], v[154:157], v[178:181], v[116:119]
	v_mfma_f32_16x16x32_bf16 v[112:115], v[166:169], v[178:181], v[112:115]
	v_mfma_f32_16x16x32_bf16 v[100:103], v[154:157], v[186:189], v[100:103]
	v_mfma_f32_16x16x32_bf16 v[88:91], v[166:169], v[186:189], v[88:91]
	v_mfma_f32_16x16x32_bf16 v[80:83], v[154:157], v[198:201], v[80:83]
	v_mfma_f32_16x16x32_bf16 v[72:75], v[166:169], v[198:201], v[72:75]
	v_mfma_f32_16x16x32_bf16 v[68:71], v[154:157], v[212:215], v[68:71]
	v_mfma_f32_16x16x32_bf16 v[64:67], v[166:169], v[212:215], v[64:67]
	v_mfma_f32_16x16x32_bf16 v[116:119], v[158:161], v[182:185], v[116:119]
	v_mfma_f32_16x16x32_bf16 v[112:115], v[170:173], v[182:185], v[112:115]
	v_mfma_f32_16x16x32_bf16 v[100:103], v[158:161], v[190:193], v[100:103]
	v_mfma_f32_16x16x32_bf16 v[88:91], v[170:173], v[190:193], v[88:91]
	v_mfma_f32_16x16x32_bf16 v[80:83], v[158:161], v[208:211], v[80:83]
	v_mfma_f32_16x16x32_bf16 v[72:75], v[170:173], v[208:211], v[72:75]
	v_mfma_f32_16x16x32_bf16 v[68:71], v[158:161], v[216:219], v[68:71]
	v_mfma_f32_16x16x32_bf16 v[64:67], v[170:173], v[216:219], v[64:67]
	s_setprio 0
	s_barrier
	s_add_u32 s30, s28, 0x100
	s_addc_u32 s31, s29, 0
	s_cmpk_eq_i32 s63, 0x54
	s_cselect_b32 s37, s15, s31
	s_cselect_b32 s36, s14, s30
	s_cselect_b32 s35, s27, s1
	s_cselect_b32 s34, s26, s0
	s_add_i32 s28, s64, s45
	v_lshl_add_u64 v[174:175], s[34:35], 0, v[176:177]
	s_mov_b32 m0, s28
	ds_read_b128 v[178:181], v165 offset:16384
	ds_read_b128 v[182:185], v165 offset:17408
	ds_read_b128 v[186:189], v165 offset:18432
	ds_read_b128 v[190:193], v165 offset:19456
	ds_read_b128 v[198:201], v165 offset:20480
	ds_read_b128 v[208:211], v165 offset:21504
	ds_read_b128 v[212:215], v165 offset:22528
	ds_read_b128 v[216:219], v165 offset:23552
	global_load_lds_dwordx4 v[174:175], off
	s_add_i32 m0, s28, 0x2000
	s_add_u32 s28, s34, 0x160000
	v_lshl_add_u64 v[194:195], s[34:35], 0, v[128:129]
	s_addc_u32 s29, s35, 0
	s_add_i32 s64, s65, s45
	global_load_lds_dwordx4 v[194:195], off
	v_lshl_add_u64 v[202:203], s[28:29], 0, v[176:177]
	s_mov_b32 m0, s64
	v_lshl_add_u64 v[220:221], s[36:37], 0, v[130:131]
	global_load_lds_dwordx4 v[202:203], off
	v_lshl_add_u64 v[202:203], s[28:29], 0, v[128:129]
	s_add_i32 m0, s64, 0x2000
	s_nop 0
	global_load_lds_dwordx4 v[202:203], off
	v_lshl_add_u64 v[202:203], s[36:37], 0, v[132:133]
	s_mov_b32 m0, s46
	s_nop 0
	global_load_lds_dwordx4 v[202:203], off
	s_mov_b32 m0, s47
	s_nop 0
	global_load_lds_dwordx4 v[220:221], off
	s_add_u32 s28, s36, 0x160000
	s_addc_u32 s29, s37, 0
	s_waitcnt vmcnt(8)
	s_waitcnt lgkmcnt(0)
	s_barrier
; #define PG8_STAGE(bufoff, gbase, voff) do { _Pragma("unroll") for (int _i = 0; _i < 2; ++_i) \
;         __builtin_amdgcn_global_load_lds((const unsigned*)((const char*)(gbase) + (voff)[_i]), (LAS unsigned*)(lds + (bufoff) + ldsw + _i * 8192), 16, 0, 0); } while (0)
; #define PG8_LDA(dst, b, h) do { _Pragma("unroll") for (int m = 0; m < 4; ++m) _Pragma("unroll") for (int k = 0; k < 2; ++k) dst[m][k] = *(const LAS bf16x8*)(lds + PG8_SA(b, h) + aoff + m * 2048 + k * 1024); } while (0)
; #define PG8_LDB(dst, b, h) do { _Pragma("unroll") for (int n = 0; n < 2; ++n) _Pragma("unroll") for (int k = 0; k < 2; ++k) dst[n][k] = *(const LAS bf16x8*)(lds + PG8_SB(b, h) + boff + n * 2048 + k * 1024); } while (0)
; #define PG8_WAIT_V(n) asm volatile("s_waitcnt vmcnt(" #n ")" ::: "memory")
; #define PG8_WAIT_L(n) asm volatile("s_waitcnt lgkmcnt(" #n ")" ::: "memory")
; #define PG8_BAR __builtin_amdgcn_s_barrier()
; #define PG8_SCHED __builtin_amdgcn_sched_barrier(0)
; template <bool F16, class Sched, class Epi>
; __device__ __forceinline__ void gemm_phase(LAS unsigned char* lds, const Gemm g, const Sched& S, const Epi& E, int wave_s) {
;     ...
;             PG8_WAIT_V(8); PG8_WAIT_L(0); PG8_BAR; PG8_MMA(1, 0, At, B0); PG8_MMA(1, 1, At, B1); PG8_BAR; PG8_SCHED;
;             PG8_LDB(B0, 1, 0); PG8_LDB(B1, 1, 1); PG8_SCHED; PG8_LDA(At, 1, 0); PG8_STAGE(PG8_SA(0, 1), a2 + hstepA, voffA);
;             PG8_WAIT_V(8); PG8_WAIT_L(0); PG8_BAR; PG8_MMA(0, 0, At, B0); PG8_MMA(0, 1, At, B1); PG8_BAR; PG8_SCHED;
	s_setprio 1
	v_mfma_f32_16x16x32_bf16 v[60:63], v[138:141], v[178:181], v[60:63]
	v_mfma_f32_16x16x32_bf16 v[56:59], v[146:149], v[178:181], v[56:59]
	v_mfma_f32_16x16x32_bf16 v[52:55], v[138:141], v[186:189], v[52:55]
	v_mfma_f32_16x16x32_bf16 v[44:47], v[146:149], v[186:189], v[44:47]
	v_mfma_f32_16x16x32_bf16 v[36:39], v[138:141], v[198:201], v[36:39]
	v_mfma_f32_16x16x32_bf16 v[28:31], v[146:149], v[198:201], v[28:31]
	v_mfma_f32_16x16x32_bf16 v[20:23], v[138:141], v[212:215], v[20:23]
	v_mfma_f32_16x16x32_bf16 v[12:15], v[146:149], v[212:215], v[12:15]
	v_mfma_f32_16x16x32_bf16 v[60:63], v[142:145], v[182:185], v[60:63]
	v_mfma_f32_16x16x32_bf16 v[56:59], v[150:153], v[182:185], v[56:59]
	v_mfma_f32_16x16x32_bf16 v[52:55], v[142:145], v[190:193], v[52:55]
	v_mfma_f32_16x16x32_bf16 v[44:47], v[150:153], v[190:193], v[44:47]
	v_mfma_f32_16x16x32_bf16 v[36:39], v[142:145], v[208:211], v[36:39]
	v_mfma_f32_16x16x32_bf16 v[28:31], v[150:153], v[208:211], v[28:31]
	v_mfma_f32_16x16x32_bf16 v[20:23], v[142:145], v[216:219], v[20:23]
	v_mfma_f32_16x16x32_bf16 v[12:15], v[150:153], v[216:219], v[12:15]
	v_mfma_f32_16x16x32_bf16 v[48:51], v[154:157], v[178:181], v[48:51]
	v_mfma_f32_16x16x32_bf16 v[40:43], v[166:169], v[178:181], v[40:43]
	v_mfma_f32_16x16x32_bf16 v[32:35], v[154:157], v[186:189], v[32:35]
	v_mfma_f32_16x16x32_bf16 v[24:27], v[166:169], v[186:189], v[24:27]
	v_mfma_f32_16x16x32_bf16 v[16:19], v[154:157], v[198:201], v[16:19]
	v_mfma_f32_16x16x32_bf16 v[8:11], v[166:169], v[198:201], v[8:11]
	v_mfma_f32_16x16x32_bf16 v[4:7], v[154:157], v[212:215], v[4:7]
	v_mfma_f32_16x16x32_bf16 v[0:3], v[166:169], v[212:215], v[0:3]
	v_mfma_f32_16x16x32_bf16 v[48:51], v[158:161], v[182:185], v[48:51]
	v_mfma_f32_16x16x32_bf16 v[40:43], v[170:173], v[182:185], v[40:43]
	v_mfma_f32_16x16x32_bf16 v[32:35], v[158:161], v[190:193], v[32:35]
	v_mfma_f32_16x16x32_bf16 v[24:27], v[170:173], v[190:193], v[24:27]
	v_mfma_f32_16x16x32_bf16 v[16:19], v[158:161], v[208:211], v[16:19]
	v_mfma_f32_16x16x32_bf16 v[8:11], v[170:173], v[208:211], v[8:11]
	v_mfma_f32_16x16x32_bf16 v[4:7], v[158:161], v[216:219], v[4:7]
	v_mfma_f32_16x16x32_bf16 v[0:3], v[170:173], v[216:219], v[0:3]
	s_setprio 0
	s_barrier
	s_add_i32 s64, 0, 0x18000
	s_add_i32 s65, 0, 0x1c000
	v_add_u32_e32 v150, s64, v163
	v_add_u32_e32 v170, s65, v163
	ds_read_b128 v[138:141], v150
	ds_read_b128 v[142:145], v150 offset:1024
	ds_read_b128 v[146:149], v150 offset:2048
	ds_read_b128 v[150:153], v150 offset:3072
	ds_read_b128 v[154:157], v170
	ds_read_b128 v[158:161], v170 offset:1024
	ds_read_b128 v[166:169], v170 offset:2048
	ds_read_b128 v[170:173], v170 offset:3072
	s_mov_b32 m0, s48
	ds_read_b128 v[178:181], v165 offset:32768
	ds_read_b128 v[182:185], v165 offset:33792
	ds_read_b128 v[186:189], v165 offset:34816
	ds_read_b128 v[190:193], v165 offset:35840
	ds_read_b128 v[198:201], v165 offset:36864
	ds_read_b128 v[208:211], v165 offset:37888
	ds_read_b128 v[212:215], v165 offset:38912
	ds_read_b128 v[216:219], v165 offset:39936
	global_load_lds_dwordx4 v132, s[28:29]
	s_mov_b32 m0, s49
	s_nop 0
	global_load_lds_dwordx4 v130, s[28:29]
	s_waitcnt vmcnt(8)
	s_waitcnt lgkmcnt(0)
	s_barrier
	s_setprio 1
	v_mfma_f32_16x16x32_bf16 v[124:127], v[138:141], v[178:181], v[124:127]
	v_mfma_f32_16x16x32_bf16 v[120:123], v[146:149], v[178:181], v[120:123]
	v_mfma_f32_16x16x32_bf16 v[108:111], v[138:141], v[186:189], v[108:111]
	v_mfma_f32_16x16x32_bf16 v[104:107], v[146:149], v[186:189], v[104:107]
	v_mfma_f32_16x16x32_bf16 v[96:99], v[138:141], v[198:201], v[96:99]
	v_mfma_f32_16x16x32_bf16 v[92:95], v[146:149], v[198:201], v[92:95]
	v_mfma_f32_16x16x32_bf16 v[84:87], v[138:141], v[212:215], v[84:87]
	v_mfma_f32_16x16x32_bf16 v[76:79], v[146:149], v[212:215], v[76:79]
	v_mfma_f32_16x16x32_bf16 v[124:127], v[142:145], v[182:185], v[124:127]
	v_mfma_f32_16x16x32_bf16 v[120:123], v[150:153], v[182:185], v[120:123]
	v_mfma_f32_16x16x32_bf16 v[108:111], v[142:145], v[190:193], v[108:111]
	v_mfma_f32_16x16x32_bf16 v[104:107], v[150:153], v[190:193], v[104:107]
	v_mfma_f32_16x16x32_bf16 v[96:99], v[142:145], v[208:211], v[96:99]
	v_mfma_f32_16x16x32_bf16 v[92:95], v[150:153], v[208:211], v[92:95]
	v_mfma_f32_16x16x32_bf16 v[84:87], v[142:145], v[216:219], v[84:87]
	v_mfma_f32_16x16x32_bf16 v[76:79], v[150:153], v[216:219], v[76:79]
	v_mfma_f32_16x16x32_bf16 v[116:119], v[154:157], v[178:181], v[116:119]
	v_mfma_f32_16x16x32_bf16 v[112:115], v[166:169], v[178:181], v[112:115]
	v_mfma_f32_16x16x32_bf16 v[100:103], v[154:157], v[186:189], v[100:103]
	v_mfma_f32_16x16x32_bf16 v[88:91], v[166:169], v[186:189], v[88:91]
	v_mfma_f32_16x16x32_bf16 v[80:83], v[154:157], v[198:201], v[80:83]
	v_mfma_f32_16x16x32_bf16 v[72:75], v[166:169], v[198:201], v[72:75]
	v_mfma_f32_16x16x32_bf16 v[68:71], v[154:157], v[212:215], v[68:71]
	v_mfma_f32_16x16x32_bf16 v[64:67], v[166:169], v[212:215], v[64:67]
	v_mfma_f32_16x16x32_bf16 v[116:119], v[158:161], v[182:185], v[116:119]
	v_mfma_f32_16x16x32_bf16 v[112:115], v[170:173], v[182:185], v[112:115]
	v_mfma_f32_16x16x32_bf16 v[100:103], v[158:161], v[190:193], v[100:103]
	v_mfma_f32_16x16x32_bf16 v[88:91], v[170:173], v[190:193], v[88:91]
	v_mfma_f32_16x16x32_bf16 v[80:83], v[158:161], v[208:211], v[80:83]
	v_mfma_f32_16x16x32_bf16 v[72:75], v[170:173], v[208:211], v[72:75]
	v_mfma_f32_16x16x32_bf16 v[68:71], v[158:161], v[216:219], v[68:71]
	v_mfma_f32_16x16x32_bf16 v[64:67], v[170:173], v[216:219], v[64:67]
	s_setprio 0
	s_barrier
; #define PG8_STAGE(bufoff, gbase, voff) do { _Pragma("unroll") for (int _i = 0; _i < 2; ++_i) \
;         __builtin_amdgcn_global_load_lds((const unsigned*)((const char*)(gbase) + (voff)[_i]), (LAS unsigned*)(lds + (bufoff) + ldsw + _i * 8192), 16, 0, 0); } while (0)
; #define PG8_LDA(dst, b, h) do { _Pragma("unroll") for (int m = 0; m < 4; ++m) _Pragma("unroll") for (int k = 0; k < 2; ++k) dst[m][k] = *(const LAS bf16x8*)(lds + PG8_SA(b, h) + aoff + m * 2048 + k * 1024); } while (0)
; #define PG8_WAIT_V(n) asm volatile("s_waitcnt vmcnt(" #n ")" ::: "memory")
; #define PG8_WAIT_L(n) asm volatile("s_waitcnt lgkmcnt(" #n ")" ::: "memory")
; #define PG8_BAR __builtin_amdgcn_s_barrier()
; #define PG8_SCHED __builtin_amdgcn_sched_barrier(0)
; template <bool F16, class Sched, class Epi>
; __device__ __forceinline__ void gemm_phase(LAS unsigned char* lds, const Gemm g, const Sched& S, const Epi& E, int wave_s) {
;     ...
;             PG8_LDA(At, 1, 1); PG8_STAGE(PG8_SB(1, 0), b3, voffB); PG8_STAGE(PG8_SB(1, 1), b3 + hstepB, voffB); PG8_STAGE(PG8_SA(1, 0), a3, voffA);
;             PG8_WAIT_V(8); PG8_WAIT_L(0); PG8_BAR; PG8_MMA(1, 0, At, B0); PG8_MMA(1, 1, At, B1); PG8_BAR; PG8_SCHED;
;         }
;         if (wr == 0) PG8_BAR;
	s_add_i32 s28, s64, s45
	v_lshl_add_u64 v[174:175], v[174:175], 0, s[54:55]
	s_mov_b32 m0, s28
	ds_read_b128 v[178:181], v165 offset:49152
	ds_read_b128 v[182:185], v165 offset:50176
	ds_read_b128 v[186:189], v165 offset:51200
	ds_read_b128 v[190:193], v165 offset:52224
	ds_read_b128 v[198:201], v165 offset:53248
	ds_read_b128 v[208:211], v165 offset:54272
	ds_read_b128 v[212:215], v165 offset:55296
	ds_read_b128 v[216:219], v165 offset:56320
	global_load_lds_dwordx4 v[174:175], off
	s_add_i32 m0, s28, 0x2000
	s_add_u32 s28, s34, 0x160080
	v_lshl_add_u64 v[174:175], v[194:195], 0, s[54:55]
	s_addc_u32 s29, s35, 0
	s_add_i32 s34, s65, s45
	global_load_lds_dwordx4 v[174:175], off
	v_lshl_add_u64 v[174:175], s[28:29], 0, v[176:177]
	s_mov_b32 m0, s34
	s_nop 0
	global_load_lds_dwordx4 v[174:175], off
	v_lshl_add_u64 v[174:175], s[28:29], 0, v[128:129]
	s_add_i32 m0, s34, 0x2000
	s_nop 0
	global_load_lds_dwordx4 v[174:175], off
	v_lshl_add_u64 v[174:175], v[202:203], 0, s[54:55]
	s_mov_b32 m0, s52
	s_nop 0
	global_load_lds_dwordx4 v[174:175], off
	v_lshl_add_u64 v[174:175], v[220:221], 0, s[54:55]
	s_mov_b32 m0, s53
	s_nop 0
	global_load_lds_dwordx4 v[174:175], off
	s_waitcnt vmcnt(8)
	s_waitcnt lgkmcnt(0)
	s_barrier
	s_setprio 1
	v_mfma_f32_16x16x32_bf16 v[60:63], v[138:141], v[178:181], v[60:63]
	v_mfma_f32_16x16x32_bf16 v[56:59], v[146:149], v[178:181], v[56:59]
	v_mfma_f32_16x16x32_bf16 v[52:55], v[138:141], v[186:189], v[52:55]
	v_mfma_f32_16x16x32_bf16 v[44:47], v[146:149], v[186:189], v[44:47]
	v_mfma_f32_16x16x32_bf16 v[36:39], v[138:141], v[198:201], v[36:39]
	v_mfma_f32_16x16x32_bf16 v[28:31], v[146:149], v[198:201], v[28:31]
	v_mfma_f32_16x16x32_bf16 v[20:23], v[138:141], v[212:215], v[20:23]
	v_mfma_f32_16x16x32_bf16 v[12:15], v[146:149], v[212:215], v[12:15]
	v_mfma_f32_16x16x32_bf16 v[60:63], v[142:145], v[182:185], v[60:63]
	v_mfma_f32_16x16x32_bf16 v[56:59], v[150:153], v[182:185], v[56:59]
	v_mfma_f32_16x16x32_bf16 v[52:55], v[142:145], v[190:193], v[52:55]
	v_mfma_f32_16x16x32_bf16 v[44:47], v[150:153], v[190:193], v[44:47]
	v_mfma_f32_16x16x32_bf16 v[36:39], v[142:145], v[208:211], v[36:39]
	v_mfma_f32_16x16x32_bf16 v[28:31], v[150:153], v[208:211], v[28:31]
	v_mfma_f32_16x16x32_bf16 v[20:23], v[142:145], v[216:219], v[20:23]
	v_mfma_f32_16x16x32_bf16 v[12:15], v[150:153], v[216:219], v[12:15]
	v_mfma_f32_16x16x32_bf16 v[48:51], v[154:157], v[178:181], v[48:51]
	v_mfma_f32_16x16x32_bf16 v[40:43], v[166:169], v[178:181], v[40:43]
	v_mfma_f32_16x16x32_bf16 v[32:35], v[154:157], v[186:189], v[32:35]
	v_mfma_f32_16x16x32_bf16 v[24:27], v[166:169], v[186:189], v[24:27]
	v_mfma_f32_16x16x32_bf16 v[16:19], v[154:157], v[198:201], v[16:19]
	v_mfma_f32_16x16x32_bf16 v[8:11], v[166:169], v[198:201], v[8:11]
	v_mfma_f32_16x16x32_bf16 v[4:7], v[154:157], v[212:215], v[4:7]
	v_mfma_f32_16x16x32_bf16 v[0:3], v[166:169], v[212:215], v[0:3]
	v_mfma_f32_16x16x32_bf16 v[48:51], v[158:161], v[182:185], v[48:51]
	v_mfma_f32_16x16x32_bf16 v[40:43], v[170:173], v[182:185], v[40:43]
	v_mfma_f32_16x16x32_bf16 v[32:35], v[158:161], v[190:193], v[32:35]
	v_mfma_f32_16x16x32_bf16 v[24:27], v[170:173], v[190:193], v[24:27]
	v_mfma_f32_16x16x32_bf16 v[16:19], v[158:161], v[208:211], v[16:19]
	v_mfma_f32_16x16x32_bf16 v[8:11], v[170:173], v[208:211], v[8:11]
	v_mfma_f32_16x16x32_bf16 v[4:7], v[158:161], v[216:219], v[4:7]
	v_mfma_f32_16x16x32_bf16 v[0:3], v[170:173], v[216:219], v[0:3]
	s_setprio 0
	s_barrier
	s_add_i32 s63, s63, 2
	s_add_u32 s0, s0, 0x100
	s_addc_u32 s1, s1, 0
	s_cmpk_gt_u32 s63, 0x55
	s_mov_b64 s[28:29], s[30:31]
	s_cbranch_scc0 .LBB0_795
	s_and_b64 vcc, exec, s[12:13]
	s_cbranch_vccz .LBB0_798
	s_barrier

; #define PG8_STAGE(bufoff, gbase, voff) do { _Pragma("unroll") for (int _i = 0; _i < 2; ++_i) \
;         __builtin_amdgcn_global_load_lds((const unsigned*)((const char*)(gbase) + (voff)[_i]), (LAS unsigned*)(lds + (bufoff) + ldsw + _i * 8192), 16, 0, 0); } while (0)
; #define PG8_LDA(dst, b, h) do { _Pragma("unroll") for (int m = 0; m < 4; ++m) _Pragma("unroll") for (int k = 0; k < 2; ++k) dst[m][k] = *(const LAS bf16x8*)(lds + PG8_SA(b, h) + aoff + m * 2048 + k * 1024); } while (0)
; #define PG8_LDB(dst, b, h) do { _Pragma("unroll") for (int n = 0; n < 2; ++n) _Pragma("unroll") for (int k = 0; k < 2; ++k) dst[n][k] = *(const LAS bf16x8*)(lds + PG8_SB(b, h) + boff + n * 2048 + k * 1024); } while (0)
; #define PG8_WAIT_V(n) asm volatile("s_waitcnt vmcnt(" #n ")" ::: "memory")
; #define PG8_WAIT_L(n) asm volatile("s_waitcnt lgkmcnt(" #n ")" ::: "memory")
; #define PG8_BAR __builtin_amdgcn_s_barrier()
; #define PG8_SCHED __builtin_amdgcn_sched_barrier(0)
; template <bool F16, class Sched, class Epi>
; __device__ __forceinline__ void gemm_phase(LAS unsigned char* lds, const Gemm g, const Sched& S, const Epi& E, int wave_s) {
;     ...
;         const char* nA = has_next ? (const char*)g.A + PG8_AOFF(nxt) : cA + (size_t)(nt - 2) * kstep; const char* nB = has_next ? (const char*)g.Bt + (size_t)nxt.pn * tstepB : cB + (size_t)(nt - 2) * kstep;
;         for (int t = 0; t < nt; t += 2) {
;             const bool last = (t == nt - 2);
;             const char* a1 = cA + (size_t)(t + 1) * kstep;
;             const char* a2 = last ? nA : cA + (size_t)(t + 2) * kstep; const char* b2 = last ? nB : cB + (size_t)(t + 2) * kstep;
;             const char* a3 = a2 + kstep; const char* b3 = b2 + kstep;
;             PG8_LDB(B0, 0, 0); PG8_LDB(B1, 0, 1); PG8_SCHED; PG8_LDA(At, 0, 0); PG8_STAGE(PG8_SA(1, 1), a1 + hstepA, voffA);
;             PG8_WAIT_V(8); PG8_WAIT_L(0); PG8_BAR; PG8_MMA(0, 0, At, B0); PG8_MMA(0, 1, At, B1); PG8_BAR; PG8_SCHED;
;             PG8_LDA(At, 0, 1); PG8_STAGE(PG8_SB(0, 0), b2, voffB); PG8_STAGE(PG8_SB(0, 1), b2 + hstepB, voffB); PG8_STAGE(PG8_SA(0, 0), a2, voffA);
.LBB0_869:
	s_add_i32 s64, 0, 0x10000
	s_add_i32 s68, 0, 0x14000
	v_add_u32_e32 v44, s64, v208
	v_add_u32_e32 v156, s68, v208
	ds_read_b128 v[32:35], v44
	ds_read_b128 v[36:39], v44 offset:1024
	ds_read_b128 v[40:43], v44 offset:2048
	ds_read_b128 v[44:47], v44 offset:3072
	ds_read_b128 v[144:147], v156
	ds_read_b128 v[148:151], v156 offset:1024
	ds_read_b128 v[152:155], v156 offset:2048
	ds_read_b128 v[156:159], v156 offset:3072
	s_add_i32 m0, s44, 0xc000
	ds_read_b128 v[160:163], v210
	ds_read_b128 v[164:167], v210 offset:1024
	ds_read_b128 v[168:171], v210 offset:2048
	ds_read_b128 v[172:175], v210 offset:3072
	ds_read_b128 v[188:191], v210 offset:4096
	ds_read_b128 v[192:195], v210 offset:5120
	ds_read_b128 v[198:201], v210 offset:6144
	ds_read_b128 v[212:215], v210 offset:7168
	global_load_lds_dwordx4 v184, s[4:5]
	s_add_i32 m0, s44, 0xe000
	s_nop 0
	global_load_lds_dwordx4 v186, s[4:5]
	s_waitcnt vmcnt(8)
	s_waitcnt lgkmcnt(0)
	s_barrier
	s_setprio 1
	v_mfma_f32_16x16x32_bf16 v[140:143], v[32:35], v[160:163], v[140:143]
	v_mfma_f32_16x16x32_bf16 v[136:139], v[40:43], v[160:163], v[136:139]
	v_mfma_f32_16x16x32_bf16 v[124:127], v[32:35], v[168:171], v[124:127]
	v_mfma_f32_16x16x32_bf16 v[120:123], v[40:43], v[168:171], v[120:123]
	v_mfma_f32_16x16x32_bf16 v[108:111], v[32:35], v[188:191], v[108:111]
	v_mfma_f32_16x16x32_bf16 v[104:107], v[40:43], v[188:191], v[104:107]
	v_mfma_f32_16x16x32_bf16 v[92:95], v[32:35], v[198:201], v[92:95]
	v_mfma_f32_16x16x32_bf16 v[88:91], v[40:43], v[198:201], v[88:91]
	v_mfma_f32_16x16x32_bf16 v[140:143], v[36:39], v[164:167], v[140:143]
	v_mfma_f32_16x16x32_bf16 v[136:139], v[44:47], v[164:167], v[136:139]
	v_mfma_f32_16x16x32_bf16 v[124:127], v[36:39], v[172:175], v[124:127]
	v_mfma_f32_16x16x32_bf16 v[120:123], v[44:47], v[172:175], v[120:123]
	v_mfma_f32_16x16x32_bf16 v[108:111], v[36:39], v[192:195], v[108:111]
	v_mfma_f32_16x16x32_bf16 v[104:107], v[44:47], v[192:195], v[104:107]
	v_mfma_f32_16x16x32_bf16 v[92:95], v[36:39], v[212:215], v[92:95]
	v_mfma_f32_16x16x32_bf16 v[88:91], v[44:47], v[212:215], v[88:91]
	v_mfma_f32_16x16x32_bf16 v[132:135], v[144:147], v[160:163], v[132:135]
	v_mfma_f32_16x16x32_bf16 v[128:131], v[152:155], v[160:163], v[128:131]
	v_mfma_f32_16x16x32_bf16 v[116:119], v[144:147], v[168:171], v[116:119]
	v_mfma_f32_16x16x32_bf16 v[112:115], v[152:155], v[168:171], v[112:115]
	v_mfma_f32_16x16x32_bf16 v[100:103], v[144:147], v[188:191], v[100:103]
	v_mfma_f32_16x16x32_bf16 v[96:99], v[152:155], v[188:191], v[96:99]
	v_mfma_f32_16x16x32_bf16 v[84:87], v[144:147], v[198:201], v[84:87]
	v_mfma_f32_16x16x32_bf16 v[80:83], v[152:155], v[198:201], v[80:83]
	v_mfma_f32_16x16x32_bf16 v[132:135], v[148:151], v[164:167], v[132:135]
	v_mfma_f32_16x16x32_bf16 v[128:131], v[156:159], v[164:167], v[128:131]
	v_mfma_f32_16x16x32_bf16 v[116:119], v[148:151], v[172:175], v[116:119]
	v_mfma_f32_16x16x32_bf16 v[112:115], v[156:159], v[172:175], v[112:115]
	v_mfma_f32_16x16x32_bf16 v[100:103], v[148:151], v[192:195], v[100:103]
	v_mfma_f32_16x16x32_bf16 v[96:99], v[156:159], v[192:195], v[96:99]
	v_mfma_f32_16x16x32_bf16 v[84:87], v[148:151], v[212:215], v[84:87]
	v_mfma_f32_16x16x32_bf16 v[80:83], v[156:159], v[212:215], v[80:83]
	s_setprio 0
	s_barrier
	s_add_u32 s30, s4, 0xfff80080
	s_addc_u32 s31, s5, -1
	s_cmp_eq_u32 s63, 28
	s_cselect_b32 s35, s53, s31
	s_cselect_b32 s34, s58, s30
	s_cselect_b32 s31, s59, s62
	s_cselect_b32 s30, s60, s61
	s_add_i32 s64, s64, s41
	v_lshl_add_u64 v[202:203], s[30:31], 0, v[176:177]
	s_mov_b32 m0, s64
	ds_read_b128 v[160:163], v210 offset:16384
	ds_read_b128 v[164:167], v210 offset:17408
	ds_read_b128 v[168:171], v210 offset:18432
	ds_read_b128 v[172:175], v210 offset:19456
	ds_read_b128 v[188:191], v210 offset:20480
	ds_read_b128 v[192:195], v210 offset:21504
	ds_read_b128 v[198:201], v210 offset:22528
	ds_read_b128 v[212:215], v210 offset:23552
	global_load_lds_dwordx4 v[202:203], off
	s_add_i32 m0, s64, 0x2000
	s_add_u32 s64, s30, 0x80000
	v_lshl_add_u64 v[216:217], s[30:31], 0, v[178:179]
	s_addc_u32 s65, s31, 0
	s_add_i32 s68, s68, s41
	global_load_lds_dwordx4 v[216:217], off
	v_lshl_add_u64 v[218:219], s[64:65], 0, v[176:177]
	s_mov_b32 m0, s68
	v_lshl_add_u64 v[220:221], s[34:35], 0, v[180:181]
	global_load_lds_dwordx4 v[218:219], off
	v_lshl_add_u64 v[218:219], s[64:65], 0, v[178:179]
	s_add_i32 m0, s68, 0x2000
	s_nop 0
	global_load_lds_dwordx4 v[218:219], off
	v_lshl_add_u64 v[218:219], s[34:35], 0, v[182:183]
	s_mov_b32 m0, s44
	s_nop 0
	global_load_lds_dwordx4 v[218:219], off
	s_mov_b32 m0, s45
	s_nop 0
	global_load_lds_dwordx4 v[220:221], off
	s_add_u32 s34, s34, 0x80000
	s_addc_u32 s35, s35, 0
	s_waitcnt vmcnt(8)
	s_waitcnt lgkmcnt(0)
	s_barrier
; #define PG8_STAGE(bufoff, gbase, voff) do { _Pragma("unroll") for (int _i = 0; _i < 2; ++_i) \
;         __builtin_amdgcn_global_load_lds((const unsigned*)((const char*)(gbase) + (voff)[_i]), (LAS unsigned*)(lds + (bufoff) + ldsw + _i * 8192), 16, 0, 0); } while (0)
; #define PG8_LDA(dst, b, h) do { _Pragma("unroll") for (int m = 0; m < 4; ++m) _Pragma("unroll") for (int k = 0; k < 2; ++k) dst[m][k] = *(const LAS bf16x8*)(lds + PG8_SA(b, h) + aoff + m * 2048 + k * 1024); } while (0)
; #define PG8_LDB(dst, b, h) do { _Pragma("unroll") for (int n = 0; n < 2; ++n) _Pragma("unroll") for (int k = 0; k < 2; ++k) dst[n][k] = *(const LAS bf16x8*)(lds + PG8_SB(b, h) + boff + n * 2048 + k * 1024); } while (0)
; #define PG8_WAIT_V(n) asm volatile("s_waitcnt vmcnt(" #n ")" ::: "memory")
; #define PG8_WAIT_L(n) asm volatile("s_waitcnt lgkmcnt(" #n ")" ::: "memory")
; #define PG8_BAR __builtin_amdgcn_s_barrier()
; #define PG8_SCHED __builtin_amdgcn_sched_barrier(0)
; template <bool F16, class Sched, class Epi>
; __device__ __forceinline__ void gemm_phase(LAS unsigned char* lds, const Gemm g, const Sched& S, const Epi& E, int wave_s) {
;     ...
;             PG8_WAIT_V(8); PG8_WAIT_L(0); PG8_BAR; PG8_MMA(1, 0, At, B0); PG8_MMA(1, 1, At, B1); PG8_BAR; PG8_SCHED;
;             PG8_LDB(B0, 1, 0); PG8_LDB(B1, 1, 1); PG8_SCHED; PG8_LDA(At, 1, 0); PG8_STAGE(PG8_SA(0, 1), a2 + hstepA, voffA);
;             PG8_WAIT_V(8); PG8_WAIT_L(0); PG8_BAR; PG8_MMA(0, 0, At, B0); PG8_MMA(0, 1, At, B1); PG8_BAR; PG8_SCHED;
	s_setprio 1
	v_mfma_f32_16x16x32_bf16 v[76:79], v[32:35], v[160:163], v[76:79]
	v_mfma_f32_16x16x32_bf16 v[72:75], v[40:43], v[160:163], v[72:75]
	v_mfma_f32_16x16x32_bf16 v[60:63], v[32:35], v[168:171], v[60:63]
	v_mfma_f32_16x16x32_bf16 v[56:59], v[40:43], v[168:171], v[56:59]
	v_mfma_f32_16x16x32_bf16 v[28:31], v[32:35], v[188:191], v[28:31]
	v_mfma_f32_16x16x32_bf16 v[24:27], v[40:43], v[188:191], v[24:27]
	v_mfma_f32_16x16x32_bf16 v[12:15], v[32:35], v[198:201], v[12:15]
	v_mfma_f32_16x16x32_bf16 v[8:11], v[40:43], v[198:201], v[8:11]
	v_mfma_f32_16x16x32_bf16 v[76:79], v[36:39], v[164:167], v[76:79]
	v_mfma_f32_16x16x32_bf16 v[72:75], v[44:47], v[164:167], v[72:75]
	v_mfma_f32_16x16x32_bf16 v[60:63], v[36:39], v[172:175], v[60:63]
	v_mfma_f32_16x16x32_bf16 v[56:59], v[44:47], v[172:175], v[56:59]
	v_mfma_f32_16x16x32_bf16 v[28:31], v[36:39], v[192:195], v[28:31]
	v_mfma_f32_16x16x32_bf16 v[24:27], v[44:47], v[192:195], v[24:27]
	v_mfma_f32_16x16x32_bf16 v[12:15], v[36:39], v[212:215], v[12:15]
	v_mfma_f32_16x16x32_bf16 v[8:11], v[44:47], v[212:215], v[8:11]
	v_mfma_f32_16x16x32_bf16 v[20:23], v[144:147], v[188:191], v[20:23]
	v_mfma_f32_16x16x32_bf16 v[16:19], v[152:155], v[188:191], v[16:19]
	v_mfma_f32_16x16x32_bf16 v[4:7], v[144:147], v[198:201], v[4:7]
	v_mfma_f32_16x16x32_bf16 v[0:3], v[152:155], v[198:201], v[0:3]
	v_mfma_f32_16x16x32_bf16 v[32:35], v[144:147], v[160:163], v[68:71]
	v_mfma_f32_16x16x32_bf16 v[36:39], v[152:155], v[160:163], v[64:67]
	v_mfma_f32_16x16x32_bf16 v[40:43], v[144:147], v[168:171], v[52:55]
	v_mfma_f32_16x16x32_bf16 v[44:47], v[152:155], v[168:171], v[48:51]
	v_mfma_f32_16x16x32_bf16 v[20:23], v[148:151], v[192:195], v[20:23]
	v_mfma_f32_16x16x32_bf16 v[16:19], v[156:159], v[192:195], v[16:19]
	v_mfma_f32_16x16x32_bf16 v[4:7], v[148:151], v[212:215], v[4:7]
	v_mfma_f32_16x16x32_bf16 v[0:3], v[156:159], v[212:215], v[0:3]
	v_mfma_f32_16x16x32_bf16 v[32:35], v[148:151], v[164:167], v[32:35]
	v_mfma_f32_16x16x32_bf16 v[36:39], v[156:159], v[164:167], v[36:39]
	v_mfma_f32_16x16x32_bf16 v[40:43], v[148:151], v[172:175], v[40:43]
	v_mfma_f32_16x16x32_bf16 v[44:47], v[156:159], v[172:175], v[44:47]
	s_setprio 0
	s_barrier
	s_add_i32 s64, 0, 0x18000
	s_add_i32 s65, 0, 0x1c000
	v_add_u32_e32 v68, s64, v208
	v_add_u32_e32 v156, s65, v208
	ds_read_b128 v[48:51], v68
	ds_read_b128 v[52:55], v68 offset:1024
	ds_read_b128 v[64:67], v68 offset:2048
	ds_read_b128 v[68:71], v68 offset:3072
	ds_read_b128 v[144:147], v156
	ds_read_b128 v[148:151], v156 offset:1024
	ds_read_b128 v[152:155], v156 offset:2048
	ds_read_b128 v[156:159], v156 offset:3072
	s_mov_b32 m0, s46
	ds_read_b128 v[160:163], v210 offset:32768
	ds_read_b128 v[164:167], v210 offset:33792
	ds_read_b128 v[168:171], v210 offset:34816
	ds_read_b128 v[172:175], v210 offset:35840
	ds_read_b128 v[188:191], v210 offset:36864
	ds_read_b128 v[192:195], v210 offset:37888
	ds_read_b128 v[198:201], v210 offset:38912
	ds_read_b128 v[212:215], v210 offset:39936
	global_load_lds_dwordx4 v182, s[34:35]
	s_mov_b32 m0, s47
	s_nop 0
	global_load_lds_dwordx4 v180, s[34:35]
	s_waitcnt vmcnt(8)
	s_waitcnt lgkmcnt(0)
	s_barrier
	s_setprio 1
	v_mfma_f32_16x16x32_bf16 v[140:143], v[48:51], v[160:163], v[140:143]
	v_mfma_f32_16x16x32_bf16 v[136:139], v[64:67], v[160:163], v[136:139]
	v_mfma_f32_16x16x32_bf16 v[124:127], v[48:51], v[168:171], v[124:127]
	v_mfma_f32_16x16x32_bf16 v[120:123], v[64:67], v[168:171], v[120:123]
	v_mfma_f32_16x16x32_bf16 v[108:111], v[48:51], v[188:191], v[108:111]
	v_mfma_f32_16x16x32_bf16 v[104:107], v[64:67], v[188:191], v[104:107]
	v_mfma_f32_16x16x32_bf16 v[92:95], v[48:51], v[198:201], v[92:95]
	v_mfma_f32_16x16x32_bf16 v[88:91], v[64:67], v[198:201], v[88:91]
	v_mfma_f32_16x16x32_bf16 v[140:143], v[52:55], v[164:167], v[140:143]
	v_mfma_f32_16x16x32_bf16 v[136:139], v[68:71], v[164:167], v[136:139]
	v_mfma_f32_16x16x32_bf16 v[124:127], v[52:55], v[172:175], v[124:127]
	v_mfma_f32_16x16x32_bf16 v[120:123], v[68:71], v[172:175], v[120:123]
	v_mfma_f32_16x16x32_bf16 v[108:111], v[52:55], v[192:195], v[108:111]
	v_mfma_f32_16x16x32_bf16 v[104:107], v[68:71], v[192:195], v[104:107]
	v_mfma_f32_16x16x32_bf16 v[92:95], v[52:55], v[212:215], v[92:95]
	v_mfma_f32_16x16x32_bf16 v[88:91], v[68:71], v[212:215], v[88:91]
	v_mfma_f32_16x16x32_bf16 v[132:135], v[144:147], v[160:163], v[132:135]
	v_mfma_f32_16x16x32_bf16 v[128:131], v[152:155], v[160:163], v[128:131]
	v_mfma_f32_16x16x32_bf16 v[116:119], v[144:147], v[168:171], v[116:119]
	v_mfma_f32_16x16x32_bf16 v[112:115], v[152:155], v[168:171], v[112:115]
	v_mfma_f32_16x16x32_bf16 v[100:103], v[144:147], v[188:191], v[100:103]
	v_mfma_f32_16x16x32_bf16 v[96:99], v[152:155], v[188:191], v[96:99]
	v_mfma_f32_16x16x32_bf16 v[84:87], v[144:147], v[198:201], v[84:87]
	v_mfma_f32_16x16x32_bf16 v[80:83], v[152:155], v[198:201], v[80:83]
	v_mfma_f32_16x16x32_bf16 v[132:135], v[148:151], v[164:167], v[132:135]
	v_mfma_f32_16x16x32_bf16 v[128:131], v[156:159], v[164:167], v[128:131]
	v_mfma_f32_16x16x32_bf16 v[116:119], v[148:151], v[172:175], v[116:119]
	v_mfma_f32_16x16x32_bf16 v[112:115], v[156:159], v[172:175], v[112:115]
	v_mfma_f32_16x16x32_bf16 v[100:103], v[148:151], v[192:195], v[100:103]
	v_mfma_f32_16x16x32_bf16 v[96:99], v[156:159], v[192:195], v[96:99]
	v_mfma_f32_16x16x32_bf16 v[84:87], v[148:151], v[212:215], v[84:87]
	v_mfma_f32_16x16x32_bf16 v[80:83], v[156:159], v[212:215], v[80:83]
	s_setprio 0
	s_barrier
; #define PG8_STAGE(bufoff, gbase, voff) do { _Pragma("unroll") for (int _i = 0; _i < 2; ++_i) \
;         __builtin_amdgcn_global_load_lds((const unsigned*)((const char*)(gbase) + (voff)[_i]), (LAS unsigned*)(lds + (bufoff) + ldsw + _i * 8192), 16, 0, 0); } while (0)
; #define PG8_LDA(dst, b, h) do { _Pragma("unroll") for (int m = 0; m < 4; ++m) _Pragma("unroll") for (int k = 0; k < 2; ++k) dst[m][k] = *(const LAS bf16x8*)(lds + PG8_SA(b, h) + aoff + m * 2048 + k * 1024); } while (0)
; #define PG8_WAIT_V(n) asm volatile("s_waitcnt vmcnt(" #n ")" ::: "memory")
; #define PG8_WAIT_L(n) asm volatile("s_waitcnt lgkmcnt(" #n ")" ::: "memory")
; #define PG8_BAR __builtin_amdgcn_s_barrier()
; #define PG8_SCHED __builtin_amdgcn_sched_barrier(0)
; template <bool F16, class Sched, class Epi>
; __device__ __forceinline__ void gemm_phase(LAS unsigned char* lds, const Gemm g, const Sched& S, const Epi& E, int wave_s) {
;     ...
;             PG8_LDA(At, 1, 1); PG8_STAGE(PG8_SB(1, 0), b3, voffB); PG8_STAGE(PG8_SB(1, 1), b3 + hstepB, voffB); PG8_STAGE(PG8_SA(1, 0), a3, voffA);
;             PG8_WAIT_V(8); PG8_WAIT_L(0); PG8_BAR; PG8_MMA(1, 0, At, B0); PG8_MMA(1, 1, At, B1); PG8_BAR; PG8_SCHED;
;         }
;         if (wr == 0) PG8_BAR;
	s_add_i32 s34, s64, s41
	v_lshl_add_u64 v[202:203], v[202:203], 0, s[54:55]
	s_mov_b32 m0, s34
	ds_read_b128 v[160:163], v210 offset:49152
	ds_read_b128 v[164:167], v210 offset:50176
	ds_read_b128 v[168:171], v210 offset:51200
	ds_read_b128 v[172:175], v210 offset:52224
	ds_read_b128 v[188:191], v210 offset:53248
	ds_read_b128 v[192:195], v210 offset:54272
	ds_read_b128 v[198:201], v210 offset:55296
	ds_read_b128 v[212:215], v210 offset:56320
	global_load_lds_dwordx4 v[202:203], off
	s_add_i32 m0, s34, 0x2000
	s_add_u32 s30, s30, 0x80080
	v_lshl_add_u64 v[202:203], v[216:217], 0, s[54:55]
	s_addc_u32 s31, s31, 0
	s_add_i32 s34, s65, s41
	global_load_lds_dwordx4 v[202:203], off
	v_lshl_add_u64 v[202:203], s[30:31], 0, v[176:177]
	s_mov_b32 m0, s34
	s_nop 0
	global_load_lds_dwordx4 v[202:203], off
	v_lshl_add_u64 v[202:203], s[30:31], 0, v[178:179]
	s_add_i32 m0, s34, 0x2000
	s_nop 0
	global_load_lds_dwordx4 v[202:203], off
	v_lshl_add_u64 v[202:203], v[218:219], 0, s[54:55]
	s_mov_b32 m0, s49
	s_nop 0
	global_load_lds_dwordx4 v[202:203], off
	v_lshl_add_u64 v[202:203], v[220:221], 0, s[54:55]
	s_mov_b32 m0, s52
	s_nop 0
	global_load_lds_dwordx4 v[202:203], off
	s_waitcnt vmcnt(8)
	s_waitcnt lgkmcnt(0)
	s_barrier
	s_setprio 1
	v_mfma_f32_16x16x32_bf16 v[76:79], v[48:51], v[160:163], v[76:79]
	v_mfma_f32_16x16x32_bf16 v[72:75], v[64:67], v[160:163], v[72:75]
	v_mfma_f32_16x16x32_bf16 v[60:63], v[48:51], v[168:171], v[60:63]
	v_mfma_f32_16x16x32_bf16 v[56:59], v[64:67], v[168:171], v[56:59]
	v_mfma_f32_16x16x32_bf16 v[28:31], v[48:51], v[188:191], v[28:31]
	v_mfma_f32_16x16x32_bf16 v[24:27], v[64:67], v[188:191], v[24:27]
	v_mfma_f32_16x16x32_bf16 v[12:15], v[48:51], v[198:201], v[12:15]
	v_mfma_f32_16x16x32_bf16 v[8:11], v[64:67], v[198:201], v[8:11]
	v_mfma_f32_16x16x32_bf16 v[76:79], v[52:55], v[164:167], v[76:79]
	v_mfma_f32_16x16x32_bf16 v[72:75], v[68:71], v[164:167], v[72:75]
	v_mfma_f32_16x16x32_bf16 v[60:63], v[52:55], v[172:175], v[60:63]
	v_mfma_f32_16x16x32_bf16 v[56:59], v[68:71], v[172:175], v[56:59]
	v_mfma_f32_16x16x32_bf16 v[28:31], v[52:55], v[192:195], v[28:31]
	v_mfma_f32_16x16x32_bf16 v[24:27], v[68:71], v[192:195], v[24:27]
	v_mfma_f32_16x16x32_bf16 v[12:15], v[52:55], v[212:215], v[12:15]
	v_mfma_f32_16x16x32_bf16 v[8:11], v[68:71], v[212:215], v[8:11]
	v_mfma_f32_16x16x32_bf16 v[32:35], v[144:147], v[160:163], v[32:35]
	v_mfma_f32_16x16x32_bf16 v[68:71], v[148:151], v[164:167], v[32:35]
	v_mfma_f32_16x16x32_bf16 v[32:35], v[152:155], v[160:163], v[36:39]
	v_mfma_f32_16x16x32_bf16 v[64:67], v[156:159], v[164:167], v[32:35]
	v_mfma_f32_16x16x32_bf16 v[32:35], v[144:147], v[168:171], v[40:43]
	v_mfma_f32_16x16x32_bf16 v[52:55], v[148:151], v[172:175], v[32:35]
	v_mfma_f32_16x16x32_bf16 v[32:35], v[152:155], v[168:171], v[44:47]
	v_mfma_f32_16x16x32_bf16 v[20:23], v[144:147], v[188:191], v[20:23]
	v_mfma_f32_16x16x32_bf16 v[16:19], v[152:155], v[188:191], v[16:19]
	v_mfma_f32_16x16x32_bf16 v[4:7], v[144:147], v[198:201], v[4:7]
	v_mfma_f32_16x16x32_bf16 v[0:3], v[152:155], v[198:201], v[0:3]
	v_mfma_f32_16x16x32_bf16 v[48:51], v[156:159], v[172:175], v[32:35]
	v_mfma_f32_16x16x32_bf16 v[20:23], v[148:151], v[192:195], v[20:23]
	v_mfma_f32_16x16x32_bf16 v[16:19], v[156:159], v[192:195], v[16:19]
	v_mfma_f32_16x16x32_bf16 v[4:7], v[148:151], v[212:215], v[4:7]
	v_mfma_f32_16x16x32_bf16 v[0:3], v[156:159], v[212:215], v[0:3]
	s_setprio 0
	s_barrier
	s_add_i32 s63, s63, 2
	s_add_u32 s4, s4, 0x100
	s_addc_u32 s5, s5, 0
	s_add_u32 s61, s61, 0x100
	s_addc_u32 s62, s62, 0
	s_cmp_gt_u32 s63, 29
	s_cbranch_scc0 .LBB0_869
	s_and_b64 vcc, exec, s[26:27]
	s_cbranch_vccz .LBB0_872
	s_barrier

; #define PG8_STAGE(bufoff, gbase, voff) do { _Pragma("unroll") for (int _i = 0; _i < 2; ++_i) \
;         __builtin_amdgcn_global_load_lds((const unsigned*)((const char*)(gbase) + (voff)[_i]), (LAS unsigned*)(lds + (bufoff) + ldsw + _i * 8192), 16, 0, 0); } while (0)
; #define PG8_LDA(dst, b, h) do { _Pragma("unroll") for (int m = 0; m < 4; ++m) _Pragma("unroll") for (int k = 0; k < 2; ++k) dst[m][k] = *(const LAS bf16x8*)(lds + PG8_SA(b, h) + aoff + m * 2048 + k * 1024); } while (0)
; #define PG8_LDB(dst, b, h) do { _Pragma("unroll") for (int n = 0; n < 2; ++n) _Pragma("unroll") for (int k = 0; k < 2; ++k) dst[n][k] = *(const LAS bf16x8*)(lds + PG8_SB(b, h) + boff + n * 2048 + k * 1024); } while (0)
; #define PG8_WAIT_V(n) asm volatile("s_waitcnt vmcnt(" #n ")" ::: "memory")
; #define PG8_WAIT_L(n) asm volatile("s_waitcnt lgkmcnt(" #n ")" ::: "memory")
; #define PG8_BAR __builtin_amdgcn_s_barrier()
; #define PG8_SCHED __builtin_amdgcn_sched_barrier(0)
; template <bool F16, class Sched, class Epi>
; __device__ __forceinline__ void gemm_phase(LAS unsigned char* lds, const Gemm g, const Sched& S, const Epi& E, int wave_s) {
;     ...
;         const char* nA = has_next ? (const char*)g.A + PG8_AOFF(nxt) : cA + (size_t)(nt - 2) * kstep; const char* nB = has_next ? (const char*)g.Bt + (size_t)nxt.pn * tstepB : cB + (size_t)(nt - 2) * kstep;
;         for (int t = 0; t < nt; t += 2) {
;             const bool last = (t == nt - 2);
;             const char* a1 = cA + (size_t)(t + 1) * kstep;
;             const char* a2 = last ? nA : cA + (size_t)(t + 2) * kstep; const char* b2 = last ? nB : cB + (size_t)(t + 2) * kstep;
;             const char* a3 = a2 + kstep; const char* b3 = b2 + kstep;
;             PG8_LDB(B0, 0, 0); PG8_LDB(B1, 0, 1); PG8_SCHED; PG8_LDA(At, 0, 0); PG8_STAGE(PG8_SA(1, 1), a1 + hstepA, voffA);
;             PG8_WAIT_V(8); PG8_WAIT_L(0); PG8_BAR; PG8_MMA(0, 0, At, B0); PG8_MMA(0, 1, At, B1); PG8_BAR; PG8_SCHED;
;             PG8_LDA(At, 0, 1); PG8_STAGE(PG8_SB(0, 0), b2, voffB); PG8_STAGE(PG8_SB(0, 1), b2 + hstepB, voffB); PG8_STAGE(PG8_SA(0, 0), a2, voffA);
.LBB0_993:
	s_add_i32 s43, 0, 0x10000
	s_add_i32 s26, 0, 0x14000
	v_add_u32_e32 v68, s43, v208
	v_add_u32_e32 v156, s26, v208
	ds_read_b128 v[56:59], v68
	ds_read_b128 v[60:63], v68 offset:1024
	ds_read_b128 v[64:67], v68 offset:2048
	ds_read_b128 v[68:71], v68 offset:3072
	ds_read_b128 v[144:147], v156
	ds_read_b128 v[148:151], v156 offset:1024
	ds_read_b128 v[152:155], v156 offset:2048
	ds_read_b128 v[156:159], v156 offset:3072
	s_add_i32 m0, s18, 0xc000
	ds_read_b128 v[160:163], v210
	ds_read_b128 v[164:167], v210 offset:1024
	ds_read_b128 v[168:171], v210 offset:2048
	ds_read_b128 v[172:175], v210 offset:3072
	ds_read_b128 v[188:191], v210 offset:4096
	ds_read_b128 v[192:195], v210 offset:5120
	ds_read_b128 v[198:201], v210 offset:6144
	ds_read_b128 v[212:215], v210 offset:7168
	global_load_lds_dwordx4 v184, s[38:39]
	s_add_i32 m0, s18, 0xe000
	s_nop 0
	global_load_lds_dwordx4 v186, s[38:39]
	s_waitcnt vmcnt(8)
	s_waitcnt lgkmcnt(0)
	s_barrier
	s_setprio 1
	v_mfma_f32_16x16x32_bf16 v[140:143], v[56:59], v[160:163], v[140:143]
	v_mfma_f32_16x16x32_bf16 v[136:139], v[64:67], v[160:163], v[136:139]
	v_mfma_f32_16x16x32_bf16 v[124:127], v[56:59], v[168:171], v[124:127]
	v_mfma_f32_16x16x32_bf16 v[120:123], v[64:67], v[168:171], v[120:123]
	v_mfma_f32_16x16x32_bf16 v[108:111], v[56:59], v[188:191], v[108:111]
	v_mfma_f32_16x16x32_bf16 v[104:107], v[64:67], v[188:191], v[104:107]
	v_mfma_f32_16x16x32_bf16 v[92:95], v[56:59], v[198:201], v[92:95]
	v_mfma_f32_16x16x32_bf16 v[88:91], v[64:67], v[198:201], v[88:91]
	v_mfma_f32_16x16x32_bf16 v[140:143], v[60:63], v[164:167], v[140:143]
	v_mfma_f32_16x16x32_bf16 v[136:139], v[68:71], v[164:167], v[136:139]
	v_mfma_f32_16x16x32_bf16 v[124:127], v[60:63], v[172:175], v[124:127]
	v_mfma_f32_16x16x32_bf16 v[120:123], v[68:71], v[172:175], v[120:123]
	v_mfma_f32_16x16x32_bf16 v[108:111], v[60:63], v[192:195], v[108:111]
	v_mfma_f32_16x16x32_bf16 v[104:107], v[68:71], v[192:195], v[104:107]
	v_mfma_f32_16x16x32_bf16 v[92:95], v[60:63], v[212:215], v[92:95]
	v_mfma_f32_16x16x32_bf16 v[88:91], v[68:71], v[212:215], v[88:91]
	v_mfma_f32_16x16x32_bf16 v[132:135], v[144:147], v[160:163], v[132:135]
	v_mfma_f32_16x16x32_bf16 v[128:131], v[152:155], v[160:163], v[128:131]
	v_mfma_f32_16x16x32_bf16 v[116:119], v[144:147], v[168:171], v[116:119]
	v_mfma_f32_16x16x32_bf16 v[112:115], v[152:155], v[168:171], v[112:115]
	v_mfma_f32_16x16x32_bf16 v[100:103], v[144:147], v[188:191], v[100:103]
	v_mfma_f32_16x16x32_bf16 v[96:99], v[152:155], v[188:191], v[96:99]
	v_mfma_f32_16x16x32_bf16 v[84:87], v[144:147], v[198:201], v[84:87]
	v_mfma_f32_16x16x32_bf16 v[80:83], v[152:155], v[198:201], v[80:83]
	v_mfma_f32_16x16x32_bf16 v[132:135], v[148:151], v[164:167], v[132:135]
	v_mfma_f32_16x16x32_bf16 v[128:131], v[156:159], v[164:167], v[128:131]
	v_mfma_f32_16x16x32_bf16 v[116:119], v[148:151], v[172:175], v[116:119]
	v_mfma_f32_16x16x32_bf16 v[112:115], v[156:159], v[172:175], v[112:115]
	v_mfma_f32_16x16x32_bf16 v[100:103], v[148:151], v[192:195], v[100:103]
	v_mfma_f32_16x16x32_bf16 v[96:99], v[156:159], v[192:195], v[96:99]
	v_mfma_f32_16x16x32_bf16 v[84:87], v[148:151], v[212:215], v[84:87]
	v_mfma_f32_16x16x32_bf16 v[80:83], v[156:159], v[212:215], v[80:83]
	s_setprio 0
	s_barrier
	s_add_u32 s24, s38, 0xfff80080
	s_addc_u32 s25, s39, -1
	s_cmp_eq_u32 s42, 28
	s_cselect_b32 s65, s4, s25
	s_cselect_b32 s64, s5, s24
	s_cselect_b32 vcc_hi, s6, s9
	s_cselect_b32 vcc_lo, s7, s8
	s_add_i32 s24, s43, s15
	v_lshl_add_u64 v[202:203], vcc, 0, v[176:177]
	s_mov_b32 m0, s24
	ds_read_b128 v[160:163], v210 offset:16384
	ds_read_b128 v[164:167], v210 offset:17408
	ds_read_b128 v[168:171], v210 offset:18432
	ds_read_b128 v[172:175], v210 offset:19456
	ds_read_b128 v[188:191], v210 offset:20480
	ds_read_b128 v[192:195], v210 offset:21504
	ds_read_b128 v[198:201], v210 offset:22528
	ds_read_b128 v[212:215], v210 offset:23552
	global_load_lds_dwordx4 v[202:203], off
	s_add_i32 m0, s24, 0x2000
	s_add_u32 s24, vcc_lo, 0x80000
	v_lshl_add_u64 v[216:217], vcc, 0, v[178:179]
	s_addc_u32 s25, vcc_hi, 0
	s_add_i32 s26, s26, s15
	global_load_lds_dwordx4 v[216:217], off
	v_lshl_add_u64 v[218:219], s[24:25], 0, v[176:177]
	s_mov_b32 m0, s26
	v_lshl_add_u64 v[220:221], s[64:65], 0, v[180:181]
	global_load_lds_dwordx4 v[218:219], off
	v_lshl_add_u64 v[218:219], s[24:25], 0, v[178:179]
	s_add_i32 m0, s26, 0x2000
	s_nop 0
	global_load_lds_dwordx4 v[218:219], off
	v_lshl_add_u64 v[218:219], s[64:65], 0, v[182:183]
	s_mov_b32 m0, s18
	s_nop 0
	global_load_lds_dwordx4 v[218:219], off
	s_mov_b32 m0, s19
	s_nop 0
	global_load_lds_dwordx4 v[220:221], off
	s_add_u32 s24, s64, 0x80000
	s_addc_u32 s25, s65, 0
	s_waitcnt vmcnt(8)
	s_waitcnt lgkmcnt(0)
	s_barrier
; #define PG8_STAGE(bufoff, gbase, voff) do { _Pragma("unroll") for (int _i = 0; _i < 2; ++_i) \
;         __builtin_amdgcn_global_load_lds((const unsigned*)((const char*)(gbase) + (voff)[_i]), (LAS unsigned*)(lds + (bufoff) + ldsw + _i * 8192), 16, 0, 0); } while (0)
; #define PG8_LDA(dst, b, h) do { _Pragma("unroll") for (int m = 0; m < 4; ++m) _Pragma("unroll") for (int k = 0; k < 2; ++k) dst[m][k] = *(const LAS bf16x8*)(lds + PG8_SA(b, h) + aoff + m * 2048 + k * 1024); } while (0)
; #define PG8_LDB(dst, b, h) do { _Pragma("unroll") for (int n = 0; n < 2; ++n) _Pragma("unroll") for (int k = 0; k < 2; ++k) dst[n][k] = *(const LAS bf16x8*)(lds + PG8_SB(b, h) + boff + n * 2048 + k * 1024); } while (0)
; #define PG8_WAIT_V(n) asm volatile("s_waitcnt vmcnt(" #n ")" ::: "memory")
; #define PG8_WAIT_L(n) asm volatile("s_waitcnt lgkmcnt(" #n ")" ::: "memory")
; #define PG8_BAR __builtin_amdgcn_s_barrier()
; #define PG8_SCHED __builtin_amdgcn_sched_barrier(0)
; template <bool F16, class Sched, class Epi>
; __device__ __forceinline__ void gemm_phase(LAS unsigned char* lds, const Gemm g, const Sched& S, const Epi& E, int wave_s) {
;     ...
;             PG8_WAIT_V(8); PG8_WAIT_L(0); PG8_BAR; PG8_MMA(1, 0, At, B0); PG8_MMA(1, 1, At, B1); PG8_BAR; PG8_SCHED;
;             PG8_LDB(B0, 1, 0); PG8_LDB(B1, 1, 1); PG8_SCHED; PG8_LDA(At, 1, 0); PG8_STAGE(PG8_SA(0, 1), a2 + hstepA, voffA);
;             PG8_WAIT_V(8); PG8_WAIT_L(0); PG8_BAR; PG8_MMA(0, 0, At, B0); PG8_MMA(0, 1, At, B1); PG8_BAR; PG8_SCHED;
	s_setprio 1
	v_mfma_f32_16x16x32_bf16 v[76:79], v[56:59], v[160:163], v[76:79]
	v_mfma_f32_16x16x32_bf16 v[72:75], v[64:67], v[160:163], v[72:75]
	v_mfma_f32_16x16x32_bf16 v[44:47], v[56:59], v[168:171], v[44:47]
	v_mfma_f32_16x16x32_bf16 v[40:43], v[64:67], v[168:171], v[40:43]
	v_mfma_f32_16x16x32_bf16 v[28:31], v[56:59], v[188:191], v[28:31]
	v_mfma_f32_16x16x32_bf16 v[24:27], v[64:67], v[188:191], v[24:27]
	v_mfma_f32_16x16x32_bf16 v[12:15], v[56:59], v[198:201], v[12:15]
	v_mfma_f32_16x16x32_bf16 v[8:11], v[64:67], v[198:201], v[8:11]
	v_mfma_f32_16x16x32_bf16 v[76:79], v[60:63], v[164:167], v[76:79]
	v_mfma_f32_16x16x32_bf16 v[72:75], v[68:71], v[164:167], v[72:75]
	v_mfma_f32_16x16x32_bf16 v[44:47], v[60:63], v[172:175], v[44:47]
	v_mfma_f32_16x16x32_bf16 v[40:43], v[68:71], v[172:175], v[40:43]
	v_mfma_f32_16x16x32_bf16 v[28:31], v[60:63], v[192:195], v[28:31]
	v_mfma_f32_16x16x32_bf16 v[24:27], v[68:71], v[192:195], v[24:27]
	v_mfma_f32_16x16x32_bf16 v[12:15], v[60:63], v[212:215], v[12:15]
	v_mfma_f32_16x16x32_bf16 v[8:11], v[68:71], v[212:215], v[8:11]
	v_mfma_f32_16x16x32_bf16 v[52:55], v[144:147], v[160:163], v[52:55]
	v_mfma_f32_16x16x32_bf16 v[48:51], v[152:155], v[160:163], v[48:51]
	v_mfma_f32_16x16x32_bf16 v[36:39], v[144:147], v[168:171], v[36:39]
	v_mfma_f32_16x16x32_bf16 v[32:35], v[152:155], v[168:171], v[32:35]
	v_mfma_f32_16x16x32_bf16 v[20:23], v[144:147], v[188:191], v[20:23]
	v_mfma_f32_16x16x32_bf16 v[16:19], v[152:155], v[188:191], v[16:19]
	v_mfma_f32_16x16x32_bf16 v[4:7], v[144:147], v[198:201], v[4:7]
	v_mfma_f32_16x16x32_bf16 v[0:3], v[152:155], v[198:201], v[0:3]
	v_mfma_f32_16x16x32_bf16 v[52:55], v[148:151], v[164:167], v[52:55]
	v_mfma_f32_16x16x32_bf16 v[48:51], v[156:159], v[164:167], v[48:51]
	v_mfma_f32_16x16x32_bf16 v[36:39], v[148:151], v[172:175], v[36:39]
	v_mfma_f32_16x16x32_bf16 v[32:35], v[156:159], v[172:175], v[32:35]
	v_mfma_f32_16x16x32_bf16 v[20:23], v[148:151], v[192:195], v[20:23]
	v_mfma_f32_16x16x32_bf16 v[16:19], v[156:159], v[192:195], v[16:19]
	v_mfma_f32_16x16x32_bf16 v[4:7], v[148:151], v[212:215], v[4:7]
	v_mfma_f32_16x16x32_bf16 v[0:3], v[156:159], v[212:215], v[0:3]
	s_setprio 0
	s_barrier
	s_add_i32 s26, 0, 0x18000
	s_add_i32 s27, 0, 0x1c000
	v_add_u32_e32 v68, s26, v208
	v_add_u32_e32 v156, s27, v208
	ds_read_b128 v[56:59], v68
	ds_read_b128 v[60:63], v68 offset:1024
	ds_read_b128 v[64:67], v68 offset:2048
	ds_read_b128 v[68:71], v68 offset:3072
	ds_read_b128 v[144:147], v156
	ds_read_b128 v[148:151], v156 offset:1024
	ds_read_b128 v[152:155], v156 offset:2048
	ds_read_b128 v[156:159], v156 offset:3072
	s_mov_b32 m0, s20
	ds_read_b128 v[160:163], v210 offset:32768
	ds_read_b128 v[164:167], v210 offset:33792
	ds_read_b128 v[168:171], v210 offset:34816
	ds_read_b128 v[172:175], v210 offset:35840
	ds_read_b128 v[188:191], v210 offset:36864
	ds_read_b128 v[192:195], v210 offset:37888
	ds_read_b128 v[198:201], v210 offset:38912
	ds_read_b128 v[212:215], v210 offset:39936
	global_load_lds_dwordx4 v182, s[24:25]
	s_mov_b32 m0, s21
	s_nop 0
	global_load_lds_dwordx4 v180, s[24:25]
	s_waitcnt vmcnt(8)
	s_waitcnt lgkmcnt(0)
	s_barrier
	s_setprio 1
	v_mfma_f32_16x16x32_bf16 v[140:143], v[56:59], v[160:163], v[140:143]
	v_mfma_f32_16x16x32_bf16 v[136:139], v[64:67], v[160:163], v[136:139]
	v_mfma_f32_16x16x32_bf16 v[124:127], v[56:59], v[168:171], v[124:127]
	v_mfma_f32_16x16x32_bf16 v[120:123], v[64:67], v[168:171], v[120:123]
	v_mfma_f32_16x16x32_bf16 v[108:111], v[56:59], v[188:191], v[108:111]
	v_mfma_f32_16x16x32_bf16 v[104:107], v[64:67], v[188:191], v[104:107]
	v_mfma_f32_16x16x32_bf16 v[92:95], v[56:59], v[198:201], v[92:95]
	v_mfma_f32_16x16x32_bf16 v[88:91], v[64:67], v[198:201], v[88:91]
	v_mfma_f32_16x16x32_bf16 v[140:143], v[60:63], v[164:167], v[140:143]
	v_mfma_f32_16x16x32_bf16 v[136:139], v[68:71], v[164:167], v[136:139]
	v_mfma_f32_16x16x32_bf16 v[124:127], v[60:63], v[172:175], v[124:127]
	v_mfma_f32_16x16x32_bf16 v[120:123], v[68:71], v[172:175], v[120:123]
	v_mfma_f32_16x16x32_bf16 v[108:111], v[60:63], v[192:195], v[108:111]
	v_mfma_f32_16x16x32_bf16 v[104:107], v[68:71], v[192:195], v[104:107]
	v_mfma_f32_16x16x32_bf16 v[92:95], v[60:63], v[212:215], v[92:95]
	v_mfma_f32_16x16x32_bf16 v[88:91], v[68:71], v[212:215], v[88:91]
	v_mfma_f32_16x16x32_bf16 v[132:135], v[144:147], v[160:163], v[132:135]
	v_mfma_f32_16x16x32_bf16 v[128:131], v[152:155], v[160:163], v[128:131]
	v_mfma_f32_16x16x32_bf16 v[116:119], v[144:147], v[168:171], v[116:119]
	v_mfma_f32_16x16x32_bf16 v[112:115], v[152:155], v[168:171], v[112:115]
	v_mfma_f32_16x16x32_bf16 v[100:103], v[144:147], v[188:191], v[100:103]
	v_mfma_f32_16x16x32_bf16 v[96:99], v[152:155], v[188:191], v[96:99]
	v_mfma_f32_16x16x32_bf16 v[84:87], v[144:147], v[198:201], v[84:87]
	v_mfma_f32_16x16x32_bf16 v[80:83], v[152:155], v[198:201], v[80:83]
	v_mfma_f32_16x16x32_bf16 v[132:135], v[148:151], v[164:167], v[132:135]
	v_mfma_f32_16x16x32_bf16 v[128:131], v[156:159], v[164:167], v[128:131]
	v_mfma_f32_16x16x32_bf16 v[116:119], v[148:151], v[172:175], v[116:119]
	v_mfma_f32_16x16x32_bf16 v[112:115], v[156:159], v[172:175], v[112:115]
	v_mfma_f32_16x16x32_bf16 v[100:103], v[148:151], v[192:195], v[100:103]
	v_mfma_f32_16x16x32_bf16 v[96:99], v[156:159], v[192:195], v[96:99]
	v_mfma_f32_16x16x32_bf16 v[84:87], v[148:151], v[212:215], v[84:87]
	v_mfma_f32_16x16x32_bf16 v[80:83], v[156:159], v[212:215], v[80:83]
	s_setprio 0
	s_barrier
; #define PG8_STAGE(bufoff, gbase, voff) do { _Pragma("unroll") for (int _i = 0; _i < 2; ++_i) \
;         __builtin_amdgcn_global_load_lds((const unsigned*)((const char*)(gbase) + (voff)[_i]), (LAS unsigned*)(lds + (bufoff) + ldsw + _i * 8192), 16, 0, 0); } while (0)
; #define PG8_LDA(dst, b, h) do { _Pragma("unroll") for (int m = 0; m < 4; ++m) _Pragma("unroll") for (int k = 0; k < 2; ++k) dst[m][k] = *(const LAS bf16x8*)(lds + PG8_SA(b, h) + aoff + m * 2048 + k * 1024); } while (0)
; #define PG8_WAIT_V(n) asm volatile("s_waitcnt vmcnt(" #n ")" ::: "memory")
; #define PG8_WAIT_L(n) asm volatile("s_waitcnt lgkmcnt(" #n ")" ::: "memory")
; #define PG8_BAR __builtin_amdgcn_s_barrier()
; #define PG8_SCHED __builtin_amdgcn_sched_barrier(0)
; template <bool F16, class Sched, class Epi>
; __device__ __forceinline__ void gemm_phase(LAS unsigned char* lds, const Gemm g, const Sched& S, const Epi& E, int wave_s) {
;     ...
;             PG8_LDA(At, 1, 1); PG8_STAGE(PG8_SB(1, 0), b3, voffB); PG8_STAGE(PG8_SB(1, 1), b3 + hstepB, voffB); PG8_STAGE(PG8_SA(1, 0), a3, voffA);
;             PG8_WAIT_V(8); PG8_WAIT_L(0); PG8_BAR; PG8_MMA(1, 0, At, B0); PG8_MMA(1, 1, At, B1); PG8_BAR; PG8_SCHED;
;         }
;         if (wr == 0) PG8_BAR;
	s_add_i32 s24, s26, s15
	v_lshl_add_u64 v[202:203], v[202:203], 0, s[54:55]
	s_mov_b32 m0, s24
	ds_read_b128 v[160:163], v210 offset:49152
	ds_read_b128 v[164:167], v210 offset:50176
	ds_read_b128 v[168:171], v210 offset:51200
	ds_read_b128 v[172:175], v210 offset:52224
	ds_read_b128 v[188:191], v210 offset:53248
	ds_read_b128 v[192:195], v210 offset:54272
	ds_read_b128 v[198:201], v210 offset:55296
	ds_read_b128 v[212:215], v210 offset:56320
	global_load_lds_dwordx4 v[202:203], off
	s_add_i32 m0, s24, 0x2000
	s_add_u32 s24, vcc_lo, 0x80080
	v_lshl_add_u64 v[202:203], v[216:217], 0, s[54:55]
	s_addc_u32 s25, vcc_hi, 0
	s_add_i32 s26, s27, s15
	global_load_lds_dwordx4 v[202:203], off
	v_lshl_add_u64 v[202:203], s[24:25], 0, v[176:177]
	s_mov_b32 m0, s26
	s_nop 0
	global_load_lds_dwordx4 v[202:203], off
	v_lshl_add_u64 v[202:203], s[24:25], 0, v[178:179]
	s_add_i32 m0, s26, 0x2000
	s_nop 0
	global_load_lds_dwordx4 v[202:203], off
	v_lshl_add_u64 v[202:203], v[218:219], 0, s[54:55]
	s_mov_b32 m0, s50
	s_nop 0
	global_load_lds_dwordx4 v[202:203], off
	v_lshl_add_u64 v[202:203], v[220:221], 0, s[54:55]
	s_mov_b32 m0, s22
	s_nop 0
	global_load_lds_dwordx4 v[202:203], off
	s_waitcnt vmcnt(8)
	s_waitcnt lgkmcnt(0)
	s_barrier
	s_setprio 1
	v_mfma_f32_16x16x32_bf16 v[76:79], v[56:59], v[160:163], v[76:79]
	v_mfma_f32_16x16x32_bf16 v[72:75], v[64:67], v[160:163], v[72:75]
	v_mfma_f32_16x16x32_bf16 v[44:47], v[56:59], v[168:171], v[44:47]
	v_mfma_f32_16x16x32_bf16 v[40:43], v[64:67], v[168:171], v[40:43]
	v_mfma_f32_16x16x32_bf16 v[28:31], v[56:59], v[188:191], v[28:31]
	v_mfma_f32_16x16x32_bf16 v[24:27], v[64:67], v[188:191], v[24:27]
	v_mfma_f32_16x16x32_bf16 v[12:15], v[56:59], v[198:201], v[12:15]
	v_mfma_f32_16x16x32_bf16 v[8:11], v[64:67], v[198:201], v[8:11]
	v_mfma_f32_16x16x32_bf16 v[76:79], v[60:63], v[164:167], v[76:79]
	v_mfma_f32_16x16x32_bf16 v[72:75], v[68:71], v[164:167], v[72:75]
	v_mfma_f32_16x16x32_bf16 v[44:47], v[60:63], v[172:175], v[44:47]
	v_mfma_f32_16x16x32_bf16 v[40:43], v[68:71], v[172:175], v[40:43]
	v_mfma_f32_16x16x32_bf16 v[28:31], v[60:63], v[192:195], v[28:31]
	v_mfma_f32_16x16x32_bf16 v[24:27], v[68:71], v[192:195], v[24:27]
	v_mfma_f32_16x16x32_bf16 v[12:15], v[60:63], v[212:215], v[12:15]
	v_mfma_f32_16x16x32_bf16 v[8:11], v[68:71], v[212:215], v[8:11]
	v_mfma_f32_16x16x32_bf16 v[52:55], v[144:147], v[160:163], v[52:55]
	v_mfma_f32_16x16x32_bf16 v[48:51], v[152:155], v[160:163], v[48:51]
	v_mfma_f32_16x16x32_bf16 v[36:39], v[144:147], v[168:171], v[36:39]
	v_mfma_f32_16x16x32_bf16 v[32:35], v[152:155], v[168:171], v[32:35]
	v_mfma_f32_16x16x32_bf16 v[20:23], v[144:147], v[188:191], v[20:23]
	v_mfma_f32_16x16x32_bf16 v[16:19], v[152:155], v[188:191], v[16:19]
	v_mfma_f32_16x16x32_bf16 v[4:7], v[144:147], v[198:201], v[4:7]
	v_mfma_f32_16x16x32_bf16 v[0:3], v[152:155], v[198:201], v[0:3]
	v_mfma_f32_16x16x32_bf16 v[52:55], v[148:151], v[164:167], v[52:55]
	v_mfma_f32_16x16x32_bf16 v[48:51], v[156:159], v[164:167], v[48:51]
	v_mfma_f32_16x16x32_bf16 v[36:39], v[148:151], v[172:175], v[36:39]
	v_mfma_f32_16x16x32_bf16 v[32:35], v[156:159], v[172:175], v[32:35]
	v_mfma_f32_16x16x32_bf16 v[20:23], v[148:151], v[192:195], v[20:23]
	v_mfma_f32_16x16x32_bf16 v[16:19], v[156:159], v[192:195], v[16:19]
	v_mfma_f32_16x16x32_bf16 v[4:7], v[148:151], v[212:215], v[4:7]
	v_mfma_f32_16x16x32_bf16 v[0:3], v[156:159], v[212:215], v[0:3]
	s_setprio 0
	s_barrier
	s_add_i32 s42, s42, 2
	s_add_u32 s38, s38, 0x100
	s_addc_u32 s39, s39, 0
	s_add_u32 s8, s8, 0x100
	s_addc_u32 s9, s9, 0
	s_cmp_gt_u32 s42, 29
	s_cbranch_scc0 .LBB0_993
	s_and_b64 vcc, exec, s[88:89]
	s_cbranch_vccz .LBB0_996
	s_barrier
